# K-loop LDS-DMA stages: 76 stage loads take the SGPR base directly (saddr form) instead of a leading 64-bit VALU add per stage
# speedup vs baseline: 1.0013x; 1.0013x over previous
; #define PG8_STAGE(bufoff, gbase, voff) do { _Pragma("unroll") for (int _i = 0; _i < 2; ++_i) \
;         __builtin_amdgcn_global_load_lds((const unsigned*)((const char*)(gbase) + (voff)[_i]), (LAS unsigned*)(lds + (bufoff) + ldsw + _i * 8192), 16, 0, 0); } while (0)
; #define PG8_LDA(dst, b, h) do { _Pragma("unroll") for (int m = 0; m < 4; ++m) _Pragma("unroll") for (int k = 0; k < 2; ++k) dst[m][k] = *(const LAS bf16x8*)(lds + PG8_SA(b, h) + aoff + m * 2048 + k * 1024); } while (0)
; #define PG8_LDB(dst, b, h) do { _Pragma("unroll") for (int n = 0; n < 2; ++n) _Pragma("unroll") for (int k = 0; k < 2; ++k) dst[n][k] = *(const LAS bf16x8*)(lds + PG8_SB(b, h) + boff + n * 2048 + k * 1024); } while (0)
; #define PG8_MMA(ai, bj, At, Bt) do { __builtin_amdgcn_s_setprio(1); _Pragma("unroll") for (int m = 0; m < 4; ++m) _Pragma("unroll") for (int n = 0; n < 2; ++n) _Pragma("unroll") for (int k = 0; k < 2; ++k) \
;         acc[ai][bj][m][n] = __builtin_amdgcn_mfma_f32_16x16x32_bf16(Bt[n][k], At[m][k], acc[ai][bj][m][n], 0, 0, 0); __builtin_amdgcn_s_setprio(0); } while (0)
; #define PG8_WAIT_L(n) asm volatile("s_waitcnt lgkmcnt(" #n ")" ::: "memory")
; #define PG8_BAR __builtin_amdgcn_s_barrier()
; #define PG8_SCHED __builtin_amdgcn_sched_barrier(0)
; template <class Epi>
; __device__ __forceinline__ void gemm_phase(LAS unsigned char* lds, const Gemm g, const StaticOrder& S, const Epi& E) {
;     ...
;         for (int t = 0; t < nt; t += 2) {
;             const bool last = (t == nt - 2);
;             const char* a1 = cA + (size_t)(t + 1) * kstep;
;             const char* a2 = last ? nA : cA + (size_t)(t + 2) * kstep; const char* b2 = last ? nB : cB + (size_t)(t + 2) * kstep;
;             const char* a3 = a2 + kstep; const char* b3 = b2 + kstep;
;             PG8_LDB(B0, 0, 0); PG8_SCHED; PG8_LDA(At, 0, 0); PG8_STAGE(PG8_SA(1, 1), a1 + hstepA, voffA);
;             PG8_WAIT_L(8); PG8_BAR; PG8_WAIT_L(0); PG8_MMA(0, 0, At, B0); PG8_BAR; PG8_SCHED;
;             PG8_LDB(B1, 0, 1); PG8_STAGE(PG8_SB(0, 0), b2, voffB);
;             PG8_BAR; PG8_WAIT_L(0); PG8_MMA(0, 1, At, B1); PG8_BAR;
;             PG8_LDA(At, 0, 1); PG8_STAGE(PG8_SA(0, 0), a2, voffA);
;             PG8_BAR; PG8_WAIT_L(0); PG8_MMA(1, 0, At, B0); PG8_BAR; PG8_SCHED;
.LBB0_1442:
	ds_read_b128 v[128:131], v207
	ds_read_b128 v[132:135], v207 offset:1024
	ds_read_b128 v[136:139], v207 offset:2048
	ds_read_b128 v[140:143], v207 offset:3072
	s_add_i32 s82, s40, 2
	s_add_u32 s41, s10, 0xfffc0080
	s_addc_u32 s42, s11, -1
	s_cmp_eq_u32 s72, s40
	s_cselect_b32 s40, s65, s80
	s_cselect_b32 s43, s27, s42
	s_cselect_b32 s42, s29, s41
	s_cselect_b32 s41, s64, s81
	s_add_i32 m0, s37, 0xc000
	ds_read_b128 v[144:147], v208
	ds_read_b128 v[148:151], v208 offset:1024
	ds_read_b128 v[152:155], v208 offset:2048
	ds_read_b128 v[156:159], v208 offset:3072
	ds_read_b128 v[160:163], v208 offset:4096
	ds_read_b128 v[164:167], v208 offset:5120
	ds_read_b128 v[168:171], v208 offset:6144
	ds_read_b128 v[172:175], v208 offset:7168
	global_load_lds_dwordx4 v184, s[10:11]
	s_add_i32 m0, s37, 0xe000
	s_nop 0
	global_load_lds_dwordx4 v186, s[10:11]
	s_waitcnt lgkmcnt(8)
	s_barrier
	s_waitcnt lgkmcnt(0)
	s_setprio 1
	s_waitcnt lgkmcnt(0)
	v_mfma_f32_16x16x32_bf16 v[120:123], v[128:131], v[144:147], v[120:123]
	v_mfma_f32_16x16x32_bf16 v[124:127], v[136:139], v[144:147], v[124:127]
	v_mfma_f32_16x16x32_bf16 v[108:111], v[128:131], v[152:155], v[108:111]
	v_mfma_f32_16x16x32_bf16 v[104:107], v[136:139], v[152:155], v[104:107]
	v_mfma_f32_16x16x32_bf16 v[92:95], v[128:131], v[160:163], v[92:95]
	v_mfma_f32_16x16x32_bf16 v[88:91], v[136:139], v[160:163], v[88:91]
	v_mfma_f32_16x16x32_bf16 v[76:79], v[128:131], v[168:171], v[76:79]
	v_mfma_f32_16x16x32_bf16 v[72:75], v[136:139], v[168:171], v[72:75]
	v_mfma_f32_16x16x32_bf16 v[120:123], v[132:135], v[148:151], v[120:123]
	v_mfma_f32_16x16x32_bf16 v[124:127], v[140:143], v[148:151], v[124:127]
	v_mfma_f32_16x16x32_bf16 v[108:111], v[132:135], v[156:159], v[108:111]
	v_mfma_f32_16x16x32_bf16 v[104:107], v[140:143], v[156:159], v[104:107]
	v_mfma_f32_16x16x32_bf16 v[92:95], v[132:135], v[164:167], v[92:95]
	v_mfma_f32_16x16x32_bf16 v[88:91], v[140:143], v[164:167], v[88:91]
	v_mfma_f32_16x16x32_bf16 v[76:79], v[132:135], v[172:175], v[76:79]
	v_mfma_f32_16x16x32_bf16 v[72:75], v[140:143], v[172:175], v[72:75]
	s_setprio 0
	s_barrier
	s_add_i32 s66, s78, s45
	v_lshl_add_u64 v[216:217], s[40:41], 0, v[178:179]
	s_mov_b32 m0, s66
	ds_read_b128 v[192:195], v209
	ds_read_b128 v[196:199], v209 offset:1024
	ds_read_b128 v[200:203], v209 offset:2048
	ds_read_b128 v[212:215], v209 offset:3072
	global_load_lds_dwordx4 v[216:217], off
	v_lshl_add_u64 v[218:219], s[40:41], 0, v[182:183]
	s_add_i32 m0, s66, 0x2000
	s_nop 0
	global_load_lds_dwordx4 v[218:219], off
	s_barrier
	s_waitcnt lgkmcnt(0)
	s_setprio 1
	s_waitcnt lgkmcnt(0)
	v_mfma_f32_16x16x32_bf16 v[116:119], v[192:195], v[144:147], v[116:119]
	v_mfma_f32_16x16x32_bf16 v[112:115], v[200:203], v[144:147], v[112:115]
	v_mfma_f32_16x16x32_bf16 v[100:103], v[192:195], v[152:155], v[100:103]
	v_mfma_f32_16x16x32_bf16 v[96:99], v[200:203], v[152:155], v[96:99]
	v_mfma_f32_16x16x32_bf16 v[84:87], v[192:195], v[160:163], v[84:87]
	v_mfma_f32_16x16x32_bf16 v[80:83], v[200:203], v[160:163], v[80:83]
	v_mfma_f32_16x16x32_bf16 v[68:71], v[192:195], v[168:171], v[68:71]
	v_mfma_f32_16x16x32_bf16 v[64:67], v[200:203], v[168:171], v[64:67]
	v_mfma_f32_16x16x32_bf16 v[116:119], v[196:199], v[148:151], v[116:119]
	v_mfma_f32_16x16x32_bf16 v[112:115], v[212:215], v[148:151], v[112:115]
	v_mfma_f32_16x16x32_bf16 v[100:103], v[196:199], v[156:159], v[100:103]
	v_mfma_f32_16x16x32_bf16 v[96:99], v[212:215], v[156:159], v[96:99]
	v_mfma_f32_16x16x32_bf16 v[84:87], v[196:199], v[164:167], v[84:87]
	v_mfma_f32_16x16x32_bf16 v[80:83], v[212:215], v[164:167], v[80:83]
	v_mfma_f32_16x16x32_bf16 v[68:71], v[196:199], v[172:175], v[68:71]
	v_mfma_f32_16x16x32_bf16 v[64:67], v[212:215], v[172:175], v[64:67]
	s_setprio 0
	s_mov_b32 m0, s37
	v_lshl_add_u64 v[220:221], s[42:43], 0, v[176:177]
	s_barrier
	ds_read_b128 v[144:147], v208 offset:16384
	ds_read_b128 v[148:151], v208 offset:17408
	ds_read_b128 v[152:155], v208 offset:18432
	ds_read_b128 v[156:159], v208 offset:19456
	ds_read_b128 v[160:163], v208 offset:20480
	ds_read_b128 v[164:167], v208 offset:21504
	ds_read_b128 v[168:171], v208 offset:22528
	ds_read_b128 v[172:175], v208 offset:23552
	global_load_lds_dwordx4 v[220:221], off
	v_lshl_add_u64 v[222:223], s[42:43], 0, v[180:181]
	s_mov_b32 m0, s39
	s_nop 0
	global_load_lds_dwordx4 v[222:223], off
	s_barrier
	s_waitcnt lgkmcnt(0)
	s_setprio 1
	s_waitcnt lgkmcnt(0)
	v_mfma_f32_16x16x32_bf16 v[60:63], v[128:131], v[144:147], v[60:63]
	v_mfma_f32_16x16x32_bf16 v[56:59], v[136:139], v[144:147], v[56:59]
	v_mfma_f32_16x16x32_bf16 v[44:47], v[128:131], v[152:155], v[44:47]
	v_mfma_f32_16x16x32_bf16 v[40:43], v[136:139], v[152:155], v[40:43]
	v_mfma_f32_16x16x32_bf16 v[28:31], v[128:131], v[160:163], v[28:31]
	v_mfma_f32_16x16x32_bf16 v[24:27], v[136:139], v[160:163], v[24:27]
	v_mfma_f32_16x16x32_bf16 v[12:15], v[128:131], v[168:171], v[12:15]
	v_mfma_f32_16x16x32_bf16 v[8:11], v[136:139], v[168:171], v[8:11]
	v_mfma_f32_16x16x32_bf16 v[60:63], v[132:135], v[148:151], v[60:63]
	v_mfma_f32_16x16x32_bf16 v[56:59], v[140:143], v[148:151], v[56:59]
	v_mfma_f32_16x16x32_bf16 v[44:47], v[132:135], v[156:159], v[44:47]
	v_mfma_f32_16x16x32_bf16 v[40:43], v[140:143], v[156:159], v[40:43]
	v_mfma_f32_16x16x32_bf16 v[28:31], v[132:135], v[164:167], v[28:31]
	v_mfma_f32_16x16x32_bf16 v[24:27], v[140:143], v[164:167], v[24:27]
	v_mfma_f32_16x16x32_bf16 v[12:15], v[132:135], v[172:175], v[12:15]
	v_mfma_f32_16x16x32_bf16 v[8:11], v[140:143], v[172:175], v[8:11]
	s_setprio 0
	s_barrier
; #define PG8_STAGE(bufoff, gbase, voff) do { _Pragma("unroll") for (int _i = 0; _i < 2; ++_i) \
;         __builtin_amdgcn_global_load_lds((const unsigned*)((const char*)(gbase) + (voff)[_i]), (LAS unsigned*)(lds + (bufoff) + ldsw + _i * 8192), 16, 0, 0); } while (0)
; #define PG8_LDA(dst, b, h) do { _Pragma("unroll") for (int m = 0; m < 4; ++m) _Pragma("unroll") for (int k = 0; k < 2; ++k) dst[m][k] = *(const LAS bf16x8*)(lds + PG8_SA(b, h) + aoff + m * 2048 + k * 1024); } while (0)
; #define PG8_LDB(dst, b, h) do { _Pragma("unroll") for (int n = 0; n < 2; ++n) _Pragma("unroll") for (int k = 0; k < 2; ++k) dst[n][k] = *(const LAS bf16x8*)(lds + PG8_SB(b, h) + boff + n * 2048 + k * 1024); } while (0)
; #define PG8_MMA(ai, bj, At, Bt) do { __builtin_amdgcn_s_setprio(1); _Pragma("unroll") for (int m = 0; m < 4; ++m) _Pragma("unroll") for (int n = 0; n < 2; ++n) _Pragma("unroll") for (int k = 0; k < 2; ++k) \
;         acc[ai][bj][m][n] = __builtin_amdgcn_mfma_f32_16x16x32_bf16(Bt[n][k], At[m][k], acc[ai][bj][m][n], 0, 0, 0); __builtin_amdgcn_s_setprio(0); } while (0)
; #define PG8_WAIT_V(n) asm volatile("s_waitcnt vmcnt(" #n ")" ::: "memory")
; #define PG8_WAIT_L(n) asm volatile("s_waitcnt lgkmcnt(" #n ")" ::: "memory")
; #define PG8_BAR __builtin_amdgcn_s_barrier()
; #define PG8_SCHED __builtin_amdgcn_sched_barrier(0)
; template <class Epi>
; __device__ __forceinline__ void gemm_phase(LAS unsigned char* lds, const Gemm g, const StaticOrder& S, const Epi& E) {
;     ...
;             PG8_STAGE(PG8_SB(0, 1), b2 + hstepB, voffB);
;             PG8_WAIT_V(6); PG8_BAR; PG8_MMA(1, 1, At, B1); PG8_BAR;
;             PG8_LDB(B0, 1, 0); PG8_SCHED; PG8_LDA(At, 1, 0); PG8_STAGE(PG8_SA(0, 1), a2 + hstepA, voffA);
;             PG8_WAIT_L(8); PG8_BAR; PG8_WAIT_L(0); PG8_MMA(0, 0, At, B0); PG8_BAR; PG8_SCHED;
;             PG8_LDB(B1, 1, 1); PG8_STAGE(PG8_SB(1, 0), b3, voffB);
	s_add_u32 s84, s40, 0x10000
	s_addc_u32 s85, s41, 0
	s_add_i32 s66, s79, s45
	s_mov_b32 m0, s66
	s_nop 0
	global_load_lds_dwordx4 v178, s[84:85]
	s_add_i32 m0, s66, 0x2000
	s_nop 0
	global_load_lds_dwordx4 v182, s[84:85]
	s_waitcnt vmcnt(6)
	s_barrier
	s_setprio 1
	v_mfma_f32_16x16x32_bf16 v[52:55], v[192:195], v[144:147], v[52:55]
	v_mfma_f32_16x16x32_bf16 v[48:51], v[200:203], v[144:147], v[48:51]
	v_mfma_f32_16x16x32_bf16 v[36:39], v[192:195], v[152:155], v[36:39]
	v_mfma_f32_16x16x32_bf16 v[32:35], v[200:203], v[152:155], v[32:35]
	v_mfma_f32_16x16x32_bf16 v[20:23], v[192:195], v[160:163], v[20:23]
	v_mfma_f32_16x16x32_bf16 v[16:19], v[200:203], v[160:163], v[16:19]
	v_mfma_f32_16x16x32_bf16 v[4:7], v[192:195], v[168:171], v[4:7]
	v_mfma_f32_16x16x32_bf16 v[0:3], v[200:203], v[168:171], v[0:3]
	v_mfma_f32_16x16x32_bf16 v[52:55], v[196:199], v[148:151], v[52:55]
	v_mfma_f32_16x16x32_bf16 v[48:51], v[212:215], v[148:151], v[48:51]
	v_mfma_f32_16x16x32_bf16 v[36:39], v[196:199], v[156:159], v[36:39]
	v_mfma_f32_16x16x32_bf16 v[32:35], v[212:215], v[156:159], v[32:35]
	v_mfma_f32_16x16x32_bf16 v[20:23], v[196:199], v[164:167], v[20:23]
	v_mfma_f32_16x16x32_bf16 v[16:19], v[212:215], v[164:167], v[16:19]
	v_mfma_f32_16x16x32_bf16 v[4:7], v[196:199], v[172:175], v[4:7]
	v_mfma_f32_16x16x32_bf16 v[0:3], v[212:215], v[172:175], v[0:3]
	s_setprio 0
	s_add_i32 s66, 0, 0x18000
	v_add_u32_e32 v140, s66, v206
	s_barrier
	ds_read_b128 v[128:131], v140
	ds_read_b128 v[132:135], v140 offset:1024
	ds_read_b128 v[136:139], v140 offset:2048
	ds_read_b128 v[140:143], v140 offset:3072
	s_add_u32 s42, s42, 0x40000
	s_addc_u32 s43, s43, 0
	s_mov_b32 m0, s46
	ds_read_b128 v[144:147], v208 offset:32768
	ds_read_b128 v[148:151], v208 offset:33792
	ds_read_b128 v[152:155], v208 offset:34816
	ds_read_b128 v[156:159], v208 offset:35840
	ds_read_b128 v[160:163], v208 offset:36864
	ds_read_b128 v[164:167], v208 offset:37888
	ds_read_b128 v[168:171], v208 offset:38912
	ds_read_b128 v[172:175], v208 offset:39936
	global_load_lds_dwordx4 v176, s[42:43]
	s_mov_b32 m0, s47
	s_nop 0
	global_load_lds_dwordx4 v180, s[42:43]
	s_waitcnt lgkmcnt(8)
	s_barrier
	s_waitcnt lgkmcnt(0)
	s_setprio 1
	s_waitcnt lgkmcnt(0)
	v_mfma_f32_16x16x32_bf16 v[120:123], v[128:131], v[144:147], v[120:123]
	v_mfma_f32_16x16x32_bf16 v[124:127], v[136:139], v[144:147], v[124:127]
	v_mfma_f32_16x16x32_bf16 v[108:111], v[128:131], v[152:155], v[108:111]
	v_mfma_f32_16x16x32_bf16 v[104:107], v[136:139], v[152:155], v[104:107]
	v_mfma_f32_16x16x32_bf16 v[92:95], v[128:131], v[160:163], v[92:95]
	v_mfma_f32_16x16x32_bf16 v[88:91], v[136:139], v[160:163], v[88:91]
	v_mfma_f32_16x16x32_bf16 v[76:79], v[128:131], v[168:171], v[76:79]
	v_mfma_f32_16x16x32_bf16 v[72:75], v[136:139], v[168:171], v[72:75]
	v_mfma_f32_16x16x32_bf16 v[120:123], v[132:135], v[148:151], v[120:123]
	v_mfma_f32_16x16x32_bf16 v[124:127], v[140:143], v[148:151], v[124:127]
	v_mfma_f32_16x16x32_bf16 v[108:111], v[132:135], v[156:159], v[108:111]
	v_mfma_f32_16x16x32_bf16 v[104:107], v[140:143], v[156:159], v[104:107]
	v_mfma_f32_16x16x32_bf16 v[92:95], v[132:135], v[164:167], v[92:95]
	v_mfma_f32_16x16x32_bf16 v[88:91], v[140:143], v[164:167], v[88:91]
	v_mfma_f32_16x16x32_bf16 v[76:79], v[132:135], v[172:175], v[76:79]
	v_mfma_f32_16x16x32_bf16 v[72:75], v[140:143], v[172:175], v[72:75]
	s_setprio 0
	s_barrier
	s_add_i32 s42, 0, 0x1c000
	s_add_i32 s43, s66, s45
	v_add_u32_e32 v212, s42, v206
	v_lshl_add_u64 v[216:217], v[216:217], 0, s[22:23]
	s_mov_b32 m0, s43
	ds_read_b128 v[192:195], v212
	ds_read_b128 v[196:199], v212 offset:1024
	ds_read_b128 v[200:203], v212 offset:2048
	ds_read_b128 v[212:215], v212 offset:3072
	global_load_lds_dwordx4 v[216:217], off
	v_lshl_add_u64 v[216:217], v[218:219], 0, s[22:23]
	s_add_i32 m0, s43, 0x2000
	s_nop 0
	global_load_lds_dwordx4 v[216:217], off
	s_barrier
; #define PG8_STAGE(bufoff, gbase, voff) do { _Pragma("unroll") for (int _i = 0; _i < 2; ++_i) \
;         __builtin_amdgcn_global_load_lds((const unsigned*)((const char*)(gbase) + (voff)[_i]), (LAS unsigned*)(lds + (bufoff) + ldsw + _i * 8192), 16, 0, 0); } while (0)
; #define PG8_LDA(dst, b, h) do { _Pragma("unroll") for (int m = 0; m < 4; ++m) _Pragma("unroll") for (int k = 0; k < 2; ++k) dst[m][k] = *(const LAS bf16x8*)(lds + PG8_SA(b, h) + aoff + m * 2048 + k * 1024); } while (0)
; #define PG8_MMA(ai, bj, At, Bt) do { __builtin_amdgcn_s_setprio(1); _Pragma("unroll") for (int m = 0; m < 4; ++m) _Pragma("unroll") for (int n = 0; n < 2; ++n) _Pragma("unroll") for (int k = 0; k < 2; ++k) \
;         acc[ai][bj][m][n] = __builtin_amdgcn_mfma_f32_16x16x32_bf16(Bt[n][k], At[m][k], acc[ai][bj][m][n], 0, 0, 0); __builtin_amdgcn_s_setprio(0); } while (0)
; #define PG8_WAIT_V(n) asm volatile("s_waitcnt vmcnt(" #n ")" ::: "memory")
; #define PG8_WAIT_L(n) asm volatile("s_waitcnt lgkmcnt(" #n ")" ::: "memory")
; #define PG8_BAR __builtin_amdgcn_s_barrier()
; #define PG8_SCHED __builtin_amdgcn_sched_barrier(0)
; template <class Epi>
; __device__ __forceinline__ void gemm_phase(LAS unsigned char* lds, const Gemm g, const StaticOrder& S, const Epi& E) {
;     ...
;             PG8_BAR; PG8_WAIT_L(0); PG8_MMA(0, 1, At, B1); PG8_BAR;
;             PG8_LDA(At, 1, 1); PG8_STAGE(PG8_SA(1, 0), a3, voffA);
;             PG8_BAR; PG8_WAIT_L(0); PG8_MMA(1, 0, At, B0); PG8_BAR; PG8_SCHED;
;             PG8_STAGE(PG8_SB(1, 1), b3 + hstepB, voffB);
;             PG8_WAIT_V(6); PG8_BAR; PG8_MMA(1, 1, At, B1); PG8_BAR;
;         }
	s_waitcnt lgkmcnt(0)
	s_setprio 1
	s_waitcnt lgkmcnt(0)
	v_mfma_f32_16x16x32_bf16 v[116:119], v[192:195], v[144:147], v[116:119]
	v_mfma_f32_16x16x32_bf16 v[112:115], v[200:203], v[144:147], v[112:115]
	v_mfma_f32_16x16x32_bf16 v[100:103], v[192:195], v[152:155], v[100:103]
	v_mfma_f32_16x16x32_bf16 v[96:99], v[200:203], v[152:155], v[96:99]
	v_mfma_f32_16x16x32_bf16 v[84:87], v[192:195], v[160:163], v[84:87]
	v_mfma_f32_16x16x32_bf16 v[80:83], v[200:203], v[160:163], v[80:83]
	v_mfma_f32_16x16x32_bf16 v[68:71], v[192:195], v[168:171], v[68:71]
	v_mfma_f32_16x16x32_bf16 v[64:67], v[200:203], v[168:171], v[64:67]
	v_mfma_f32_16x16x32_bf16 v[116:119], v[196:199], v[148:151], v[116:119]
	v_mfma_f32_16x16x32_bf16 v[112:115], v[212:215], v[148:151], v[112:115]
	v_mfma_f32_16x16x32_bf16 v[100:103], v[196:199], v[156:159], v[100:103]
	v_mfma_f32_16x16x32_bf16 v[96:99], v[212:215], v[156:159], v[96:99]
	v_mfma_f32_16x16x32_bf16 v[84:87], v[196:199], v[164:167], v[84:87]
	v_mfma_f32_16x16x32_bf16 v[80:83], v[212:215], v[164:167], v[80:83]
	v_mfma_f32_16x16x32_bf16 v[68:71], v[196:199], v[172:175], v[68:71]
	v_mfma_f32_16x16x32_bf16 v[64:67], v[212:215], v[172:175], v[64:67]
	s_setprio 0
	s_mov_b32 m0, s62
	v_lshl_add_u64 v[216:217], v[220:221], 0, s[22:23]
	s_barrier
	ds_read_b128 v[144:147], v208 offset:49152
	ds_read_b128 v[148:151], v208 offset:50176
	ds_read_b128 v[152:155], v208 offset:51200
	ds_read_b128 v[156:159], v208 offset:52224
	ds_read_b128 v[160:163], v208 offset:53248
	ds_read_b128 v[164:167], v208 offset:54272
	ds_read_b128 v[168:171], v208 offset:55296
	ds_read_b128 v[172:175], v208 offset:56320
	global_load_lds_dwordx4 v[216:217], off
	v_lshl_add_u64 v[216:217], v[222:223], 0, s[22:23]
	s_mov_b32 m0, s63
	s_nop 0
	global_load_lds_dwordx4 v[216:217], off
	s_barrier
	s_waitcnt lgkmcnt(0)
	s_setprio 1
	s_waitcnt lgkmcnt(0)
	v_mfma_f32_16x16x32_bf16 v[60:63], v[128:131], v[144:147], v[60:63]
	v_mfma_f32_16x16x32_bf16 v[56:59], v[136:139], v[144:147], v[56:59]
	v_mfma_f32_16x16x32_bf16 v[44:47], v[128:131], v[152:155], v[44:47]
	v_mfma_f32_16x16x32_bf16 v[40:43], v[136:139], v[152:155], v[40:43]
	v_mfma_f32_16x16x32_bf16 v[28:31], v[128:131], v[160:163], v[28:31]
	v_mfma_f32_16x16x32_bf16 v[24:27], v[136:139], v[160:163], v[24:27]
	v_mfma_f32_16x16x32_bf16 v[12:15], v[128:131], v[168:171], v[12:15]
	v_mfma_f32_16x16x32_bf16 v[8:11], v[136:139], v[168:171], v[8:11]
	v_mfma_f32_16x16x32_bf16 v[60:63], v[132:135], v[148:151], v[60:63]
	v_mfma_f32_16x16x32_bf16 v[56:59], v[140:143], v[148:151], v[56:59]
	v_mfma_f32_16x16x32_bf16 v[44:47], v[132:135], v[156:159], v[44:47]
	v_mfma_f32_16x16x32_bf16 v[40:43], v[140:143], v[156:159], v[40:43]
	v_mfma_f32_16x16x32_bf16 v[28:31], v[132:135], v[164:167], v[28:31]
	v_mfma_f32_16x16x32_bf16 v[24:27], v[140:143], v[164:167], v[24:27]
	v_mfma_f32_16x16x32_bf16 v[12:15], v[132:135], v[172:175], v[12:15]
	v_mfma_f32_16x16x32_bf16 v[8:11], v[140:143], v[172:175], v[8:11]
	s_setprio 0
	s_barrier
	s_add_u32 s40, s40, 0x10080
	s_addc_u32 s41, s41, 0
	s_add_i32 s42, s42, s45
	s_mov_b32 m0, s42
	s_nop 0
	global_load_lds_dwordx4 v178, s[40:41]
	s_add_i32 m0, s42, 0x2000
	s_nop 0
	global_load_lds_dwordx4 v182, s[40:41]
	s_waitcnt vmcnt(6)
	s_barrier
	s_setprio 1
	v_mfma_f32_16x16x32_bf16 v[52:55], v[192:195], v[144:147], v[52:55]
	v_mfma_f32_16x16x32_bf16 v[48:51], v[200:203], v[144:147], v[48:51]
	v_mfma_f32_16x16x32_bf16 v[36:39], v[192:195], v[152:155], v[36:39]
	v_mfma_f32_16x16x32_bf16 v[32:35], v[200:203], v[152:155], v[32:35]
	v_mfma_f32_16x16x32_bf16 v[20:23], v[192:195], v[160:163], v[20:23]
	v_mfma_f32_16x16x32_bf16 v[16:19], v[200:203], v[160:163], v[16:19]
	v_mfma_f32_16x16x32_bf16 v[4:7], v[192:195], v[168:171], v[4:7]
	v_mfma_f32_16x16x32_bf16 v[0:3], v[200:203], v[168:171], v[0:3]
	v_mfma_f32_16x16x32_bf16 v[52:55], v[196:199], v[148:151], v[52:55]
	v_mfma_f32_16x16x32_bf16 v[48:51], v[212:215], v[148:151], v[48:51]
	v_mfma_f32_16x16x32_bf16 v[36:39], v[196:199], v[156:159], v[36:39]
	v_mfma_f32_16x16x32_bf16 v[32:35], v[212:215], v[156:159], v[32:35]
	v_mfma_f32_16x16x32_bf16 v[20:23], v[196:199], v[164:167], v[20:23]
	v_mfma_f32_16x16x32_bf16 v[16:19], v[212:215], v[164:167], v[16:19]
	v_mfma_f32_16x16x32_bf16 v[4:7], v[196:199], v[172:175], v[4:7]
	v_mfma_f32_16x16x32_bf16 v[0:3], v[212:215], v[172:175], v[0:3]
	s_setprio 0
	s_add_u32 s10, s10, 0x100
	s_addc_u32 s11, s11, 0
	s_add_u32 s80, s80, 0x100
	s_addc_u32 s81, s81, 0
	s_cmp_ge_i32 s82, s61
	s_mov_b32 s40, s82
	s_barrier
	s_cbranch_scc0 .LBB0_1442

; #define PG8_STAGE(bufoff, gbase, voff) do { _Pragma("unroll") for (int _i = 0; _i < 2; ++_i) \
;         __builtin_amdgcn_global_load_lds((const unsigned*)((const char*)(gbase) + (voff)[_i]), (LAS unsigned*)(lds + (bufoff) + ldsw + _i * 8192), 16, 0, 0); } while (0)
; #define PG8_LDA(dst, b, h) do { _Pragma("unroll") for (int m = 0; m < 4; ++m) _Pragma("unroll") for (int k = 0; k < 2; ++k) dst[m][k] = *(const LAS bf16x8*)(lds + PG8_SA(b, h) + aoff + m * 2048 + k * 1024); } while (0)
; #define PG8_LDB(dst, b, h) do { _Pragma("unroll") for (int n = 0; n < 2; ++n) _Pragma("unroll") for (int k = 0; k < 2; ++k) dst[n][k] = *(const LAS bf16x8*)(lds + PG8_SB(b, h) + boff + n * 2048 + k * 1024); } while (0)
; #define PG8_MMA(ai, bj, At, Bt) do { __builtin_amdgcn_s_setprio(1); _Pragma("unroll") for (int m = 0; m < 4; ++m) _Pragma("unroll") for (int n = 0; n < 2; ++n) _Pragma("unroll") for (int k = 0; k < 2; ++k) \
;         acc[ai][bj][m][n] = __builtin_amdgcn_mfma_f32_16x16x32_bf16(Bt[n][k], At[m][k], acc[ai][bj][m][n], 0, 0, 0); __builtin_amdgcn_s_setprio(0); } while (0)
; #define PG8_WAIT_L(n) asm volatile("s_waitcnt lgkmcnt(" #n ")" ::: "memory")
; #define PG8_BAR __builtin_amdgcn_s_barrier()
; #define PG8_SCHED __builtin_amdgcn_sched_barrier(0)
; template <class Epi>
; __device__ __forceinline__ void gemm_phase(LAS unsigned char* lds, const Gemm g, const StaticOrder& S, const Epi& E) {
;     ...
;             PG8_LDB(B0, 0, 0); PG8_SCHED; PG8_LDA(At, 0, 0); PG8_STAGE(PG8_SA(1, 1), a1 + hstepA, voffA);
;             PG8_WAIT_L(8); PG8_BAR; PG8_WAIT_L(0); PG8_MMA(0, 0, At, B0); PG8_BAR; PG8_SCHED;
;             PG8_LDB(B1, 0, 1); PG8_STAGE(PG8_SB(0, 0), b2, voffB);
;             PG8_BAR; PG8_WAIT_L(0); PG8_MMA(0, 1, At, B1); PG8_BAR;
;             PG8_LDA(At, 0, 1); PG8_STAGE(PG8_SA(0, 0), a2, voffA);
;             PG8_BAR; PG8_WAIT_L(0); PG8_MMA(1, 0, At, B0); PG8_BAR; PG8_SCHED;
;             PG8_STAGE(PG8_SB(0, 1), b2 + hstepB, voffB);
.Lgu15558_skip:
	s_add_i32 m0, s37, 0xc000
	ds_read_b128 v[168:171], v152
	ds_read_b128 v[172:175], v152 offset:1024
	ds_read_b128 v[176:179], v152 offset:2048
	ds_read_b128 v[180:183], v152 offset:3072
	ds_read_b128 v[184:187], v152 offset:4096
	ds_read_b128 v[188:191], v152 offset:5120
	ds_read_b128 v[192:195], v152 offset:6144
	ds_read_b128 v[196:199], v152 offset:7168
	global_load_lds_dwordx4 v136, s[8:9]
	s_add_i32 m0, s37, 0xe000
	s_nop 0
	global_load_lds_dwordx4 v138, s[8:9]
	s_waitcnt lgkmcnt(8)
	s_barrier
	s_waitcnt lgkmcnt(0)
	s_setprio 1
	s_waitcnt lgkmcnt(0)
	v_mfma_f32_16x16x32_bf16 v[116:119], v[144:147], v[168:171], v[116:119]
	v_mfma_f32_16x16x32_bf16 v[112:115], v[160:163], v[168:171], v[112:115]
	v_mfma_f32_16x16x32_bf16 v[104:107], v[144:147], v[176:179], v[104:107]
	v_mfma_f32_16x16x32_bf16 v[96:99], v[160:163], v[176:179], v[96:99]
	v_mfma_f32_16x16x32_bf16 v[88:91], v[144:147], v[184:187], v[88:91]
	v_mfma_f32_16x16x32_bf16 v[80:83], v[160:163], v[184:187], v[80:83]
	v_mfma_f32_16x16x32_bf16 v[72:75], v[144:147], v[192:195], v[72:75]
	v_mfma_f32_16x16x32_bf16 v[64:67], v[160:163], v[192:195], v[64:67]
	v_mfma_f32_16x16x32_bf16 v[116:119], v[156:159], v[172:175], v[116:119]
	v_mfma_f32_16x16x32_bf16 v[112:115], v[164:167], v[172:175], v[112:115]
	v_mfma_f32_16x16x32_bf16 v[104:107], v[156:159], v[180:183], v[104:107]
	v_mfma_f32_16x16x32_bf16 v[96:99], v[164:167], v[180:183], v[96:99]
	v_mfma_f32_16x16x32_bf16 v[88:91], v[156:159], v[188:191], v[88:91]
	v_mfma_f32_16x16x32_bf16 v[80:83], v[164:167], v[188:191], v[80:83]
	v_mfma_f32_16x16x32_bf16 v[72:75], v[156:159], v[196:199], v[72:75]
	v_mfma_f32_16x16x32_bf16 v[64:67], v[164:167], v[196:199], v[64:67]
	s_setprio 0
	s_barrier
	s_add_i32 s66, s49, s36
	v_lshl_add_u64 v[208:209], s[26:27], 0, v[130:131]
	s_mov_b32 m0, s66
	ds_read_b128 v[200:203], v153
	ds_read_b128 v[204:207], v153 offset:1024
	ds_read_b128 v[212:215], v153 offset:2048
	ds_read_b128 v[216:219], v153 offset:3072
	global_load_lds_dwordx4 v[208:209], off
	v_lshl_add_u64 v[220:221], s[26:27], 0, v[134:135]
	s_add_i32 m0, s66, 0x2000
	s_nop 0
	global_load_lds_dwordx4 v[220:221], off
	s_barrier
	s_waitcnt lgkmcnt(0)
	s_setprio 1
	s_waitcnt lgkmcnt(0)
	v_mfma_f32_16x16x32_bf16 v[124:127], v[200:203], v[168:171], v[124:127]
	v_mfma_f32_16x16x32_bf16 v[120:123], v[212:215], v[168:171], v[120:123]
	v_mfma_f32_16x16x32_bf16 v[108:111], v[200:203], v[176:179], v[108:111]
	v_mfma_f32_16x16x32_bf16 v[100:103], v[212:215], v[176:179], v[100:103]
	v_mfma_f32_16x16x32_bf16 v[92:95], v[200:203], v[184:187], v[92:95]
	v_mfma_f32_16x16x32_bf16 v[84:87], v[212:215], v[184:187], v[84:87]
	v_mfma_f32_16x16x32_bf16 v[76:79], v[200:203], v[192:195], v[76:79]
	v_mfma_f32_16x16x32_bf16 v[68:71], v[212:215], v[192:195], v[68:71]
	v_mfma_f32_16x16x32_bf16 v[124:127], v[204:207], v[172:175], v[124:127]
	v_mfma_f32_16x16x32_bf16 v[120:123], v[216:219], v[172:175], v[120:123]
	v_mfma_f32_16x16x32_bf16 v[108:111], v[204:207], v[180:183], v[108:111]
	v_mfma_f32_16x16x32_bf16 v[100:103], v[216:219], v[180:183], v[100:103]
	v_mfma_f32_16x16x32_bf16 v[92:95], v[204:207], v[188:191], v[92:95]
	v_mfma_f32_16x16x32_bf16 v[84:87], v[216:219], v[188:191], v[84:87]
	v_mfma_f32_16x16x32_bf16 v[76:79], v[204:207], v[196:199], v[76:79]
	v_mfma_f32_16x16x32_bf16 v[68:71], v[216:219], v[196:199], v[68:71]
	s_setprio 0
	s_mov_b32 m0, s37
	v_lshl_add_u64 v[222:223], s[28:29], 0, v[128:129]
	s_barrier
	ds_read_b128 v[168:171], v152 offset:16384
	ds_read_b128 v[172:175], v152 offset:17408
	ds_read_b128 v[176:179], v152 offset:18432
	ds_read_b128 v[180:183], v152 offset:19456
	ds_read_b128 v[184:187], v152 offset:20480
	ds_read_b128 v[188:191], v152 offset:21504
	ds_read_b128 v[192:195], v152 offset:22528
	ds_read_b128 v[196:199], v152 offset:23552
	global_load_lds_dwordx4 v[222:223], off
	v_lshl_add_u64 v[224:225], s[28:29], 0, v[132:133]
	s_mov_b32 m0, s38
	s_nop 0
	global_load_lds_dwordx4 v[224:225], off
	s_barrier
	s_waitcnt lgkmcnt(0)
	s_setprio 1
	s_waitcnt lgkmcnt(0)
	v_mfma_f32_16x16x32_bf16 v[56:59], v[144:147], v[168:171], v[56:59]
	v_mfma_f32_16x16x32_bf16 v[48:51], v[160:163], v[168:171], v[48:51]
	v_mfma_f32_16x16x32_bf16 v[40:43], v[144:147], v[176:179], v[40:43]
	v_mfma_f32_16x16x32_bf16 v[32:35], v[160:163], v[176:179], v[32:35]
	v_mfma_f32_16x16x32_bf16 v[24:27], v[144:147], v[184:187], v[24:27]
	v_mfma_f32_16x16x32_bf16 v[16:19], v[160:163], v[184:187], v[16:19]
	v_mfma_f32_16x16x32_bf16 v[8:11], v[144:147], v[192:195], v[8:11]
	v_mfma_f32_16x16x32_bf16 v[4:7], v[160:163], v[192:195], v[4:7]
	v_mfma_f32_16x16x32_bf16 v[56:59], v[156:159], v[172:175], v[56:59]
	v_mfma_f32_16x16x32_bf16 v[48:51], v[164:167], v[172:175], v[48:51]
	v_mfma_f32_16x16x32_bf16 v[40:43], v[156:159], v[180:183], v[40:43]
	v_mfma_f32_16x16x32_bf16 v[32:35], v[164:167], v[180:183], v[32:35]
	v_mfma_f32_16x16x32_bf16 v[24:27], v[156:159], v[188:191], v[24:27]
	v_mfma_f32_16x16x32_bf16 v[16:19], v[164:167], v[188:191], v[16:19]
	v_mfma_f32_16x16x32_bf16 v[8:11], v[156:159], v[196:199], v[8:11]
	v_mfma_f32_16x16x32_bf16 v[4:7], v[164:167], v[196:199], v[4:7]
	s_setprio 0
	s_barrier
	s_add_u32 s78, s26, 0x40000
	s_addc_u32 s79, s27, 0
	s_add_i32 s66, s60, s36
	s_mov_b32 m0, s66
	s_nop 0
	global_load_lds_dwordx4 v130, s[78:79]
	s_add_i32 m0, s66, 0x2000
	s_nop 0
	global_load_lds_dwordx4 v134, s[78:79]
	s_waitcnt vmcnt(6)
	s_barrier
; #define PG8_STAGE(bufoff, gbase, voff) do { _Pragma("unroll") for (int _i = 0; _i < 2; ++_i) \
;         __builtin_amdgcn_global_load_lds((const unsigned*)((const char*)(gbase) + (voff)[_i]), (LAS unsigned*)(lds + (bufoff) + ldsw + _i * 8192), 16, 0, 0); } while (0)
; #define PG8_LDA(dst, b, h) do { _Pragma("unroll") for (int m = 0; m < 4; ++m) _Pragma("unroll") for (int k = 0; k < 2; ++k) dst[m][k] = *(const LAS bf16x8*)(lds + PG8_SA(b, h) + aoff + m * 2048 + k * 1024); } while (0)
; #define PG8_LDB(dst, b, h) do { _Pragma("unroll") for (int n = 0; n < 2; ++n) _Pragma("unroll") for (int k = 0; k < 2; ++k) dst[n][k] = *(const LAS bf16x8*)(lds + PG8_SB(b, h) + boff + n * 2048 + k * 1024); } while (0)
; #define PG8_MMA(ai, bj, At, Bt) do { __builtin_amdgcn_s_setprio(1); _Pragma("unroll") for (int m = 0; m < 4; ++m) _Pragma("unroll") for (int n = 0; n < 2; ++n) _Pragma("unroll") for (int k = 0; k < 2; ++k) \
;         acc[ai][bj][m][n] = __builtin_amdgcn_mfma_f32_16x16x32_bf16(Bt[n][k], At[m][k], acc[ai][bj][m][n], 0, 0, 0); __builtin_amdgcn_s_setprio(0); } while (0)
; #define PG8_WAIT_V(n) asm volatile("s_waitcnt vmcnt(" #n ")" ::: "memory")
; #define PG8_WAIT_L(n) asm volatile("s_waitcnt lgkmcnt(" #n ")" ::: "memory")
; #define PG8_BAR __builtin_amdgcn_s_barrier()
; #define PG8_SCHED __builtin_amdgcn_sched_barrier(0)
; template <class Epi>
; __device__ __forceinline__ void gemm_phase(LAS unsigned char* lds, const Gemm g, const StaticOrder& S, const Epi& E) {
;     ...
;             PG8_WAIT_V(6); PG8_BAR; PG8_MMA(1, 1, At, B1); PG8_BAR;
;             PG8_LDB(B0, 1, 0); PG8_SCHED; PG8_LDA(At, 1, 0); PG8_STAGE(PG8_SA(0, 1), a2 + hstepA, voffA);
;             PG8_WAIT_L(8); PG8_BAR; PG8_WAIT_L(0); PG8_MMA(0, 0, At, B0); PG8_BAR; PG8_SCHED;
;             PG8_LDB(B1, 1, 1); PG8_STAGE(PG8_SB(1, 0), b3, voffB);
	s_setprio 1
	v_mfma_f32_16x16x32_bf16 v[60:63], v[200:203], v[168:171], v[60:63]
	v_mfma_f32_16x16x32_bf16 v[52:55], v[212:215], v[168:171], v[52:55]
	v_mfma_f32_16x16x32_bf16 v[44:47], v[200:203], v[176:179], v[44:47]
	v_mfma_f32_16x16x32_bf16 v[36:39], v[212:215], v[176:179], v[36:39]
	v_mfma_f32_16x16x32_bf16 v[28:31], v[200:203], v[184:187], v[28:31]
	v_mfma_f32_16x16x32_bf16 v[20:23], v[212:215], v[184:187], v[20:23]
	v_mfma_f32_16x16x32_bf16 v[12:15], v[200:203], v[192:195], v[12:15]
	v_mfma_f32_16x16x32_bf16 v[0:3], v[212:215], v[192:195], v[0:3]
	v_mfma_f32_16x16x32_bf16 v[60:63], v[204:207], v[172:175], v[60:63]
	v_mfma_f32_16x16x32_bf16 v[52:55], v[216:219], v[172:175], v[52:55]
	v_mfma_f32_16x16x32_bf16 v[44:47], v[204:207], v[180:183], v[44:47]
	v_mfma_f32_16x16x32_bf16 v[36:39], v[216:219], v[180:183], v[36:39]
	v_mfma_f32_16x16x32_bf16 v[28:31], v[204:207], v[188:191], v[28:31]
	v_mfma_f32_16x16x32_bf16 v[20:23], v[216:219], v[188:191], v[20:23]
	v_mfma_f32_16x16x32_bf16 v[12:15], v[204:207], v[196:199], v[12:15]
	v_mfma_f32_16x16x32_bf16 v[0:3], v[216:219], v[196:199], v[0:3]
	s_setprio 0
	s_add_i32 s66, 0, 0x18000
	v_add_u32_e32 v155, s66, v150
	s_barrier
	ds_read_b128 v[144:147], v155
	ds_read_b128 v[156:159], v155 offset:1024
	ds_read_b128 v[160:163], v155 offset:2048
	ds_read_b128 v[164:167], v155 offset:3072
	s_add_u32 s28, s28, 0x40000
	s_addc_u32 s29, s29, 0
	s_mov_b32 m0, s39
	ds_read_b128 v[168:171], v152 offset:32768
	ds_read_b128 v[172:175], v152 offset:33792
	ds_read_b128 v[176:179], v152 offset:34816
	ds_read_b128 v[180:183], v152 offset:35840
	ds_read_b128 v[184:187], v152 offset:36864
	ds_read_b128 v[188:191], v152 offset:37888
	ds_read_b128 v[192:195], v152 offset:38912
	ds_read_b128 v[196:199], v152 offset:39936
	global_load_lds_dwordx4 v128, s[28:29]
	s_mov_b32 m0, s40
	s_nop 0
	global_load_lds_dwordx4 v132, s[28:29]
	s_waitcnt lgkmcnt(8)
	s_barrier
	s_waitcnt lgkmcnt(0)
	s_setprio 1
	s_waitcnt lgkmcnt(0)
	v_mfma_f32_16x16x32_bf16 v[116:119], v[144:147], v[168:171], v[116:119]
	v_mfma_f32_16x16x32_bf16 v[112:115], v[160:163], v[168:171], v[112:115]
	v_mfma_f32_16x16x32_bf16 v[104:107], v[144:147], v[176:179], v[104:107]
	v_mfma_f32_16x16x32_bf16 v[96:99], v[160:163], v[176:179], v[96:99]
	v_mfma_f32_16x16x32_bf16 v[88:91], v[144:147], v[184:187], v[88:91]
	v_mfma_f32_16x16x32_bf16 v[80:83], v[160:163], v[184:187], v[80:83]
	v_mfma_f32_16x16x32_bf16 v[72:75], v[144:147], v[192:195], v[72:75]
	v_mfma_f32_16x16x32_bf16 v[64:67], v[160:163], v[192:195], v[64:67]
	v_mfma_f32_16x16x32_bf16 v[116:119], v[156:159], v[172:175], v[116:119]
	v_mfma_f32_16x16x32_bf16 v[112:115], v[164:167], v[172:175], v[112:115]
	v_mfma_f32_16x16x32_bf16 v[104:107], v[156:159], v[180:183], v[104:107]
	v_mfma_f32_16x16x32_bf16 v[96:99], v[164:167], v[180:183], v[96:99]
	v_mfma_f32_16x16x32_bf16 v[88:91], v[156:159], v[188:191], v[88:91]
	v_mfma_f32_16x16x32_bf16 v[80:83], v[164:167], v[188:191], v[80:83]
	v_mfma_f32_16x16x32_bf16 v[72:75], v[156:159], v[196:199], v[72:75]
	v_mfma_f32_16x16x32_bf16 v[64:67], v[164:167], v[196:199], v[64:67]
	s_setprio 0
	s_barrier
	s_add_i32 s28, 0, 0x1c000
	s_add_i32 s29, s66, s36
	v_add_u32_e32 v155, s28, v150
	v_lshl_add_u64 v[208:209], v[208:209], 0, s[10:11]
	s_mov_b32 m0, s29
	ds_read_b128 v[200:203], v155
	ds_read_b128 v[204:207], v155 offset:1024
	ds_read_b128 v[212:215], v155 offset:2048
	ds_read_b128 v[216:219], v155 offset:3072
	global_load_lds_dwordx4 v[208:209], off
	v_lshl_add_u64 v[208:209], v[220:221], 0, s[10:11]
	s_add_i32 m0, s29, 0x2000
	s_nop 0
	global_load_lds_dwordx4 v[208:209], off
	s_barrier
; #define PG8_STAGE(bufoff, gbase, voff) do { _Pragma("unroll") for (int _i = 0; _i < 2; ++_i) \
;         __builtin_amdgcn_global_load_lds((const unsigned*)((const char*)(gbase) + (voff)[_i]), (LAS unsigned*)(lds + (bufoff) + ldsw + _i * 8192), 16, 0, 0); } while (0)
; #define PG8_LDA(dst, b, h) do { _Pragma("unroll") for (int m = 0; m < 4; ++m) _Pragma("unroll") for (int k = 0; k < 2; ++k) dst[m][k] = *(const LAS bf16x8*)(lds + PG8_SA(b, h) + aoff + m * 2048 + k * 1024); } while (0)
; #define PG8_MMA(ai, bj, At, Bt) do { __builtin_amdgcn_s_setprio(1); _Pragma("unroll") for (int m = 0; m < 4; ++m) _Pragma("unroll") for (int n = 0; n < 2; ++n) _Pragma("unroll") for (int k = 0; k < 2; ++k) \
;         acc[ai][bj][m][n] = __builtin_amdgcn_mfma_f32_16x16x32_bf16(Bt[n][k], At[m][k], acc[ai][bj][m][n], 0, 0, 0); __builtin_amdgcn_s_setprio(0); } while (0)
; #define PG8_WAIT_V(n) asm volatile("s_waitcnt vmcnt(" #n ")" ::: "memory")
; #define PG8_WAIT_L(n) asm volatile("s_waitcnt lgkmcnt(" #n ")" ::: "memory")
; #define PG8_BAR __builtin_amdgcn_s_barrier()
; #define PG8_SCHED __builtin_amdgcn_sched_barrier(0)
; template <class Epi>
; __device__ __forceinline__ void gemm_phase(LAS unsigned char* lds, const Gemm g, const StaticOrder& S, const Epi& E) {
;     ...
;             PG8_BAR; PG8_WAIT_L(0); PG8_MMA(0, 1, At, B1); PG8_BAR;
;             PG8_LDA(At, 1, 1); PG8_STAGE(PG8_SA(1, 0), a3, voffA);
;             PG8_BAR; PG8_WAIT_L(0); PG8_MMA(1, 0, At, B0); PG8_BAR; PG8_SCHED;
;             PG8_STAGE(PG8_SB(1, 1), b3 + hstepB, voffB);
;             PG8_WAIT_V(6); PG8_BAR; PG8_MMA(1, 1, At, B1); PG8_BAR;
	s_waitcnt lgkmcnt(0)
	s_setprio 1
	s_waitcnt lgkmcnt(0)
	v_mfma_f32_16x16x32_bf16 v[124:127], v[200:203], v[168:171], v[124:127]
	v_mfma_f32_16x16x32_bf16 v[120:123], v[212:215], v[168:171], v[120:123]
	v_mfma_f32_16x16x32_bf16 v[108:111], v[200:203], v[176:179], v[108:111]
	v_mfma_f32_16x16x32_bf16 v[100:103], v[212:215], v[176:179], v[100:103]
	v_mfma_f32_16x16x32_bf16 v[92:95], v[200:203], v[184:187], v[92:95]
	v_mfma_f32_16x16x32_bf16 v[84:87], v[212:215], v[184:187], v[84:87]
	v_mfma_f32_16x16x32_bf16 v[76:79], v[200:203], v[192:195], v[76:79]
	v_mfma_f32_16x16x32_bf16 v[68:71], v[212:215], v[192:195], v[68:71]
	v_mfma_f32_16x16x32_bf16 v[124:127], v[204:207], v[172:175], v[124:127]
	v_mfma_f32_16x16x32_bf16 v[120:123], v[216:219], v[172:175], v[120:123]
	v_mfma_f32_16x16x32_bf16 v[108:111], v[204:207], v[180:183], v[108:111]
	v_mfma_f32_16x16x32_bf16 v[100:103], v[216:219], v[180:183], v[100:103]
	v_mfma_f32_16x16x32_bf16 v[92:95], v[204:207], v[188:191], v[92:95]
	v_mfma_f32_16x16x32_bf16 v[84:87], v[216:219], v[188:191], v[84:87]
	v_mfma_f32_16x16x32_bf16 v[76:79], v[204:207], v[196:199], v[76:79]
	v_mfma_f32_16x16x32_bf16 v[68:71], v[216:219], v[196:199], v[68:71]
	s_setprio 0
	s_mov_b32 m0, s44
	v_lshl_add_u64 v[208:209], v[222:223], 0, s[10:11]
	s_barrier
	ds_read_b128 v[168:171], v152 offset:49152
	ds_read_b128 v[172:175], v152 offset:50176
	ds_read_b128 v[176:179], v152 offset:51200
	ds_read_b128 v[180:183], v152 offset:52224
	ds_read_b128 v[184:187], v152 offset:53248
	ds_read_b128 v[188:191], v152 offset:54272
	ds_read_b128 v[192:195], v152 offset:55296
	ds_read_b128 v[196:199], v152 offset:56320
	global_load_lds_dwordx4 v[208:209], off
	v_lshl_add_u64 v[208:209], v[224:225], 0, s[10:11]
	s_mov_b32 m0, s45
	s_nop 0
	global_load_lds_dwordx4 v[208:209], off
	s_barrier
	s_waitcnt lgkmcnt(0)
	s_setprio 1
	s_waitcnt lgkmcnt(0)
	v_mfma_f32_16x16x32_bf16 v[56:59], v[144:147], v[168:171], v[56:59]
	v_mfma_f32_16x16x32_bf16 v[48:51], v[160:163], v[168:171], v[48:51]
	v_mfma_f32_16x16x32_bf16 v[40:43], v[144:147], v[176:179], v[40:43]
	v_mfma_f32_16x16x32_bf16 v[32:35], v[160:163], v[176:179], v[32:35]
	v_mfma_f32_16x16x32_bf16 v[24:27], v[144:147], v[184:187], v[24:27]
	v_mfma_f32_16x16x32_bf16 v[16:19], v[160:163], v[184:187], v[16:19]
	v_mfma_f32_16x16x32_bf16 v[8:11], v[144:147], v[192:195], v[8:11]
	v_mfma_f32_16x16x32_bf16 v[4:7], v[160:163], v[192:195], v[4:7]
	v_mfma_f32_16x16x32_bf16 v[56:59], v[156:159], v[172:175], v[56:59]
	v_mfma_f32_16x16x32_bf16 v[48:51], v[164:167], v[172:175], v[48:51]
	v_mfma_f32_16x16x32_bf16 v[40:43], v[156:159], v[180:183], v[40:43]
	v_mfma_f32_16x16x32_bf16 v[32:35], v[164:167], v[180:183], v[32:35]
	v_mfma_f32_16x16x32_bf16 v[24:27], v[156:159], v[188:191], v[24:27]
	v_mfma_f32_16x16x32_bf16 v[16:19], v[164:167], v[188:191], v[16:19]
	v_mfma_f32_16x16x32_bf16 v[8:11], v[156:159], v[196:199], v[8:11]
	v_mfma_f32_16x16x32_bf16 v[4:7], v[164:167], v[196:199], v[4:7]
	s_setprio 0
	s_barrier
	s_add_u32 s26, s26, 0x40080
	s_addc_u32 s27, s27, 0
	s_add_i32 s28, s28, s36
	s_mov_b32 m0, s28
	s_nop 0
	global_load_lds_dwordx4 v130, s[26:27]
	s_add_i32 m0, s28, 0x2000
	s_nop 0
	global_load_lds_dwordx4 v134, s[26:27]
	s_waitcnt vmcnt(6)
	s_barrier
	s_setprio 1
	v_mfma_f32_16x16x32_bf16 v[60:63], v[200:203], v[168:171], v[60:63]
	v_mfma_f32_16x16x32_bf16 v[52:55], v[212:215], v[168:171], v[52:55]
	v_mfma_f32_16x16x32_bf16 v[44:47], v[200:203], v[176:179], v[44:47]
	v_mfma_f32_16x16x32_bf16 v[36:39], v[212:215], v[176:179], v[36:39]
	v_mfma_f32_16x16x32_bf16 v[28:31], v[200:203], v[184:187], v[28:31]
	v_mfma_f32_16x16x32_bf16 v[20:23], v[212:215], v[184:187], v[20:23]
	v_mfma_f32_16x16x32_bf16 v[12:15], v[200:203], v[192:195], v[12:15]
	v_mfma_f32_16x16x32_bf16 v[0:3], v[212:215], v[192:195], v[0:3]
	v_mfma_f32_16x16x32_bf16 v[60:63], v[204:207], v[172:175], v[60:63]
	v_mfma_f32_16x16x32_bf16 v[52:55], v[216:219], v[172:175], v[52:55]
	v_mfma_f32_16x16x32_bf16 v[44:47], v[204:207], v[180:183], v[44:47]
	v_mfma_f32_16x16x32_bf16 v[36:39], v[216:219], v[180:183], v[36:39]
	v_mfma_f32_16x16x32_bf16 v[28:31], v[204:207], v[188:191], v[28:31]
	v_mfma_f32_16x16x32_bf16 v[20:23], v[216:219], v[188:191], v[20:23]
	v_mfma_f32_16x16x32_bf16 v[12:15], v[204:207], v[196:199], v[12:15]
	v_mfma_f32_16x16x32_bf16 v[0:3], v[216:219], v[196:199], v[0:3]
	s_setprio 0
	s_add_u32 s8, s8, 0x100
	s_addc_u32 s9, s9, 0
	s_add_u32 s65, s65, 0x100
	s_addc_u32 s76, s76, 0
	s_cmp_ge_i32 s77, s43
	s_mov_b32 s26, s77
	s_barrier
	s_cbranch_scc0 .LBB0_1544
	s_branch .LBB0_1535

; #define PG8_STAGE(bufoff, gbase, voff) do { _Pragma("unroll") for (int _i = 0; _i < 2; ++_i) \
;         __builtin_amdgcn_global_load_lds((const unsigned*)((const char*)(gbase) + (voff)[_i]), (LAS unsigned*)(lds + (bufoff) + ldsw + _i * 8192), 16, 0, 0); } while (0)
; #define PG8_LDA(dst, b, h) do { _Pragma("unroll") for (int m = 0; m < 4; ++m) _Pragma("unroll") for (int k = 0; k < 2; ++k) dst[m][k] = *(const LAS bf16x8*)(lds + PG8_SA(b, h) + aoff + m * 2048 + k * 1024); } while (0)
; #define PG8_LDB(dst, b, h) do { _Pragma("unroll") for (int n = 0; n < 2; ++n) _Pragma("unroll") for (int k = 0; k < 2; ++k) dst[n][k] = *(const LAS bf16x8*)(lds + PG8_SB(b, h) + boff + n * 2048 + k * 1024); } while (0)
; #define PG8_MMA(ai, bj, At, Bt) do { __builtin_amdgcn_s_setprio(1); _Pragma("unroll") for (int m = 0; m < 4; ++m) _Pragma("unroll") for (int n = 0; n < 2; ++n) _Pragma("unroll") for (int k = 0; k < 2; ++k) \
;         acc[ai][bj][m][n] = __builtin_amdgcn_mfma_f32_16x16x32_bf16(Bt[n][k], At[m][k], acc[ai][bj][m][n], 0, 0, 0); __builtin_amdgcn_s_setprio(0); } while (0)
; #define PG8_WAIT_L(n) asm volatile("s_waitcnt lgkmcnt(" #n ")" ::: "memory")
; #define PG8_BAR __builtin_amdgcn_s_barrier()
; #define PG8_SCHED __builtin_amdgcn_sched_barrier(0)
; template <class Epi>
; __device__ __forceinline__ void gemm_phase(LAS unsigned char* lds, const Gemm g, const StaticOrder& S, const Epi& E) {
;     ...
;         for (int t = 0; t < nt; t += 2) {
;             const bool last = (t == nt - 2);
;             const char* a1 = cA + (size_t)(t + 1) * kstep;
;             const char* a2 = last ? nA : cA + (size_t)(t + 2) * kstep; const char* b2 = last ? nB : cB + (size_t)(t + 2) * kstep;
;             const char* a3 = a2 + kstep; const char* b3 = b2 + kstep;
;             PG8_LDB(B0, 0, 0); PG8_SCHED; PG8_LDA(At, 0, 0); PG8_STAGE(PG8_SA(1, 1), a1 + hstepA, voffA);
;             PG8_WAIT_L(8); PG8_BAR; PG8_WAIT_L(0); PG8_MMA(0, 0, At, B0); PG8_BAR; PG8_SCHED;
;             PG8_LDB(B1, 0, 1); PG8_STAGE(PG8_SB(0, 0), b2, voffB);
;             PG8_BAR; PG8_WAIT_L(0); PG8_MMA(0, 1, At, B1); PG8_BAR;
;             PG8_LDA(At, 0, 1); PG8_STAGE(PG8_SA(0, 0), a2, voffA);
;             PG8_BAR; PG8_WAIT_L(0); PG8_MMA(1, 0, At, B0); PG8_BAR; PG8_SCHED;
.LBB0_1566:
	ds_read_b128 v[150:153], v147
	ds_read_b128 v[154:157], v147 offset:1024
	ds_read_b128 v[158:161], v147 offset:2048
	ds_read_b128 v[162:165], v147 offset:3072
	s_add_i32 s64, s26, 2
	s_add_u32 s27, s10, 0xffff0080
	s_addc_u32 s28, s11, -1
	s_cmp_eq_u32 s45, s26
	s_cselect_b32 s26, s61, s62
	s_cselect_b32 s29, s19, s28
	s_cselect_b32 s28, s21, s27
	s_cselect_b32 s27, s60, s63
	s_add_i32 m0, s17, 0xc000
	ds_read_b128 v[166:169], v148
	ds_read_b128 v[170:173], v148 offset:1024
	ds_read_b128 v[174:177], v148 offset:2048
	ds_read_b128 v[178:181], v148 offset:3072
	ds_read_b128 v[182:185], v148 offset:4096
	ds_read_b128 v[186:189], v148 offset:5120
	ds_read_b128 v[190:193], v148 offset:6144
	ds_read_b128 v[194:197], v148 offset:7168
	global_load_lds_dwordx4 v136, s[10:11]
	s_add_i32 m0, s17, 0xe000
	s_nop 0
	global_load_lds_dwordx4 v138, s[10:11]
	s_waitcnt lgkmcnt(8)
	s_barrier
	s_waitcnt lgkmcnt(0)
	s_setprio 1
	s_waitcnt lgkmcnt(0)
	v_mfma_f32_16x16x32_bf16 v[124:127], v[150:153], v[166:169], v[124:127]
	v_mfma_f32_16x16x32_bf16 v[120:123], v[158:161], v[166:169], v[120:123]
	v_mfma_f32_16x16x32_bf16 v[108:111], v[150:153], v[174:177], v[108:111]
	v_mfma_f32_16x16x32_bf16 v[104:107], v[158:161], v[174:177], v[104:107]
	v_mfma_f32_16x16x32_bf16 v[92:95], v[150:153], v[182:185], v[92:95]
	v_mfma_f32_16x16x32_bf16 v[88:91], v[158:161], v[182:185], v[88:91]
	v_mfma_f32_16x16x32_bf16 v[76:79], v[150:153], v[190:193], v[76:79]
	v_mfma_f32_16x16x32_bf16 v[72:75], v[158:161], v[190:193], v[72:75]
	v_mfma_f32_16x16x32_bf16 v[124:127], v[154:157], v[170:173], v[124:127]
	v_mfma_f32_16x16x32_bf16 v[120:123], v[162:165], v[170:173], v[120:123]
	v_mfma_f32_16x16x32_bf16 v[108:111], v[154:157], v[178:181], v[108:111]
	v_mfma_f32_16x16x32_bf16 v[104:107], v[162:165], v[178:181], v[104:107]
	v_mfma_f32_16x16x32_bf16 v[92:95], v[154:157], v[186:189], v[92:95]
	v_mfma_f32_16x16x32_bf16 v[88:91], v[162:165], v[186:189], v[88:91]
	v_mfma_f32_16x16x32_bf16 v[76:79], v[154:157], v[194:197], v[76:79]
	v_mfma_f32_16x16x32_bf16 v[72:75], v[162:165], v[194:197], v[72:75]
	s_setprio 0
	s_barrier
	s_add_i32 s65, s47, s36
	v_lshl_add_u64 v[216:217], s[26:27], 0, v[130:131]
	s_mov_b32 m0, s65
	ds_read_b128 v[198:201], v149
	ds_read_b128 v[202:205], v149 offset:1024
	ds_read_b128 v[206:209], v149 offset:2048
	ds_read_b128 v[212:215], v149 offset:3072
	global_load_lds_dwordx4 v[216:217], off
	v_lshl_add_u64 v[218:219], s[26:27], 0, v[134:135]
	s_add_i32 m0, s65, 0x2000
	s_nop 0
	global_load_lds_dwordx4 v[218:219], off
	s_barrier
	s_waitcnt lgkmcnt(0)
	s_setprio 1
	s_waitcnt lgkmcnt(0)
	v_mfma_f32_16x16x32_bf16 v[116:119], v[198:201], v[166:169], v[116:119]
	v_mfma_f32_16x16x32_bf16 v[112:115], v[206:209], v[166:169], v[112:115]
	v_mfma_f32_16x16x32_bf16 v[100:103], v[198:201], v[174:177], v[100:103]
	v_mfma_f32_16x16x32_bf16 v[96:99], v[206:209], v[174:177], v[96:99]
	v_mfma_f32_16x16x32_bf16 v[84:87], v[198:201], v[182:185], v[84:87]
	v_mfma_f32_16x16x32_bf16 v[80:83], v[206:209], v[182:185], v[80:83]
	v_mfma_f32_16x16x32_bf16 v[68:71], v[198:201], v[190:193], v[68:71]
	v_mfma_f32_16x16x32_bf16 v[64:67], v[206:209], v[190:193], v[64:67]
	v_mfma_f32_16x16x32_bf16 v[116:119], v[202:205], v[170:173], v[116:119]
	v_mfma_f32_16x16x32_bf16 v[112:115], v[212:215], v[170:173], v[112:115]
	v_mfma_f32_16x16x32_bf16 v[100:103], v[202:205], v[178:181], v[100:103]
	v_mfma_f32_16x16x32_bf16 v[96:99], v[212:215], v[178:181], v[96:99]
	v_mfma_f32_16x16x32_bf16 v[84:87], v[202:205], v[186:189], v[84:87]
	v_mfma_f32_16x16x32_bf16 v[80:83], v[212:215], v[186:189], v[80:83]
	v_mfma_f32_16x16x32_bf16 v[68:71], v[202:205], v[194:197], v[68:71]
	v_mfma_f32_16x16x32_bf16 v[64:67], v[212:215], v[194:197], v[64:67]
	s_setprio 0
	s_mov_b32 m0, s17
	v_lshl_add_u64 v[220:221], s[28:29], 0, v[128:129]
	s_barrier
	ds_read_b128 v[166:169], v148 offset:16384
	ds_read_b128 v[170:173], v148 offset:17408
	ds_read_b128 v[174:177], v148 offset:18432
	ds_read_b128 v[178:181], v148 offset:19456
	ds_read_b128 v[182:185], v148 offset:20480
	ds_read_b128 v[186:189], v148 offset:21504
	ds_read_b128 v[190:193], v148 offset:22528
	ds_read_b128 v[194:197], v148 offset:23552
	global_load_lds_dwordx4 v[220:221], off
	v_lshl_add_u64 v[222:223], s[28:29], 0, v[132:133]
	s_mov_b32 m0, s37
	s_nop 0
	global_load_lds_dwordx4 v[222:223], off
	s_barrier
	s_waitcnt lgkmcnt(0)
	s_setprio 1
	s_waitcnt lgkmcnt(0)
	v_mfma_f32_16x16x32_bf16 v[60:63], v[150:153], v[166:169], v[60:63]
	v_mfma_f32_16x16x32_bf16 v[56:59], v[158:161], v[166:169], v[56:59]
	v_mfma_f32_16x16x32_bf16 v[44:47], v[150:153], v[174:177], v[44:47]
	v_mfma_f32_16x16x32_bf16 v[40:43], v[158:161], v[174:177], v[40:43]
	v_mfma_f32_16x16x32_bf16 v[28:31], v[150:153], v[182:185], v[28:31]
	v_mfma_f32_16x16x32_bf16 v[24:27], v[158:161], v[182:185], v[24:27]
	v_mfma_f32_16x16x32_bf16 v[12:15], v[150:153], v[190:193], v[12:15]
	v_mfma_f32_16x16x32_bf16 v[8:11], v[158:161], v[190:193], v[8:11]
	v_mfma_f32_16x16x32_bf16 v[60:63], v[154:157], v[170:173], v[60:63]
	v_mfma_f32_16x16x32_bf16 v[56:59], v[162:165], v[170:173], v[56:59]
	v_mfma_f32_16x16x32_bf16 v[44:47], v[154:157], v[178:181], v[44:47]
	v_mfma_f32_16x16x32_bf16 v[40:43], v[162:165], v[178:181], v[40:43]
	v_mfma_f32_16x16x32_bf16 v[28:31], v[154:157], v[186:189], v[28:31]
	v_mfma_f32_16x16x32_bf16 v[24:27], v[162:165], v[186:189], v[24:27]
	v_mfma_f32_16x16x32_bf16 v[12:15], v[154:157], v[194:197], v[12:15]
	v_mfma_f32_16x16x32_bf16 v[8:11], v[162:165], v[194:197], v[8:11]
	s_setprio 0
	s_barrier
; #define PG8_STAGE(bufoff, gbase, voff) do { _Pragma("unroll") for (int _i = 0; _i < 2; ++_i) \
;         __builtin_amdgcn_global_load_lds((const unsigned*)((const char*)(gbase) + (voff)[_i]), (LAS unsigned*)(lds + (bufoff) + ldsw + _i * 8192), 16, 0, 0); } while (0)
; #define PG8_LDA(dst, b, h) do { _Pragma("unroll") for (int m = 0; m < 4; ++m) _Pragma("unroll") for (int k = 0; k < 2; ++k) dst[m][k] = *(const LAS bf16x8*)(lds + PG8_SA(b, h) + aoff + m * 2048 + k * 1024); } while (0)
; #define PG8_LDB(dst, b, h) do { _Pragma("unroll") for (int n = 0; n < 2; ++n) _Pragma("unroll") for (int k = 0; k < 2; ++k) dst[n][k] = *(const LAS bf16x8*)(lds + PG8_SB(b, h) + boff + n * 2048 + k * 1024); } while (0)
; #define PG8_MMA(ai, bj, At, Bt) do { __builtin_amdgcn_s_setprio(1); _Pragma("unroll") for (int m = 0; m < 4; ++m) _Pragma("unroll") for (int n = 0; n < 2; ++n) _Pragma("unroll") for (int k = 0; k < 2; ++k) \
;         acc[ai][bj][m][n] = __builtin_amdgcn_mfma_f32_16x16x32_bf16(Bt[n][k], At[m][k], acc[ai][bj][m][n], 0, 0, 0); __builtin_amdgcn_s_setprio(0); } while (0)
; #define PG8_WAIT_V(n) asm volatile("s_waitcnt vmcnt(" #n ")" ::: "memory")
; #define PG8_WAIT_L(n) asm volatile("s_waitcnt lgkmcnt(" #n ")" ::: "memory")
; #define PG8_BAR __builtin_amdgcn_s_barrier()
; #define PG8_SCHED __builtin_amdgcn_sched_barrier(0)
; template <class Epi>
; __device__ __forceinline__ void gemm_phase(LAS unsigned char* lds, const Gemm g, const StaticOrder& S, const Epi& E) {
;     ...
;             PG8_STAGE(PG8_SB(0, 1), b2 + hstepB, voffB);
;             PG8_WAIT_V(6); PG8_BAR; PG8_MMA(1, 1, At, B1); PG8_BAR;
;             PG8_LDB(B0, 1, 0); PG8_SCHED; PG8_LDA(At, 1, 0); PG8_STAGE(PG8_SA(0, 1), a2 + hstepA, voffA);
;             PG8_WAIT_L(8); PG8_BAR; PG8_WAIT_L(0); PG8_MMA(0, 0, At, B0); PG8_BAR; PG8_SCHED;
;             PG8_LDB(B1, 1, 1); PG8_STAGE(PG8_SB(1, 0), b3, voffB);
	s_add_u32 s76, s26, 0x10000
	s_addc_u32 s77, s27, 0
	s_add_i32 s65, s48, s36
	s_mov_b32 m0, s65
	s_nop 0
	global_load_lds_dwordx4 v130, s[76:77]
	s_add_i32 m0, s65, 0x2000
	s_nop 0
	global_load_lds_dwordx4 v134, s[76:77]
	s_waitcnt vmcnt(6)
	s_barrier
	s_setprio 1
	v_mfma_f32_16x16x32_bf16 v[52:55], v[198:201], v[166:169], v[52:55]
	v_mfma_f32_16x16x32_bf16 v[48:51], v[206:209], v[166:169], v[48:51]
	v_mfma_f32_16x16x32_bf16 v[36:39], v[198:201], v[174:177], v[36:39]
	v_mfma_f32_16x16x32_bf16 v[32:35], v[206:209], v[174:177], v[32:35]
	v_mfma_f32_16x16x32_bf16 v[20:23], v[198:201], v[182:185], v[20:23]
	v_mfma_f32_16x16x32_bf16 v[16:19], v[206:209], v[182:185], v[16:19]
	v_mfma_f32_16x16x32_bf16 v[4:7], v[198:201], v[190:193], v[4:7]
	v_mfma_f32_16x16x32_bf16 v[0:3], v[206:209], v[190:193], v[0:3]
	v_mfma_f32_16x16x32_bf16 v[52:55], v[202:205], v[170:173], v[52:55]
	v_mfma_f32_16x16x32_bf16 v[48:51], v[212:215], v[170:173], v[48:51]
	v_mfma_f32_16x16x32_bf16 v[36:39], v[202:205], v[178:181], v[36:39]
	v_mfma_f32_16x16x32_bf16 v[32:35], v[212:215], v[178:181], v[32:35]
	v_mfma_f32_16x16x32_bf16 v[20:23], v[202:205], v[186:189], v[20:23]
	v_mfma_f32_16x16x32_bf16 v[16:19], v[212:215], v[186:189], v[16:19]
	v_mfma_f32_16x16x32_bf16 v[4:7], v[202:205], v[194:197], v[4:7]
	v_mfma_f32_16x16x32_bf16 v[0:3], v[212:215], v[194:197], v[0:3]
	s_setprio 0
	s_add_i32 s65, 0, 0x18000
	v_add_u32_e32 v162, s65, v146
	s_barrier
	ds_read_b128 v[150:153], v162
	ds_read_b128 v[154:157], v162 offset:1024
	ds_read_b128 v[158:161], v162 offset:2048
	ds_read_b128 v[162:165], v162 offset:3072
	s_add_u32 s28, s28, 0x10000
	s_addc_u32 s29, s29, 0
	s_mov_b32 m0, s38
	ds_read_b128 v[166:169], v148 offset:32768
	ds_read_b128 v[170:173], v148 offset:33792
	ds_read_b128 v[174:177], v148 offset:34816
	ds_read_b128 v[178:181], v148 offset:35840
	ds_read_b128 v[182:185], v148 offset:36864
	ds_read_b128 v[186:189], v148 offset:37888
	ds_read_b128 v[190:193], v148 offset:38912
	ds_read_b128 v[194:197], v148 offset:39936
	global_load_lds_dwordx4 v128, s[28:29]
	s_mov_b32 m0, s39
	s_nop 0
	global_load_lds_dwordx4 v132, s[28:29]
	s_waitcnt lgkmcnt(8)
	s_barrier
	s_waitcnt lgkmcnt(0)
	s_setprio 1
	s_waitcnt lgkmcnt(0)
	v_mfma_f32_16x16x32_bf16 v[124:127], v[150:153], v[166:169], v[124:127]
	v_mfma_f32_16x16x32_bf16 v[120:123], v[158:161], v[166:169], v[120:123]
	v_mfma_f32_16x16x32_bf16 v[108:111], v[150:153], v[174:177], v[108:111]
	v_mfma_f32_16x16x32_bf16 v[104:107], v[158:161], v[174:177], v[104:107]
	v_mfma_f32_16x16x32_bf16 v[92:95], v[150:153], v[182:185], v[92:95]
	v_mfma_f32_16x16x32_bf16 v[88:91], v[158:161], v[182:185], v[88:91]
	v_mfma_f32_16x16x32_bf16 v[76:79], v[150:153], v[190:193], v[76:79]
	v_mfma_f32_16x16x32_bf16 v[72:75], v[158:161], v[190:193], v[72:75]
	v_mfma_f32_16x16x32_bf16 v[124:127], v[154:157], v[170:173], v[124:127]
	v_mfma_f32_16x16x32_bf16 v[120:123], v[162:165], v[170:173], v[120:123]
	v_mfma_f32_16x16x32_bf16 v[108:111], v[154:157], v[178:181], v[108:111]
	v_mfma_f32_16x16x32_bf16 v[104:107], v[162:165], v[178:181], v[104:107]
	v_mfma_f32_16x16x32_bf16 v[92:95], v[154:157], v[186:189], v[92:95]
	v_mfma_f32_16x16x32_bf16 v[88:91], v[162:165], v[186:189], v[88:91]
	v_mfma_f32_16x16x32_bf16 v[76:79], v[154:157], v[194:197], v[76:79]
	v_mfma_f32_16x16x32_bf16 v[72:75], v[162:165], v[194:197], v[72:75]
	s_setprio 0
	s_barrier
	s_add_i32 s28, 0, 0x1c000
	s_add_i32 s29, s65, s36
	v_add_u32_e32 v211, s28, v146
	v_lshl_add_u64 v[216:217], v[216:217], 0, s[14:15]
	s_mov_b32 m0, s29
	ds_read_b128 v[198:201], v211
	ds_read_b128 v[202:205], v211 offset:1024
	ds_read_b128 v[206:209], v211 offset:2048
	ds_read_b128 v[212:215], v211 offset:3072
	global_load_lds_dwordx4 v[216:217], off
	v_lshl_add_u64 v[216:217], v[218:219], 0, s[14:15]
	s_add_i32 m0, s29, 0x2000
	s_nop 0
	global_load_lds_dwordx4 v[216:217], off
	s_barrier
; #define PG8_STAGE(bufoff, gbase, voff) do { _Pragma("unroll") for (int _i = 0; _i < 2; ++_i) \
;         __builtin_amdgcn_global_load_lds((const unsigned*)((const char*)(gbase) + (voff)[_i]), (LAS unsigned*)(lds + (bufoff) + ldsw + _i * 8192), 16, 0, 0); } while (0)
; #define PG8_LDA(dst, b, h) do { _Pragma("unroll") for (int m = 0; m < 4; ++m) _Pragma("unroll") for (int k = 0; k < 2; ++k) dst[m][k] = *(const LAS bf16x8*)(lds + PG8_SA(b, h) + aoff + m * 2048 + k * 1024); } while (0)
; #define PG8_MMA(ai, bj, At, Bt) do { __builtin_amdgcn_s_setprio(1); _Pragma("unroll") for (int m = 0; m < 4; ++m) _Pragma("unroll") for (int n = 0; n < 2; ++n) _Pragma("unroll") for (int k = 0; k < 2; ++k) \
;         acc[ai][bj][m][n] = __builtin_amdgcn_mfma_f32_16x16x32_bf16(Bt[n][k], At[m][k], acc[ai][bj][m][n], 0, 0, 0); __builtin_amdgcn_s_setprio(0); } while (0)
; #define PG8_WAIT_V(n) asm volatile("s_waitcnt vmcnt(" #n ")" ::: "memory")
; #define PG8_WAIT_L(n) asm volatile("s_waitcnt lgkmcnt(" #n ")" ::: "memory")
; #define PG8_BAR __builtin_amdgcn_s_barrier()
; #define PG8_SCHED __builtin_amdgcn_sched_barrier(0)
; template <class Epi>
; __device__ __forceinline__ void gemm_phase(LAS unsigned char* lds, const Gemm g, const StaticOrder& S, const Epi& E) {
;     ...
;             PG8_BAR; PG8_WAIT_L(0); PG8_MMA(0, 1, At, B1); PG8_BAR;
;             PG8_LDA(At, 1, 1); PG8_STAGE(PG8_SA(1, 0), a3, voffA);
;             PG8_BAR; PG8_WAIT_L(0); PG8_MMA(1, 0, At, B0); PG8_BAR; PG8_SCHED;
;             PG8_STAGE(PG8_SB(1, 1), b3 + hstepB, voffB);
;             PG8_WAIT_V(6); PG8_BAR; PG8_MMA(1, 1, At, B1); PG8_BAR;
;         }
	s_waitcnt lgkmcnt(0)
	s_setprio 1
	s_waitcnt lgkmcnt(0)
	v_mfma_f32_16x16x32_bf16 v[116:119], v[198:201], v[166:169], v[116:119]
	v_mfma_f32_16x16x32_bf16 v[112:115], v[206:209], v[166:169], v[112:115]
	v_mfma_f32_16x16x32_bf16 v[100:103], v[198:201], v[174:177], v[100:103]
	v_mfma_f32_16x16x32_bf16 v[96:99], v[206:209], v[174:177], v[96:99]
	v_mfma_f32_16x16x32_bf16 v[84:87], v[198:201], v[182:185], v[84:87]
	v_mfma_f32_16x16x32_bf16 v[80:83], v[206:209], v[182:185], v[80:83]
	v_mfma_f32_16x16x32_bf16 v[68:71], v[198:201], v[190:193], v[68:71]
	v_mfma_f32_16x16x32_bf16 v[64:67], v[206:209], v[190:193], v[64:67]
	v_mfma_f32_16x16x32_bf16 v[116:119], v[202:205], v[170:173], v[116:119]
	v_mfma_f32_16x16x32_bf16 v[112:115], v[212:215], v[170:173], v[112:115]
	v_mfma_f32_16x16x32_bf16 v[100:103], v[202:205], v[178:181], v[100:103]
	v_mfma_f32_16x16x32_bf16 v[96:99], v[212:215], v[178:181], v[96:99]
	v_mfma_f32_16x16x32_bf16 v[84:87], v[202:205], v[186:189], v[84:87]
	v_mfma_f32_16x16x32_bf16 v[80:83], v[212:215], v[186:189], v[80:83]
	v_mfma_f32_16x16x32_bf16 v[68:71], v[202:205], v[194:197], v[68:71]
	v_mfma_f32_16x16x32_bf16 v[64:67], v[212:215], v[194:197], v[64:67]
	s_setprio 0
	s_mov_b32 m0, s43
	v_lshl_add_u64 v[216:217], v[220:221], 0, s[14:15]
	s_barrier
	ds_read_b128 v[166:169], v148 offset:49152
	ds_read_b128 v[170:173], v148 offset:50176
	ds_read_b128 v[174:177], v148 offset:51200
	ds_read_b128 v[178:181], v148 offset:52224
	ds_read_b128 v[182:185], v148 offset:53248
	ds_read_b128 v[186:189], v148 offset:54272
	ds_read_b128 v[190:193], v148 offset:55296
	ds_read_b128 v[194:197], v148 offset:56320
	global_load_lds_dwordx4 v[216:217], off
	v_lshl_add_u64 v[216:217], v[222:223], 0, s[14:15]
	s_mov_b32 m0, s44
	s_nop 0
	global_load_lds_dwordx4 v[216:217], off
	s_barrier
	s_waitcnt lgkmcnt(0)
	s_setprio 1
	s_waitcnt lgkmcnt(0)
	v_mfma_f32_16x16x32_bf16 v[60:63], v[150:153], v[166:169], v[60:63]
	v_mfma_f32_16x16x32_bf16 v[56:59], v[158:161], v[166:169], v[56:59]
	v_mfma_f32_16x16x32_bf16 v[44:47], v[150:153], v[174:177], v[44:47]
	v_mfma_f32_16x16x32_bf16 v[40:43], v[158:161], v[174:177], v[40:43]
	v_mfma_f32_16x16x32_bf16 v[28:31], v[150:153], v[182:185], v[28:31]
	v_mfma_f32_16x16x32_bf16 v[24:27], v[158:161], v[182:185], v[24:27]
	v_mfma_f32_16x16x32_bf16 v[12:15], v[150:153], v[190:193], v[12:15]
	v_mfma_f32_16x16x32_bf16 v[8:11], v[158:161], v[190:193], v[8:11]
	v_mfma_f32_16x16x32_bf16 v[60:63], v[154:157], v[170:173], v[60:63]
	v_mfma_f32_16x16x32_bf16 v[56:59], v[162:165], v[170:173], v[56:59]
	v_mfma_f32_16x16x32_bf16 v[44:47], v[154:157], v[178:181], v[44:47]
	v_mfma_f32_16x16x32_bf16 v[40:43], v[162:165], v[178:181], v[40:43]
	v_mfma_f32_16x16x32_bf16 v[28:31], v[154:157], v[186:189], v[28:31]
	v_mfma_f32_16x16x32_bf16 v[24:27], v[162:165], v[186:189], v[24:27]
	v_mfma_f32_16x16x32_bf16 v[12:15], v[154:157], v[194:197], v[12:15]
	v_mfma_f32_16x16x32_bf16 v[8:11], v[162:165], v[194:197], v[8:11]
	s_setprio 0
	s_barrier
	s_add_u32 s26, s26, 0x10080
	s_addc_u32 s27, s27, 0
	s_add_i32 s28, s28, s36
	s_mov_b32 m0, s28
	s_nop 0
	global_load_lds_dwordx4 v130, s[26:27]
	s_add_i32 m0, s28, 0x2000
	s_nop 0
	global_load_lds_dwordx4 v134, s[26:27]
	s_waitcnt vmcnt(6)
	s_barrier
	s_setprio 1
	v_mfma_f32_16x16x32_bf16 v[52:55], v[198:201], v[166:169], v[52:55]
	v_mfma_f32_16x16x32_bf16 v[48:51], v[206:209], v[166:169], v[48:51]
	v_mfma_f32_16x16x32_bf16 v[36:39], v[198:201], v[174:177], v[36:39]
	v_mfma_f32_16x16x32_bf16 v[32:35], v[206:209], v[174:177], v[32:35]
	v_mfma_f32_16x16x32_bf16 v[20:23], v[198:201], v[182:185], v[20:23]
	v_mfma_f32_16x16x32_bf16 v[16:19], v[206:209], v[182:185], v[16:19]
	v_mfma_f32_16x16x32_bf16 v[4:7], v[198:201], v[190:193], v[4:7]
	v_mfma_f32_16x16x32_bf16 v[0:3], v[206:209], v[190:193], v[0:3]
	v_mfma_f32_16x16x32_bf16 v[52:55], v[202:205], v[170:173], v[52:55]
	v_mfma_f32_16x16x32_bf16 v[48:51], v[212:215], v[170:173], v[48:51]
	v_mfma_f32_16x16x32_bf16 v[36:39], v[202:205], v[178:181], v[36:39]
	v_mfma_f32_16x16x32_bf16 v[32:35], v[212:215], v[178:181], v[32:35]
	v_mfma_f32_16x16x32_bf16 v[20:23], v[202:205], v[186:189], v[20:23]
	v_mfma_f32_16x16x32_bf16 v[16:19], v[212:215], v[186:189], v[16:19]
	v_mfma_f32_16x16x32_bf16 v[4:7], v[202:205], v[194:197], v[4:7]
	v_mfma_f32_16x16x32_bf16 v[0:3], v[212:215], v[194:197], v[0:3]
	s_setprio 0
	s_add_u32 s10, s10, 0x100
	s_addc_u32 s11, s11, 0
	s_add_u32 s62, s62, 0x100
	s_addc_u32 s63, s63, 0
	s_cmp_ge_i32 s64, s42
	s_mov_b32 s26, s64
	s_barrier
	s_cbranch_scc0 .LBB0_1566
	s_branch .LBB0_1557

; #define PG8_STAGE(bufoff, gbase, voff) do { _Pragma("unroll") for (int _i = 0; _i < 2; ++_i) \
;         __builtin_amdgcn_global_load_lds((const unsigned*)((const char*)(gbase) + (voff)[_i]), (LAS unsigned*)(lds + (bufoff) + ldsw + _i * 8192), 16, 0, 0); } while (0)
; #define PG8_LDA(dst, b, h) do { _Pragma("unroll") for (int m = 0; m < 4; ++m) _Pragma("unroll") for (int k = 0; k < 2; ++k) dst[m][k] = *(const LAS bf16x8*)(lds + PG8_SA(b, h) + aoff + m * 2048 + k * 1024); } while (0)
; #define PG8_LDB(dst, b, h) do { _Pragma("unroll") for (int n = 0; n < 2; ++n) _Pragma("unroll") for (int k = 0; k < 2; ++k) dst[n][k] = *(const LAS bf16x8*)(lds + PG8_SB(b, h) + boff + n * 2048 + k * 1024); } while (0)
; #define PG8_MMA(ai, bj, At, Bt) do { __builtin_amdgcn_s_setprio(1); _Pragma("unroll") for (int m = 0; m < 4; ++m) _Pragma("unroll") for (int n = 0; n < 2; ++n) _Pragma("unroll") for (int k = 0; k < 2; ++k) \
;         acc[ai][bj][m][n] = __builtin_amdgcn_mfma_f32_16x16x32_bf16(Bt[n][k], At[m][k], acc[ai][bj][m][n], 0, 0, 0); __builtin_amdgcn_s_setprio(0); } while (0)
; #define PG8_WAIT_L(n) asm volatile("s_waitcnt lgkmcnt(" #n ")" ::: "memory")
; #define PG8_BAR __builtin_amdgcn_s_barrier()
; #define PG8_SCHED __builtin_amdgcn_sched_barrier(0)
; template <class Epi>
; __device__ __forceinline__ void gemm_phase(LAS unsigned char* lds, const Gemm g, const StaticOrder& S, const Epi& E) {
;     ...
;         for (int t = 0; t < nt; t += 2) {
;             const bool last = (t == nt - 2);
;             const char* a1 = cA + (size_t)(t + 1) * kstep;
;             const char* a2 = last ? nA : cA + (size_t)(t + 2) * kstep; const char* b2 = last ? nB : cB + (size_t)(t + 2) * kstep;
;             const char* a3 = a2 + kstep; const char* b3 = b2 + kstep;
;             PG8_LDB(B0, 0, 0); PG8_SCHED; PG8_LDA(At, 0, 0); PG8_STAGE(PG8_SA(1, 1), a1 + hstepA, voffA);
;             PG8_WAIT_L(8); PG8_BAR; PG8_WAIT_L(0); PG8_MMA(0, 0, At, B0); PG8_BAR; PG8_SCHED;
;             PG8_LDB(B1, 0, 1); PG8_STAGE(PG8_SB(0, 0), b2, voffB);
;             PG8_BAR; PG8_WAIT_L(0); PG8_MMA(0, 1, At, B1); PG8_BAR;
;             PG8_LDA(At, 0, 1); PG8_STAGE(PG8_SA(0, 0), a2, voffA);
;             PG8_BAR; PG8_WAIT_L(0); PG8_MMA(1, 0, At, B0); PG8_BAR; PG8_SCHED;
.LBB0_1653:
	ds_read_b128 v[128:131], v214
	ds_read_b128 v[132:135], v214 offset:1024
	ds_read_b128 v[136:139], v214 offset:2048
	ds_read_b128 v[140:143], v214 offset:3072
	s_add_i32 s65, s26, 2
	s_add_u32 s10, s24, 0x100
	s_addc_u32 s11, s25, 0
	s_cmp_eq_u32 s43, s26
	s_cselect_b32 s26, s12, s63
	s_cselect_b32 s29, s23, s11
	s_cselect_b32 s28, s22, s10
	s_cselect_b32 s27, s13, s64
	v_lshl_add_u64 v[192:193], s[24:25], 0, v[184:185]
	s_add_i32 m0, s34, 0xc000
	ds_read_b128 v[144:147], v215
	ds_read_b128 v[148:151], v215 offset:1024
	ds_read_b128 v[152:155], v215 offset:2048
	ds_read_b128 v[156:159], v215 offset:3072
	ds_read_b128 v[160:163], v215 offset:4096
	ds_read_b128 v[164:167], v215 offset:5120
	ds_read_b128 v[168:171], v215 offset:6144
	ds_read_b128 v[172:175], v215 offset:7168
	global_load_lds_dwordx4 v[192:193], off
	v_lshl_add_u64 v[192:193], s[24:25], 0, v[186:187]
	s_add_i32 m0, s34, 0xe000
	s_nop 0
	global_load_lds_dwordx4 v[192:193], off
	s_waitcnt lgkmcnt(8)
	s_barrier
	s_waitcnt lgkmcnt(0)
	s_setprio 1
	s_waitcnt lgkmcnt(0)
	v_mfma_f32_16x16x32_bf16 v[116:119], v[128:131], v[144:147], v[116:119]
	v_mfma_f32_16x16x32_bf16 v[124:127], v[136:139], v[144:147], v[124:127]
	v_mfma_f32_16x16x32_bf16 v[108:111], v[128:131], v[152:155], v[108:111]
	v_mfma_f32_16x16x32_bf16 v[104:107], v[136:139], v[152:155], v[104:107]
	v_mfma_f32_16x16x32_bf16 v[92:95], v[128:131], v[160:163], v[92:95]
	v_mfma_f32_16x16x32_bf16 v[88:91], v[136:139], v[160:163], v[88:91]
	v_mfma_f32_16x16x32_bf16 v[76:79], v[128:131], v[168:171], v[76:79]
	v_mfma_f32_16x16x32_bf16 v[72:75], v[136:139], v[168:171], v[72:75]
	v_mfma_f32_16x16x32_bf16 v[116:119], v[132:135], v[148:151], v[116:119]
	v_mfma_f32_16x16x32_bf16 v[124:127], v[140:143], v[148:151], v[124:127]
	v_mfma_f32_16x16x32_bf16 v[108:111], v[132:135], v[156:159], v[108:111]
	v_mfma_f32_16x16x32_bf16 v[104:107], v[140:143], v[156:159], v[104:107]
	v_mfma_f32_16x16x32_bf16 v[92:95], v[132:135], v[164:167], v[92:95]
	v_mfma_f32_16x16x32_bf16 v[88:91], v[140:143], v[164:167], v[88:91]
	v_mfma_f32_16x16x32_bf16 v[76:79], v[132:135], v[172:175], v[76:79]
	v_mfma_f32_16x16x32_bf16 v[72:75], v[140:143], v[172:175], v[72:75]
	s_setprio 0
	s_barrier
	s_add_i32 s24, s47, s31
	v_lshl_add_u64 v[208:209], s[26:27], 0, v[178:179]
	s_mov_b32 m0, s24
	ds_read_b128 v[192:195], v216
	ds_read_b128 v[196:199], v216 offset:1024
	ds_read_b128 v[200:203], v216 offset:2048
	ds_read_b128 v[204:207], v216 offset:3072
	global_load_lds_dwordx4 v[208:209], off
	v_lshl_add_u64 v[218:219], s[26:27], 0, v[182:183]
	s_add_i32 m0, s24, 0x2000
	s_nop 0
	global_load_lds_dwordx4 v[218:219], off
	s_barrier
	s_waitcnt lgkmcnt(0)
	s_setprio 1
	s_waitcnt lgkmcnt(0)
	v_mfma_f32_16x16x32_bf16 v[120:123], v[192:195], v[144:147], v[120:123]
	v_mfma_f32_16x16x32_bf16 v[112:115], v[200:203], v[144:147], v[112:115]
	v_mfma_f32_16x16x32_bf16 v[100:103], v[192:195], v[152:155], v[100:103]
	v_mfma_f32_16x16x32_bf16 v[96:99], v[200:203], v[152:155], v[96:99]
	v_mfma_f32_16x16x32_bf16 v[84:87], v[192:195], v[160:163], v[84:87]
	v_mfma_f32_16x16x32_bf16 v[80:83], v[200:203], v[160:163], v[80:83]
	v_mfma_f32_16x16x32_bf16 v[68:71], v[192:195], v[168:171], v[68:71]
	v_mfma_f32_16x16x32_bf16 v[64:67], v[200:203], v[168:171], v[64:67]
	v_mfma_f32_16x16x32_bf16 v[120:123], v[196:199], v[148:151], v[120:123]
	v_mfma_f32_16x16x32_bf16 v[112:115], v[204:207], v[148:151], v[112:115]
	v_mfma_f32_16x16x32_bf16 v[100:103], v[196:199], v[156:159], v[100:103]
	v_mfma_f32_16x16x32_bf16 v[96:99], v[204:207], v[156:159], v[96:99]
	v_mfma_f32_16x16x32_bf16 v[84:87], v[196:199], v[164:167], v[84:87]
	v_mfma_f32_16x16x32_bf16 v[80:83], v[204:207], v[164:167], v[80:83]
	v_mfma_f32_16x16x32_bf16 v[68:71], v[196:199], v[172:175], v[68:71]
	v_mfma_f32_16x16x32_bf16 v[64:67], v[204:207], v[172:175], v[64:67]
	s_setprio 0
	s_mov_b32 m0, s34
	v_lshl_add_u64 v[220:221], s[28:29], 0, v[176:177]
	s_barrier
	ds_read_b128 v[144:147], v215 offset:16384
	ds_read_b128 v[148:151], v215 offset:17408
	ds_read_b128 v[152:155], v215 offset:18432
	ds_read_b128 v[156:159], v215 offset:19456
	ds_read_b128 v[160:163], v215 offset:20480
	ds_read_b128 v[164:167], v215 offset:21504
	ds_read_b128 v[168:171], v215 offset:22528
	ds_read_b128 v[172:175], v215 offset:23552
	global_load_lds_dwordx4 v[220:221], off
	v_lshl_add_u64 v[222:223], s[28:29], 0, v[180:181]
	s_mov_b32 m0, s35
	s_nop 0
	global_load_lds_dwordx4 v[222:223], off
	s_barrier
	s_waitcnt lgkmcnt(0)
	s_setprio 1
	s_waitcnt lgkmcnt(0)
	v_mfma_f32_16x16x32_bf16 v[60:63], v[128:131], v[144:147], v[60:63]
	v_mfma_f32_16x16x32_bf16 v[56:59], v[136:139], v[144:147], v[56:59]
	v_mfma_f32_16x16x32_bf16 v[44:47], v[128:131], v[152:155], v[44:47]
	v_mfma_f32_16x16x32_bf16 v[40:43], v[136:139], v[152:155], v[40:43]
	v_mfma_f32_16x16x32_bf16 v[28:31], v[128:131], v[160:163], v[28:31]
	v_mfma_f32_16x16x32_bf16 v[24:27], v[136:139], v[160:163], v[24:27]
	v_mfma_f32_16x16x32_bf16 v[12:15], v[128:131], v[168:171], v[12:15]
	v_mfma_f32_16x16x32_bf16 v[8:11], v[136:139], v[168:171], v[8:11]
	v_mfma_f32_16x16x32_bf16 v[60:63], v[132:135], v[148:151], v[60:63]
	v_mfma_f32_16x16x32_bf16 v[56:59], v[140:143], v[148:151], v[56:59]
	v_mfma_f32_16x16x32_bf16 v[44:47], v[132:135], v[156:159], v[44:47]
	v_mfma_f32_16x16x32_bf16 v[40:43], v[140:143], v[156:159], v[40:43]
	v_mfma_f32_16x16x32_bf16 v[28:31], v[132:135], v[164:167], v[28:31]
	v_mfma_f32_16x16x32_bf16 v[24:27], v[140:143], v[164:167], v[24:27]
	v_mfma_f32_16x16x32_bf16 v[12:15], v[132:135], v[172:175], v[12:15]
	v_mfma_f32_16x16x32_bf16 v[8:11], v[140:143], v[172:175], v[8:11]
	s_setprio 0
	s_barrier
; #define PG8_STAGE(bufoff, gbase, voff) do { _Pragma("unroll") for (int _i = 0; _i < 2; ++_i) \
;         __builtin_amdgcn_global_load_lds((const unsigned*)((const char*)(gbase) + (voff)[_i]), (LAS unsigned*)(lds + (bufoff) + ldsw + _i * 8192), 16, 0, 0); } while (0)
; #define PG8_LDA(dst, b, h) do { _Pragma("unroll") for (int m = 0; m < 4; ++m) _Pragma("unroll") for (int k = 0; k < 2; ++k) dst[m][k] = *(const LAS bf16x8*)(lds + PG8_SA(b, h) + aoff + m * 2048 + k * 1024); } while (0)
; #define PG8_LDB(dst, b, h) do { _Pragma("unroll") for (int n = 0; n < 2; ++n) _Pragma("unroll") for (int k = 0; k < 2; ++k) dst[n][k] = *(const LAS bf16x8*)(lds + PG8_SB(b, h) + boff + n * 2048 + k * 1024); } while (0)
; #define PG8_MMA(ai, bj, At, Bt) do { __builtin_amdgcn_s_setprio(1); _Pragma("unroll") for (int m = 0; m < 4; ++m) _Pragma("unroll") for (int n = 0; n < 2; ++n) _Pragma("unroll") for (int k = 0; k < 2; ++k) \
;         acc[ai][bj][m][n] = __builtin_amdgcn_mfma_f32_16x16x32_bf16(Bt[n][k], At[m][k], acc[ai][bj][m][n], 0, 0, 0); __builtin_amdgcn_s_setprio(0); } while (0)
; #define PG8_WAIT_V(n) asm volatile("s_waitcnt vmcnt(" #n ")" ::: "memory")
; #define PG8_WAIT_L(n) asm volatile("s_waitcnt lgkmcnt(" #n ")" ::: "memory")
; #define PG8_BAR __builtin_amdgcn_s_barrier()
; #define PG8_SCHED __builtin_amdgcn_sched_barrier(0)
; template <class Epi>
; __device__ __forceinline__ void gemm_phase(LAS unsigned char* lds, const Gemm g, const StaticOrder& S, const Epi& E) {
;     ...
;             PG8_STAGE(PG8_SB(0, 1), b2 + hstepB, voffB);
;             PG8_WAIT_V(6); PG8_BAR; PG8_MMA(1, 1, At, B1); PG8_BAR;
;             PG8_LDB(B0, 1, 0); PG8_SCHED; PG8_LDA(At, 1, 0); PG8_STAGE(PG8_SA(0, 1), a2 + hstepA, voffA);
;             PG8_WAIT_L(8); PG8_BAR; PG8_WAIT_L(0); PG8_MMA(0, 0, At, B0); PG8_BAR; PG8_SCHED;
;             PG8_LDB(B1, 1, 1); PG8_STAGE(PG8_SB(1, 0), b3, voffB);
	s_add_u32 s24, s26, 0xb0000
	s_addc_u32 s25, s27, 0
	s_add_i32 s66, s48, s31
	s_mov_b32 m0, s66
	s_nop 0
	global_load_lds_dwordx4 v178, s[24:25]
	s_add_i32 m0, s66, 0x2000
	s_nop 0
	global_load_lds_dwordx4 v182, s[24:25]
	s_waitcnt vmcnt(6)
	s_barrier
	s_setprio 1
	v_mfma_f32_16x16x32_bf16 v[52:55], v[192:195], v[144:147], v[52:55]
	v_mfma_f32_16x16x32_bf16 v[48:51], v[200:203], v[144:147], v[48:51]
	v_mfma_f32_16x16x32_bf16 v[36:39], v[192:195], v[152:155], v[36:39]
	v_mfma_f32_16x16x32_bf16 v[32:35], v[200:203], v[152:155], v[32:35]
	v_mfma_f32_16x16x32_bf16 v[20:23], v[192:195], v[160:163], v[20:23]
	v_mfma_f32_16x16x32_bf16 v[16:19], v[200:203], v[160:163], v[16:19]
	v_mfma_f32_16x16x32_bf16 v[4:7], v[192:195], v[168:171], v[4:7]
	v_mfma_f32_16x16x32_bf16 v[0:3], v[200:203], v[168:171], v[0:3]
	v_mfma_f32_16x16x32_bf16 v[52:55], v[196:199], v[148:151], v[52:55]
	v_mfma_f32_16x16x32_bf16 v[48:51], v[204:207], v[148:151], v[48:51]
	v_mfma_f32_16x16x32_bf16 v[36:39], v[196:199], v[156:159], v[36:39]
	v_mfma_f32_16x16x32_bf16 v[32:35], v[204:207], v[156:159], v[32:35]
	v_mfma_f32_16x16x32_bf16 v[20:23], v[196:199], v[164:167], v[20:23]
	v_mfma_f32_16x16x32_bf16 v[16:19], v[204:207], v[164:167], v[16:19]
	v_mfma_f32_16x16x32_bf16 v[4:7], v[196:199], v[172:175], v[4:7]
	v_mfma_f32_16x16x32_bf16 v[0:3], v[204:207], v[172:175], v[0:3]
	s_setprio 0
	s_add_i32 s66, 0, 0x18000
	v_add_u32_e32 v140, s66, v213
	s_barrier
	ds_read_b128 v[128:131], v140
	ds_read_b128 v[132:135], v140 offset:1024
	ds_read_b128 v[136:139], v140 offset:2048
	ds_read_b128 v[140:143], v140 offset:3072
	s_add_u32 s24, s28, 0xb0000
	s_addc_u32 s25, s29, 0
	s_mov_b32 m0, s36
	ds_read_b128 v[144:147], v215 offset:32768
	ds_read_b128 v[148:151], v215 offset:33792
	ds_read_b128 v[152:155], v215 offset:34816
	ds_read_b128 v[156:159], v215 offset:35840
	ds_read_b128 v[160:163], v215 offset:36864
	ds_read_b128 v[164:167], v215 offset:37888
	ds_read_b128 v[168:171], v215 offset:38912
	ds_read_b128 v[172:175], v215 offset:39936
	global_load_lds_dwordx4 v176, s[24:25]
	s_mov_b32 m0, s37
	s_nop 0
	global_load_lds_dwordx4 v180, s[24:25]
	s_waitcnt lgkmcnt(8)
	s_barrier
	s_waitcnt lgkmcnt(0)
	s_setprio 1
	s_waitcnt lgkmcnt(0)
	v_mfma_f32_16x16x32_bf16 v[116:119], v[128:131], v[144:147], v[116:119]
	v_mfma_f32_16x16x32_bf16 v[124:127], v[136:139], v[144:147], v[124:127]
	v_mfma_f32_16x16x32_bf16 v[108:111], v[128:131], v[152:155], v[108:111]
	v_mfma_f32_16x16x32_bf16 v[104:107], v[136:139], v[152:155], v[104:107]
	v_mfma_f32_16x16x32_bf16 v[92:95], v[128:131], v[160:163], v[92:95]
	v_mfma_f32_16x16x32_bf16 v[88:91], v[136:139], v[160:163], v[88:91]
	v_mfma_f32_16x16x32_bf16 v[76:79], v[128:131], v[168:171], v[76:79]
	v_mfma_f32_16x16x32_bf16 v[72:75], v[136:139], v[168:171], v[72:75]
	v_mfma_f32_16x16x32_bf16 v[116:119], v[132:135], v[148:151], v[116:119]
	v_mfma_f32_16x16x32_bf16 v[124:127], v[140:143], v[148:151], v[124:127]
	v_mfma_f32_16x16x32_bf16 v[108:111], v[132:135], v[156:159], v[108:111]
	v_mfma_f32_16x16x32_bf16 v[104:107], v[140:143], v[156:159], v[104:107]
	v_mfma_f32_16x16x32_bf16 v[92:95], v[132:135], v[164:167], v[92:95]
	v_mfma_f32_16x16x32_bf16 v[88:91], v[140:143], v[164:167], v[88:91]
	v_mfma_f32_16x16x32_bf16 v[76:79], v[132:135], v[172:175], v[76:79]
	v_mfma_f32_16x16x32_bf16 v[72:75], v[140:143], v[172:175], v[72:75]
	s_setprio 0
	s_barrier
	s_add_i32 s28, 0, 0x1c000
	s_add_i32 s24, s66, s31
	v_add_u32_e32 v204, s28, v213
	v_lshl_add_u64 v[208:209], v[208:209], 0, s[18:19]
	s_mov_b32 m0, s24
	ds_read_b128 v[192:195], v204
	ds_read_b128 v[196:199], v204 offset:1024
	ds_read_b128 v[200:203], v204 offset:2048
	ds_read_b128 v[204:207], v204 offset:3072
	global_load_lds_dwordx4 v[208:209], off
	v_lshl_add_u64 v[208:209], v[218:219], 0, s[18:19]
	s_add_i32 m0, s24, 0x2000
	s_nop 0
	global_load_lds_dwordx4 v[208:209], off
	s_barrier
; #define PG8_STAGE(bufoff, gbase, voff) do { _Pragma("unroll") for (int _i = 0; _i < 2; ++_i) \
;         __builtin_amdgcn_global_load_lds((const unsigned*)((const char*)(gbase) + (voff)[_i]), (LAS unsigned*)(lds + (bufoff) + ldsw + _i * 8192), 16, 0, 0); } while (0)
; #define PG8_LDA(dst, b, h) do { _Pragma("unroll") for (int m = 0; m < 4; ++m) _Pragma("unroll") for (int k = 0; k < 2; ++k) dst[m][k] = *(const LAS bf16x8*)(lds + PG8_SA(b, h) + aoff + m * 2048 + k * 1024); } while (0)
; #define PG8_MMA(ai, bj, At, Bt) do { __builtin_amdgcn_s_setprio(1); _Pragma("unroll") for (int m = 0; m < 4; ++m) _Pragma("unroll") for (int n = 0; n < 2; ++n) _Pragma("unroll") for (int k = 0; k < 2; ++k) \
;         acc[ai][bj][m][n] = __builtin_amdgcn_mfma_f32_16x16x32_bf16(Bt[n][k], At[m][k], acc[ai][bj][m][n], 0, 0, 0); __builtin_amdgcn_s_setprio(0); } while (0)
; #define PG8_WAIT_V(n) asm volatile("s_waitcnt vmcnt(" #n ")" ::: "memory")
; #define PG8_WAIT_L(n) asm volatile("s_waitcnt lgkmcnt(" #n ")" ::: "memory")
; #define PG8_BAR __builtin_amdgcn_s_barrier()
; #define PG8_SCHED __builtin_amdgcn_sched_barrier(0)
; template <class Epi>
; __device__ __forceinline__ void gemm_phase(LAS unsigned char* lds, const Gemm g, const StaticOrder& S, const Epi& E) {
;     ...
;             PG8_BAR; PG8_WAIT_L(0); PG8_MMA(0, 1, At, B1); PG8_BAR;
;             PG8_LDA(At, 1, 1); PG8_STAGE(PG8_SA(1, 0), a3, voffA);
;             PG8_BAR; PG8_WAIT_L(0); PG8_MMA(1, 0, At, B0); PG8_BAR; PG8_SCHED;
;             PG8_STAGE(PG8_SB(1, 1), b3 + hstepB, voffB);
;             PG8_WAIT_V(6); PG8_BAR; PG8_MMA(1, 1, At, B1); PG8_BAR;
;         }
	s_waitcnt lgkmcnt(0)
	s_setprio 1
	s_waitcnt lgkmcnt(0)
	v_mfma_f32_16x16x32_bf16 v[120:123], v[192:195], v[144:147], v[120:123]
	v_mfma_f32_16x16x32_bf16 v[112:115], v[200:203], v[144:147], v[112:115]
	v_mfma_f32_16x16x32_bf16 v[100:103], v[192:195], v[152:155], v[100:103]
	v_mfma_f32_16x16x32_bf16 v[96:99], v[200:203], v[152:155], v[96:99]
	v_mfma_f32_16x16x32_bf16 v[84:87], v[192:195], v[160:163], v[84:87]
	v_mfma_f32_16x16x32_bf16 v[80:83], v[200:203], v[160:163], v[80:83]
	v_mfma_f32_16x16x32_bf16 v[68:71], v[192:195], v[168:171], v[68:71]
	v_mfma_f32_16x16x32_bf16 v[64:67], v[200:203], v[168:171], v[64:67]
	v_mfma_f32_16x16x32_bf16 v[120:123], v[196:199], v[148:151], v[120:123]
	v_mfma_f32_16x16x32_bf16 v[112:115], v[204:207], v[148:151], v[112:115]
	v_mfma_f32_16x16x32_bf16 v[100:103], v[196:199], v[156:159], v[100:103]
	v_mfma_f32_16x16x32_bf16 v[96:99], v[204:207], v[156:159], v[96:99]
	v_mfma_f32_16x16x32_bf16 v[84:87], v[196:199], v[164:167], v[84:87]
	v_mfma_f32_16x16x32_bf16 v[80:83], v[204:207], v[164:167], v[80:83]
	v_mfma_f32_16x16x32_bf16 v[68:71], v[196:199], v[172:175], v[68:71]
	v_mfma_f32_16x16x32_bf16 v[64:67], v[204:207], v[172:175], v[64:67]
	s_setprio 0
	s_mov_b32 m0, s41
	v_lshl_add_u64 v[208:209], v[220:221], 0, s[18:19]
	s_barrier
	ds_read_b128 v[144:147], v215 offset:49152
	ds_read_b128 v[148:151], v215 offset:50176
	ds_read_b128 v[152:155], v215 offset:51200
	ds_read_b128 v[156:159], v215 offset:52224
	ds_read_b128 v[160:163], v215 offset:53248
	ds_read_b128 v[164:167], v215 offset:54272
	ds_read_b128 v[168:171], v215 offset:55296
	ds_read_b128 v[172:175], v215 offset:56320
	global_load_lds_dwordx4 v[208:209], off
	v_lshl_add_u64 v[208:209], v[222:223], 0, s[18:19]
	s_mov_b32 m0, s42
	s_nop 0
	global_load_lds_dwordx4 v[208:209], off
	s_barrier
	s_waitcnt lgkmcnt(0)
	s_setprio 1
	s_waitcnt lgkmcnt(0)
	v_mfma_f32_16x16x32_bf16 v[60:63], v[128:131], v[144:147], v[60:63]
	v_mfma_f32_16x16x32_bf16 v[56:59], v[136:139], v[144:147], v[56:59]
	v_mfma_f32_16x16x32_bf16 v[44:47], v[128:131], v[152:155], v[44:47]
	v_mfma_f32_16x16x32_bf16 v[40:43], v[136:139], v[152:155], v[40:43]
	v_mfma_f32_16x16x32_bf16 v[28:31], v[128:131], v[160:163], v[28:31]
	v_mfma_f32_16x16x32_bf16 v[24:27], v[136:139], v[160:163], v[24:27]
	v_mfma_f32_16x16x32_bf16 v[12:15], v[128:131], v[168:171], v[12:15]
	v_mfma_f32_16x16x32_bf16 v[8:11], v[136:139], v[168:171], v[8:11]
	v_mfma_f32_16x16x32_bf16 v[60:63], v[132:135], v[148:151], v[60:63]
	v_mfma_f32_16x16x32_bf16 v[56:59], v[140:143], v[148:151], v[56:59]
	v_mfma_f32_16x16x32_bf16 v[44:47], v[132:135], v[156:159], v[44:47]
	v_mfma_f32_16x16x32_bf16 v[40:43], v[140:143], v[156:159], v[40:43]
	v_mfma_f32_16x16x32_bf16 v[28:31], v[132:135], v[164:167], v[28:31]
	v_mfma_f32_16x16x32_bf16 v[24:27], v[140:143], v[164:167], v[24:27]
	v_mfma_f32_16x16x32_bf16 v[12:15], v[132:135], v[172:175], v[12:15]
	v_mfma_f32_16x16x32_bf16 v[8:11], v[140:143], v[172:175], v[8:11]
	s_setprio 0
	s_barrier
	s_add_u32 s24, s26, 0xb0080
	s_addc_u32 s25, s27, 0
	s_add_i32 s26, s28, s31
	s_mov_b32 m0, s26
	s_nop 0
	global_load_lds_dwordx4 v178, s[24:25]
	s_add_i32 m0, s26, 0x2000
	s_nop 0
	global_load_lds_dwordx4 v182, s[24:25]
	s_waitcnt vmcnt(6)
	s_barrier
	s_setprio 1
	v_mfma_f32_16x16x32_bf16 v[52:55], v[192:195], v[144:147], v[52:55]
	v_mfma_f32_16x16x32_bf16 v[48:51], v[200:203], v[144:147], v[48:51]
	v_mfma_f32_16x16x32_bf16 v[36:39], v[192:195], v[152:155], v[36:39]
	v_mfma_f32_16x16x32_bf16 v[32:35], v[200:203], v[152:155], v[32:35]
	v_mfma_f32_16x16x32_bf16 v[20:23], v[192:195], v[160:163], v[20:23]
	v_mfma_f32_16x16x32_bf16 v[16:19], v[200:203], v[160:163], v[16:19]
	v_mfma_f32_16x16x32_bf16 v[4:7], v[192:195], v[168:171], v[4:7]
	v_mfma_f32_16x16x32_bf16 v[0:3], v[200:203], v[168:171], v[0:3]
	v_mfma_f32_16x16x32_bf16 v[52:55], v[196:199], v[148:151], v[52:55]
	v_mfma_f32_16x16x32_bf16 v[48:51], v[204:207], v[148:151], v[48:51]
	v_mfma_f32_16x16x32_bf16 v[36:39], v[196:199], v[156:159], v[36:39]
	v_mfma_f32_16x16x32_bf16 v[32:35], v[204:207], v[156:159], v[32:35]
	v_mfma_f32_16x16x32_bf16 v[20:23], v[196:199], v[164:167], v[20:23]
	v_mfma_f32_16x16x32_bf16 v[16:19], v[204:207], v[164:167], v[16:19]
	v_mfma_f32_16x16x32_bf16 v[4:7], v[196:199], v[172:175], v[4:7]
	v_mfma_f32_16x16x32_bf16 v[0:3], v[204:207], v[172:175], v[0:3]
	s_setprio 0
	s_add_u32 s63, s63, 0x100
	s_addc_u32 s64, s64, 0
	s_cmp_ge_i32 s65, s40
	s_mov_b64 s[24:25], s[10:11]
	s_mov_b32 s26, s65
	s_barrier
	s_cbranch_scc0 .LBB0_1653

; #define PG8_STAGE(bufoff, gbase, voff) do { _Pragma("unroll") for (int _i = 0; _i < 2; ++_i) \
;         __builtin_amdgcn_global_load_lds((const unsigned*)((const char*)(gbase) + (voff)[_i]), (LAS unsigned*)(lds + (bufoff) + ldsw + _i * 8192), 16, 0, 0); } while (0)
; #define PG8_LDA(dst, b, h) do { _Pragma("unroll") for (int m = 0; m < 4; ++m) _Pragma("unroll") for (int k = 0; k < 2; ++k) dst[m][k] = *(const LAS bf16x8*)(lds + PG8_SA(b, h) + aoff + m * 2048 + k * 1024); } while (0)
; #define PG8_LDB(dst, b, h) do { _Pragma("unroll") for (int n = 0; n < 2; ++n) _Pragma("unroll") for (int k = 0; k < 2; ++k) dst[n][k] = *(const LAS bf16x8*)(lds + PG8_SB(b, h) + boff + n * 2048 + k * 1024); } while (0)
; #define PG8_MMA(ai, bj, At, Bt) do { __builtin_amdgcn_s_setprio(1); _Pragma("unroll") for (int m = 0; m < 4; ++m) _Pragma("unroll") for (int n = 0; n < 2; ++n) _Pragma("unroll") for (int k = 0; k < 2; ++k) \
;         acc[ai][bj][m][n] = __builtin_amdgcn_mfma_f32_16x16x32_bf16(Bt[n][k], At[m][k], acc[ai][bj][m][n], 0, 0, 0); __builtin_amdgcn_s_setprio(0); } while (0)
; #define PG8_WAIT_L(n) asm volatile("s_waitcnt lgkmcnt(" #n ")" ::: "memory")
; #define PG8_BAR __builtin_amdgcn_s_barrier()
; #define PG8_SCHED __builtin_amdgcn_sched_barrier(0)
; template <class Epi>
; __device__ __forceinline__ void gemm_phase(LAS unsigned char* lds, const Gemm g, const StaticOrder& S, const Epi& E) {
;     ...
;         for (int t = 0; t < nt; t += 2) {
;             const bool last = (t == nt - 2);
;             const char* a1 = cA + (size_t)(t + 1) * kstep;
;             const char* a2 = last ? nA : cA + (size_t)(t + 2) * kstep; const char* b2 = last ? nB : cB + (size_t)(t + 2) * kstep;
;             const char* a3 = a2 + kstep; const char* b3 = b2 + kstep;
;             PG8_LDB(B0, 0, 0); PG8_SCHED; PG8_LDA(At, 0, 0); PG8_STAGE(PG8_SA(1, 1), a1 + hstepA, voffA);
;             PG8_WAIT_L(8); PG8_BAR; PG8_WAIT_L(0); PG8_MMA(0, 0, At, B0); PG8_BAR; PG8_SCHED;
;             PG8_LDB(B1, 0, 1); PG8_STAGE(PG8_SB(0, 0), b2, voffB);
;             PG8_BAR; PG8_WAIT_L(0); PG8_MMA(0, 1, At, B1); PG8_BAR;
;             PG8_LDA(At, 0, 1); PG8_STAGE(PG8_SA(0, 0), a2, voffA);
;             PG8_BAR; PG8_WAIT_L(0); PG8_MMA(1, 0, At, B0); PG8_BAR; PG8_SCHED;
.LBB0_1753:
	ds_read_b128 v[128:131], v193
	ds_read_b128 v[132:135], v193 offset:1024
	ds_read_b128 v[136:139], v193 offset:2048
	ds_read_b128 v[140:143], v193 offset:3072
	s_add_i32 s80, s36, 2
	s_add_u32 s37, s12, 0xfffc0080
	s_addc_u32 s38, s13, -1
	s_cmp_eq_u32 s49, s36
	s_cselect_b32 s36, s65, s78
	s_cselect_b32 s39, s23, s38
	s_cselect_b32 s38, s25, s37
	s_cselect_b32 s37, s64, s79
	s_add_i32 m0, s31, 0xc000
	ds_read_b128 v[144:147], v194
	ds_read_b128 v[148:151], v194 offset:1024
	ds_read_b128 v[152:155], v194 offset:2048
	ds_read_b128 v[156:159], v194 offset:3072
	ds_read_b128 v[176:179], v194 offset:4096
	ds_read_b128 v[180:183], v194 offset:5120
	ds_read_b128 v[184:187], v194 offset:6144
	ds_read_b128 v[198:201], v194 offset:7168
	global_load_lds_dwordx4 v168, s[12:13]
	s_add_i32 m0, s31, 0xe000
	s_nop 0
	global_load_lds_dwordx4 v170, s[12:13]
	s_waitcnt lgkmcnt(8)
	s_barrier
	s_waitcnt lgkmcnt(0)
	s_setprio 1
	s_waitcnt lgkmcnt(0)
	v_mfma_f32_16x16x32_bf16 v[124:127], v[128:131], v[144:147], v[124:127]
	v_mfma_f32_16x16x32_bf16 v[120:123], v[136:139], v[144:147], v[120:123]
	v_mfma_f32_16x16x32_bf16 v[108:111], v[128:131], v[152:155], v[108:111]
	v_mfma_f32_16x16x32_bf16 v[104:107], v[136:139], v[152:155], v[104:107]
	v_mfma_f32_16x16x32_bf16 v[92:95], v[128:131], v[176:179], v[92:95]
	v_mfma_f32_16x16x32_bf16 v[88:91], v[136:139], v[176:179], v[88:91]
	v_mfma_f32_16x16x32_bf16 v[76:79], v[128:131], v[184:187], v[76:79]
	v_mfma_f32_16x16x32_bf16 v[72:75], v[136:139], v[184:187], v[72:75]
	v_mfma_f32_16x16x32_bf16 v[124:127], v[132:135], v[148:151], v[124:127]
	v_mfma_f32_16x16x32_bf16 v[120:123], v[140:143], v[148:151], v[120:123]
	v_mfma_f32_16x16x32_bf16 v[108:111], v[132:135], v[156:159], v[108:111]
	v_mfma_f32_16x16x32_bf16 v[104:107], v[140:143], v[156:159], v[104:107]
	v_mfma_f32_16x16x32_bf16 v[92:95], v[132:135], v[180:183], v[92:95]
	v_mfma_f32_16x16x32_bf16 v[88:91], v[140:143], v[180:183], v[88:91]
	v_mfma_f32_16x16x32_bf16 v[76:79], v[132:135], v[198:201], v[76:79]
	v_mfma_f32_16x16x32_bf16 v[72:75], v[140:143], v[198:201], v[72:75]
	s_setprio 0
	s_barrier
	s_add_i32 s66, s63, s41
	v_lshl_add_u64 v[188:189], s[36:37], 0, v[162:163]
	s_mov_b32 m0, s66
	ds_read_b128 v[202:205], v195
	ds_read_b128 v[206:209], v195 offset:1024
	ds_read_b128 v[212:215], v195 offset:2048
	ds_read_b128 v[216:219], v195 offset:3072
	global_load_lds_dwordx4 v[188:189], off
	v_lshl_add_u64 v[220:221], s[36:37], 0, v[166:167]
	s_add_i32 m0, s66, 0x2000
	s_nop 0
	global_load_lds_dwordx4 v[220:221], off
	s_barrier
	s_waitcnt lgkmcnt(0)
	s_setprio 1
	s_waitcnt lgkmcnt(0)
	v_mfma_f32_16x16x32_bf16 v[116:119], v[202:205], v[144:147], v[116:119]
	v_mfma_f32_16x16x32_bf16 v[112:115], v[212:215], v[144:147], v[112:115]
	v_mfma_f32_16x16x32_bf16 v[100:103], v[202:205], v[152:155], v[100:103]
	v_mfma_f32_16x16x32_bf16 v[96:99], v[212:215], v[152:155], v[96:99]
	v_mfma_f32_16x16x32_bf16 v[84:87], v[202:205], v[176:179], v[84:87]
	v_mfma_f32_16x16x32_bf16 v[80:83], v[212:215], v[176:179], v[80:83]
	v_mfma_f32_16x16x32_bf16 v[68:71], v[202:205], v[184:187], v[68:71]
	v_mfma_f32_16x16x32_bf16 v[64:67], v[212:215], v[184:187], v[64:67]
	v_mfma_f32_16x16x32_bf16 v[116:119], v[206:209], v[148:151], v[116:119]
	v_mfma_f32_16x16x32_bf16 v[112:115], v[216:219], v[148:151], v[112:115]
	v_mfma_f32_16x16x32_bf16 v[100:103], v[206:209], v[156:159], v[100:103]
	v_mfma_f32_16x16x32_bf16 v[96:99], v[216:219], v[156:159], v[96:99]
	v_mfma_f32_16x16x32_bf16 v[84:87], v[206:209], v[180:183], v[84:87]
	v_mfma_f32_16x16x32_bf16 v[80:83], v[216:219], v[180:183], v[80:83]
	v_mfma_f32_16x16x32_bf16 v[68:71], v[206:209], v[198:201], v[68:71]
	v_mfma_f32_16x16x32_bf16 v[64:67], v[216:219], v[198:201], v[64:67]
	s_setprio 0
	s_mov_b32 m0, s31
	v_lshl_add_u64 v[222:223], s[38:39], 0, v[160:161]
	s_barrier
	ds_read_b128 v[144:147], v194 offset:16384
	ds_read_b128 v[148:151], v194 offset:17408
	ds_read_b128 v[152:155], v194 offset:18432
	ds_read_b128 v[156:159], v194 offset:19456
	ds_read_b128 v[176:179], v194 offset:20480
	ds_read_b128 v[180:183], v194 offset:21504
	ds_read_b128 v[184:187], v194 offset:22528
	ds_read_b128 v[198:201], v194 offset:23552
	global_load_lds_dwordx4 v[222:223], off
	v_lshl_add_u64 v[224:225], s[38:39], 0, v[164:165]
	s_mov_b32 m0, s35
	s_nop 0
	global_load_lds_dwordx4 v[224:225], off
	s_barrier
	s_waitcnt lgkmcnt(0)
	s_setprio 1
	s_waitcnt lgkmcnt(0)
	v_mfma_f32_16x16x32_bf16 v[60:63], v[128:131], v[144:147], v[60:63]
	v_mfma_f32_16x16x32_bf16 v[56:59], v[136:139], v[144:147], v[56:59]
	v_mfma_f32_16x16x32_bf16 v[44:47], v[128:131], v[152:155], v[44:47]
	v_mfma_f32_16x16x32_bf16 v[40:43], v[136:139], v[152:155], v[40:43]
	v_mfma_f32_16x16x32_bf16 v[28:31], v[128:131], v[176:179], v[28:31]
	v_mfma_f32_16x16x32_bf16 v[24:27], v[136:139], v[176:179], v[24:27]
	v_mfma_f32_16x16x32_bf16 v[12:15], v[128:131], v[184:187], v[12:15]
	v_mfma_f32_16x16x32_bf16 v[8:11], v[136:139], v[184:187], v[8:11]
	v_mfma_f32_16x16x32_bf16 v[60:63], v[132:135], v[148:151], v[60:63]
	v_mfma_f32_16x16x32_bf16 v[56:59], v[140:143], v[148:151], v[56:59]
	v_mfma_f32_16x16x32_bf16 v[44:47], v[132:135], v[156:159], v[44:47]
	v_mfma_f32_16x16x32_bf16 v[40:43], v[140:143], v[156:159], v[40:43]
	v_mfma_f32_16x16x32_bf16 v[28:31], v[132:135], v[180:183], v[28:31]
	v_mfma_f32_16x16x32_bf16 v[24:27], v[140:143], v[180:183], v[24:27]
	v_mfma_f32_16x16x32_bf16 v[12:15], v[132:135], v[198:201], v[12:15]
	v_mfma_f32_16x16x32_bf16 v[8:11], v[140:143], v[198:201], v[8:11]
	s_setprio 0
	s_barrier
; #define PG8_STAGE(bufoff, gbase, voff) do { _Pragma("unroll") for (int _i = 0; _i < 2; ++_i) \
;         __builtin_amdgcn_global_load_lds((const unsigned*)((const char*)(gbase) + (voff)[_i]), (LAS unsigned*)(lds + (bufoff) + ldsw + _i * 8192), 16, 0, 0); } while (0)
; #define PG8_LDA(dst, b, h) do { _Pragma("unroll") for (int m = 0; m < 4; ++m) _Pragma("unroll") for (int k = 0; k < 2; ++k) dst[m][k] = *(const LAS bf16x8*)(lds + PG8_SA(b, h) + aoff + m * 2048 + k * 1024); } while (0)
; #define PG8_LDB(dst, b, h) do { _Pragma("unroll") for (int n = 0; n < 2; ++n) _Pragma("unroll") for (int k = 0; k < 2; ++k) dst[n][k] = *(const LAS bf16x8*)(lds + PG8_SB(b, h) + boff + n * 2048 + k * 1024); } while (0)
; #define PG8_MMA(ai, bj, At, Bt) do { __builtin_amdgcn_s_setprio(1); _Pragma("unroll") for (int m = 0; m < 4; ++m) _Pragma("unroll") for (int n = 0; n < 2; ++n) _Pragma("unroll") for (int k = 0; k < 2; ++k) \
;         acc[ai][bj][m][n] = __builtin_amdgcn_mfma_f32_16x16x32_bf16(Bt[n][k], At[m][k], acc[ai][bj][m][n], 0, 0, 0); __builtin_amdgcn_s_setprio(0); } while (0)
; #define PG8_WAIT_V(n) asm volatile("s_waitcnt vmcnt(" #n ")" ::: "memory")
; #define PG8_WAIT_L(n) asm volatile("s_waitcnt lgkmcnt(" #n ")" ::: "memory")
; #define PG8_BAR __builtin_amdgcn_s_barrier()
; #define PG8_SCHED __builtin_amdgcn_sched_barrier(0)
; template <class Epi>
; __device__ __forceinline__ void gemm_phase(LAS unsigned char* lds, const Gemm g, const StaticOrder& S, const Epi& E) {
;     ...
;             PG8_STAGE(PG8_SB(0, 1), b2 + hstepB, voffB);
;             PG8_WAIT_V(6); PG8_BAR; PG8_MMA(1, 1, At, B1); PG8_BAR;
;             PG8_LDB(B0, 1, 0); PG8_SCHED; PG8_LDA(At, 1, 0); PG8_STAGE(PG8_SA(0, 1), a2 + hstepA, voffA);
;             PG8_WAIT_L(8); PG8_BAR; PG8_WAIT_L(0); PG8_MMA(0, 0, At, B0); PG8_BAR; PG8_SCHED;
;             PG8_LDB(B1, 1, 1); PG8_STAGE(PG8_SB(1, 0), b3, voffB);
	s_add_u32 s82, s36, 0x40000
	s_addc_u32 s83, s37, 0
	s_add_i32 s66, s76, s41
	s_mov_b32 m0, s66
	s_nop 0
	global_load_lds_dwordx4 v162, s[82:83]
	s_add_i32 m0, s66, 0x2000
	s_nop 0
	global_load_lds_dwordx4 v166, s[82:83]
	s_waitcnt vmcnt(6)
	s_barrier
	s_setprio 1
	v_mfma_f32_16x16x32_bf16 v[52:55], v[202:205], v[144:147], v[52:55]
	v_mfma_f32_16x16x32_bf16 v[48:51], v[212:215], v[144:147], v[48:51]
	v_mfma_f32_16x16x32_bf16 v[36:39], v[202:205], v[152:155], v[36:39]
	v_mfma_f32_16x16x32_bf16 v[32:35], v[212:215], v[152:155], v[32:35]
	v_mfma_f32_16x16x32_bf16 v[20:23], v[202:205], v[176:179], v[20:23]
	v_mfma_f32_16x16x32_bf16 v[16:19], v[212:215], v[176:179], v[16:19]
	v_mfma_f32_16x16x32_bf16 v[4:7], v[202:205], v[184:187], v[4:7]
	v_mfma_f32_16x16x32_bf16 v[0:3], v[212:215], v[184:187], v[0:3]
	v_mfma_f32_16x16x32_bf16 v[52:55], v[206:209], v[148:151], v[52:55]
	v_mfma_f32_16x16x32_bf16 v[48:51], v[216:219], v[148:151], v[48:51]
	v_mfma_f32_16x16x32_bf16 v[36:39], v[206:209], v[156:159], v[36:39]
	v_mfma_f32_16x16x32_bf16 v[32:35], v[216:219], v[156:159], v[32:35]
	v_mfma_f32_16x16x32_bf16 v[20:23], v[206:209], v[180:183], v[20:23]
	v_mfma_f32_16x16x32_bf16 v[16:19], v[216:219], v[180:183], v[16:19]
	v_mfma_f32_16x16x32_bf16 v[4:7], v[206:209], v[198:201], v[4:7]
	v_mfma_f32_16x16x32_bf16 v[0:3], v[216:219], v[198:201], v[0:3]
	s_setprio 0
	s_add_i32 s66, 0, 0x18000
	v_add_u32_e32 v140, s66, v192
	s_barrier
	ds_read_b128 v[128:131], v140
	ds_read_b128 v[132:135], v140 offset:1024
	ds_read_b128 v[136:139], v140 offset:2048
	ds_read_b128 v[140:143], v140 offset:3072
	s_add_u32 s38, s38, 0x40000
	s_addc_u32 s39, s39, 0
	s_mov_b32 m0, s42
	ds_read_b128 v[144:147], v194 offset:32768
	ds_read_b128 v[148:151], v194 offset:33792
	ds_read_b128 v[152:155], v194 offset:34816
	ds_read_b128 v[156:159], v194 offset:35840
	ds_read_b128 v[176:179], v194 offset:36864
	ds_read_b128 v[180:183], v194 offset:37888
	ds_read_b128 v[184:187], v194 offset:38912
	ds_read_b128 v[198:201], v194 offset:39936
	global_load_lds_dwordx4 v160, s[38:39]
	s_mov_b32 m0, s43
	s_nop 0
	global_load_lds_dwordx4 v164, s[38:39]
	s_waitcnt lgkmcnt(8)
	s_barrier
	s_waitcnt lgkmcnt(0)
	s_setprio 1
	s_waitcnt lgkmcnt(0)
	v_mfma_f32_16x16x32_bf16 v[124:127], v[128:131], v[144:147], v[124:127]
	v_mfma_f32_16x16x32_bf16 v[120:123], v[136:139], v[144:147], v[120:123]
	v_mfma_f32_16x16x32_bf16 v[108:111], v[128:131], v[152:155], v[108:111]
	v_mfma_f32_16x16x32_bf16 v[104:107], v[136:139], v[152:155], v[104:107]
	v_mfma_f32_16x16x32_bf16 v[92:95], v[128:131], v[176:179], v[92:95]
	v_mfma_f32_16x16x32_bf16 v[88:91], v[136:139], v[176:179], v[88:91]
	v_mfma_f32_16x16x32_bf16 v[76:79], v[128:131], v[184:187], v[76:79]
	v_mfma_f32_16x16x32_bf16 v[72:75], v[136:139], v[184:187], v[72:75]
	v_mfma_f32_16x16x32_bf16 v[124:127], v[132:135], v[148:151], v[124:127]
	v_mfma_f32_16x16x32_bf16 v[120:123], v[140:143], v[148:151], v[120:123]
	v_mfma_f32_16x16x32_bf16 v[108:111], v[132:135], v[156:159], v[108:111]
	v_mfma_f32_16x16x32_bf16 v[104:107], v[140:143], v[156:159], v[104:107]
	v_mfma_f32_16x16x32_bf16 v[92:95], v[132:135], v[180:183], v[92:95]
	v_mfma_f32_16x16x32_bf16 v[88:91], v[140:143], v[180:183], v[88:91]
	v_mfma_f32_16x16x32_bf16 v[76:79], v[132:135], v[198:201], v[76:79]
	v_mfma_f32_16x16x32_bf16 v[72:75], v[140:143], v[198:201], v[72:75]
	s_setprio 0
	s_barrier
	s_add_i32 s38, 0, 0x1c000
	s_add_i32 s39, s66, s41
	v_add_u32_e32 v211, s38, v192
	v_lshl_add_u64 v[188:189], v[188:189], 0, s[20:21]
	s_mov_b32 m0, s39
	ds_read_b128 v[202:205], v211
	ds_read_b128 v[206:209], v211 offset:1024
	ds_read_b128 v[212:215], v211 offset:2048
	ds_read_b128 v[216:219], v211 offset:3072
	global_load_lds_dwordx4 v[188:189], off
	v_lshl_add_u64 v[188:189], v[220:221], 0, s[20:21]
	s_add_i32 m0, s39, 0x2000
	s_nop 0
	global_load_lds_dwordx4 v[188:189], off
	s_barrier
; #define PG8_STAGE(bufoff, gbase, voff) do { _Pragma("unroll") for (int _i = 0; _i < 2; ++_i) \
;         __builtin_amdgcn_global_load_lds((const unsigned*)((const char*)(gbase) + (voff)[_i]), (LAS unsigned*)(lds + (bufoff) + ldsw + _i * 8192), 16, 0, 0); } while (0)
; #define PG8_LDA(dst, b, h) do { _Pragma("unroll") for (int m = 0; m < 4; ++m) _Pragma("unroll") for (int k = 0; k < 2; ++k) dst[m][k] = *(const LAS bf16x8*)(lds + PG8_SA(b, h) + aoff + m * 2048 + k * 1024); } while (0)
; #define PG8_MMA(ai, bj, At, Bt) do { __builtin_amdgcn_s_setprio(1); _Pragma("unroll") for (int m = 0; m < 4; ++m) _Pragma("unroll") for (int n = 0; n < 2; ++n) _Pragma("unroll") for (int k = 0; k < 2; ++k) \
;         acc[ai][bj][m][n] = __builtin_amdgcn_mfma_f32_16x16x32_bf16(Bt[n][k], At[m][k], acc[ai][bj][m][n], 0, 0, 0); __builtin_amdgcn_s_setprio(0); } while (0)
; #define PG8_WAIT_V(n) asm volatile("s_waitcnt vmcnt(" #n ")" ::: "memory")
; #define PG8_WAIT_L(n) asm volatile("s_waitcnt lgkmcnt(" #n ")" ::: "memory")
; #define PG8_BAR __builtin_amdgcn_s_barrier()
; #define PG8_SCHED __builtin_amdgcn_sched_barrier(0)
; template <class Epi>
; __device__ __forceinline__ void gemm_phase(LAS unsigned char* lds, const Gemm g, const StaticOrder& S, const Epi& E) {
;     ...
;             PG8_BAR; PG8_WAIT_L(0); PG8_MMA(0, 1, At, B1); PG8_BAR;
;             PG8_LDA(At, 1, 1); PG8_STAGE(PG8_SA(1, 0), a3, voffA);
;             PG8_BAR; PG8_WAIT_L(0); PG8_MMA(1, 0, At, B0); PG8_BAR; PG8_SCHED;
;             PG8_STAGE(PG8_SB(1, 1), b3 + hstepB, voffB);
;             PG8_WAIT_V(6); PG8_BAR; PG8_MMA(1, 1, At, B1); PG8_BAR;
;         }
	s_waitcnt lgkmcnt(0)
	s_setprio 1
	s_waitcnt lgkmcnt(0)
	v_mfma_f32_16x16x32_bf16 v[116:119], v[202:205], v[144:147], v[116:119]
	v_mfma_f32_16x16x32_bf16 v[112:115], v[212:215], v[144:147], v[112:115]
	v_mfma_f32_16x16x32_bf16 v[100:103], v[202:205], v[152:155], v[100:103]
	v_mfma_f32_16x16x32_bf16 v[96:99], v[212:215], v[152:155], v[96:99]
	v_mfma_f32_16x16x32_bf16 v[84:87], v[202:205], v[176:179], v[84:87]
	v_mfma_f32_16x16x32_bf16 v[80:83], v[212:215], v[176:179], v[80:83]
	v_mfma_f32_16x16x32_bf16 v[68:71], v[202:205], v[184:187], v[68:71]
	v_mfma_f32_16x16x32_bf16 v[64:67], v[212:215], v[184:187], v[64:67]
	v_mfma_f32_16x16x32_bf16 v[116:119], v[206:209], v[148:151], v[116:119]
	v_mfma_f32_16x16x32_bf16 v[112:115], v[216:219], v[148:151], v[112:115]
	v_mfma_f32_16x16x32_bf16 v[100:103], v[206:209], v[156:159], v[100:103]
	v_mfma_f32_16x16x32_bf16 v[96:99], v[216:219], v[156:159], v[96:99]
	v_mfma_f32_16x16x32_bf16 v[84:87], v[206:209], v[180:183], v[84:87]
	v_mfma_f32_16x16x32_bf16 v[80:83], v[216:219], v[180:183], v[80:83]
	v_mfma_f32_16x16x32_bf16 v[68:71], v[206:209], v[198:201], v[68:71]
	v_mfma_f32_16x16x32_bf16 v[64:67], v[216:219], v[198:201], v[64:67]
	s_setprio 0
	s_mov_b32 m0, s47
	v_lshl_add_u64 v[188:189], v[222:223], 0, s[20:21]
	s_barrier
	ds_read_b128 v[144:147], v194 offset:49152
	ds_read_b128 v[148:151], v194 offset:50176
	ds_read_b128 v[152:155], v194 offset:51200
	ds_read_b128 v[156:159], v194 offset:52224
	ds_read_b128 v[176:179], v194 offset:53248
	ds_read_b128 v[180:183], v194 offset:54272
	ds_read_b128 v[184:187], v194 offset:55296
	ds_read_b128 v[198:201], v194 offset:56320
	global_load_lds_dwordx4 v[188:189], off
	v_lshl_add_u64 v[188:189], v[224:225], 0, s[20:21]
	s_mov_b32 m0, s48
	s_nop 0
	global_load_lds_dwordx4 v[188:189], off
	s_barrier
	s_waitcnt lgkmcnt(0)
	s_setprio 1
	s_waitcnt lgkmcnt(0)
	v_mfma_f32_16x16x32_bf16 v[60:63], v[128:131], v[144:147], v[60:63]
	v_mfma_f32_16x16x32_bf16 v[56:59], v[136:139], v[144:147], v[56:59]
	v_mfma_f32_16x16x32_bf16 v[44:47], v[128:131], v[152:155], v[44:47]
	v_mfma_f32_16x16x32_bf16 v[40:43], v[136:139], v[152:155], v[40:43]
	v_mfma_f32_16x16x32_bf16 v[28:31], v[128:131], v[176:179], v[28:31]
	v_mfma_f32_16x16x32_bf16 v[24:27], v[136:139], v[176:179], v[24:27]
	v_mfma_f32_16x16x32_bf16 v[12:15], v[128:131], v[184:187], v[12:15]
	v_mfma_f32_16x16x32_bf16 v[8:11], v[136:139], v[184:187], v[8:11]
	v_mfma_f32_16x16x32_bf16 v[60:63], v[132:135], v[148:151], v[60:63]
	v_mfma_f32_16x16x32_bf16 v[56:59], v[140:143], v[148:151], v[56:59]
	v_mfma_f32_16x16x32_bf16 v[44:47], v[132:135], v[156:159], v[44:47]
	v_mfma_f32_16x16x32_bf16 v[40:43], v[140:143], v[156:159], v[40:43]
	v_mfma_f32_16x16x32_bf16 v[28:31], v[132:135], v[180:183], v[28:31]
	v_mfma_f32_16x16x32_bf16 v[24:27], v[140:143], v[180:183], v[24:27]
	v_mfma_f32_16x16x32_bf16 v[12:15], v[132:135], v[198:201], v[12:15]
	v_mfma_f32_16x16x32_bf16 v[8:11], v[140:143], v[198:201], v[8:11]
	s_setprio 0
	s_barrier
	s_add_u32 s36, s36, 0x40080
	s_addc_u32 s37, s37, 0
	s_add_i32 s38, s38, s41
	s_mov_b32 m0, s38
	s_nop 0
	global_load_lds_dwordx4 v162, s[36:37]
	s_add_i32 m0, s38, 0x2000
	s_nop 0
	global_load_lds_dwordx4 v166, s[36:37]
	s_waitcnt vmcnt(6)
	s_barrier
	s_setprio 1
	v_mfma_f32_16x16x32_bf16 v[52:55], v[202:205], v[144:147], v[52:55]
	v_mfma_f32_16x16x32_bf16 v[48:51], v[212:215], v[144:147], v[48:51]
	v_mfma_f32_16x16x32_bf16 v[36:39], v[202:205], v[152:155], v[36:39]
	v_mfma_f32_16x16x32_bf16 v[32:35], v[212:215], v[152:155], v[32:35]
	v_mfma_f32_16x16x32_bf16 v[20:23], v[202:205], v[176:179], v[20:23]
	v_mfma_f32_16x16x32_bf16 v[16:19], v[212:215], v[176:179], v[16:19]
	v_mfma_f32_16x16x32_bf16 v[4:7], v[202:205], v[184:187], v[4:7]
	v_mfma_f32_16x16x32_bf16 v[0:3], v[212:215], v[184:187], v[0:3]
	v_mfma_f32_16x16x32_bf16 v[52:55], v[206:209], v[148:151], v[52:55]
	v_mfma_f32_16x16x32_bf16 v[48:51], v[216:219], v[148:151], v[48:51]
	v_mfma_f32_16x16x32_bf16 v[36:39], v[206:209], v[156:159], v[36:39]
	v_mfma_f32_16x16x32_bf16 v[32:35], v[216:219], v[156:159], v[32:35]
	v_mfma_f32_16x16x32_bf16 v[20:23], v[206:209], v[180:183], v[20:23]
	v_mfma_f32_16x16x32_bf16 v[16:19], v[216:219], v[180:183], v[16:19]
	v_mfma_f32_16x16x32_bf16 v[4:7], v[206:209], v[198:201], v[4:7]
	v_mfma_f32_16x16x32_bf16 v[0:3], v[216:219], v[198:201], v[0:3]
	s_setprio 0
	s_add_u32 s12, s12, 0x100
	s_addc_u32 s13, s13, 0
	s_add_u32 s78, s78, 0x100
	s_addc_u32 s79, s79, 0
	s_cmp_ge_i32 s80, s46
	s_mov_b32 s36, s80
	s_barrier
	s_cbranch_scc0 .LBB0_1753

; #define PG8_STAGE(bufoff, gbase, voff) do { _Pragma("unroll") for (int _i = 0; _i < 2; ++_i) \
;         __builtin_amdgcn_global_load_lds((const unsigned*)((const char*)(gbase) + (voff)[_i]), (LAS unsigned*)(lds + (bufoff) + ldsw + _i * 8192), 16, 0, 0); } while (0)
; #define PG8_LDA(dst, b, h) do { _Pragma("unroll") for (int m = 0; m < 4; ++m) _Pragma("unroll") for (int k = 0; k < 2; ++k) dst[m][k] = *(const LAS bf16x8*)(lds + PG8_SA(b, h) + aoff + m * 2048 + k * 1024); } while (0)
; #define PG8_LDB(dst, b, h) do { _Pragma("unroll") for (int n = 0; n < 2; ++n) _Pragma("unroll") for (int k = 0; k < 2; ++k) dst[n][k] = *(const LAS bf16x8*)(lds + PG8_SB(b, h) + boff + n * 2048 + k * 1024); } while (0)
; #define PG8_MMA(ai, bj, At, Bt) do { __builtin_amdgcn_s_setprio(1); _Pragma("unroll") for (int m = 0; m < 4; ++m) _Pragma("unroll") for (int n = 0; n < 2; ++n) _Pragma("unroll") for (int k = 0; k < 2; ++k) \
;         acc[ai][bj][m][n] = __builtin_amdgcn_mfma_f32_16x16x32_bf16(Bt[n][k], At[m][k], acc[ai][bj][m][n], 0, 0, 0); __builtin_amdgcn_s_setprio(0); } while (0)
; #define PG8_WAIT_L(n) asm volatile("s_waitcnt lgkmcnt(" #n ")" ::: "memory")
; #define PG8_BAR __builtin_amdgcn_s_barrier()
; #define PG8_SCHED __builtin_amdgcn_sched_barrier(0)
; template <class Epi>
; __device__ __forceinline__ void gemm_phase(LAS unsigned char* lds, const Gemm g, const StaticOrder& S, const Epi& E) {
;     ...
;         for (int t = 0; t < nt; t += 2) {
;             const bool last = (t == nt - 2);
;             const char* a1 = cA + (size_t)(t + 1) * kstep;
;             const char* a2 = last ? nA : cA + (size_t)(t + 2) * kstep; const char* b2 = last ? nB : cB + (size_t)(t + 2) * kstep;
;             const char* a3 = a2 + kstep; const char* b3 = b2 + kstep;
;             PG8_LDB(B0, 0, 0); PG8_SCHED; PG8_LDA(At, 0, 0); PG8_STAGE(PG8_SA(1, 1), a1 + hstepA, voffA);
;             PG8_WAIT_L(8); PG8_BAR; PG8_WAIT_L(0); PG8_MMA(0, 0, At, B0); PG8_BAR; PG8_SCHED;
;             PG8_LDB(B1, 0, 1); PG8_STAGE(PG8_SB(0, 0), b2, voffB);
;             PG8_BAR; PG8_WAIT_L(0); PG8_MMA(0, 1, At, B1); PG8_BAR;
;             PG8_LDA(At, 0, 1); PG8_STAGE(PG8_SA(0, 0), a2, voffA);
;             PG8_BAR; PG8_WAIT_L(0); PG8_MMA(1, 0, At, B0); PG8_BAR; PG8_SCHED;
.LBB0_2296:
	ds_read_b128 v[128:131], v214
	ds_read_b128 v[132:135], v214 offset:1024
	ds_read_b128 v[136:139], v214 offset:2048
	ds_read_b128 v[140:143], v214 offset:3072
	s_add_i32 s77, s34, 2
	s_add_u32 s35, s12, 0xfffc0080
	s_addc_u32 s36, s13, -1
	s_cmp_eq_u32 s47, s34
	s_cselect_b32 s34, s64, s65
	s_cselect_b32 s37, s21, s36
	s_cselect_b32 s36, s23, s35
	s_cselect_b32 s35, s63, s76
	s_add_i32 m0, s29, 0xc000
	ds_read_b128 v[144:147], v215
	ds_read_b128 v[148:151], v215 offset:1024
	ds_read_b128 v[152:155], v215 offset:2048
	ds_read_b128 v[156:159], v215 offset:3072
	ds_read_b128 v[160:163], v215 offset:4096
	ds_read_b128 v[164:167], v215 offset:5120
	ds_read_b128 v[168:171], v215 offset:6144
	ds_read_b128 v[172:175], v215 offset:7168
	global_load_lds_dwordx4 v184, s[12:13]
	s_add_i32 m0, s29, 0xe000
	s_nop 0
	global_load_lds_dwordx4 v186, s[12:13]
	s_waitcnt lgkmcnt(8)
	s_barrier
	s_waitcnt lgkmcnt(0)
	s_setprio 1
	s_waitcnt lgkmcnt(0)
	v_mfma_f32_16x16x32_bf16 v[124:127], v[128:131], v[144:147], v[124:127]
	v_mfma_f32_16x16x32_bf16 v[120:123], v[136:139], v[144:147], v[120:123]
	v_mfma_f32_16x16x32_bf16 v[108:111], v[128:131], v[152:155], v[108:111]
	v_mfma_f32_16x16x32_bf16 v[104:107], v[136:139], v[152:155], v[104:107]
	v_mfma_f32_16x16x32_bf16 v[92:95], v[128:131], v[160:163], v[92:95]
	v_mfma_f32_16x16x32_bf16 v[88:91], v[136:139], v[160:163], v[88:91]
	v_mfma_f32_16x16x32_bf16 v[76:79], v[128:131], v[168:171], v[76:79]
	v_mfma_f32_16x16x32_bf16 v[72:75], v[136:139], v[168:171], v[72:75]
	v_mfma_f32_16x16x32_bf16 v[124:127], v[132:135], v[148:151], v[124:127]
	v_mfma_f32_16x16x32_bf16 v[120:123], v[140:143], v[148:151], v[120:123]
	v_mfma_f32_16x16x32_bf16 v[108:111], v[132:135], v[156:159], v[108:111]
	v_mfma_f32_16x16x32_bf16 v[104:107], v[140:143], v[156:159], v[104:107]
	v_mfma_f32_16x16x32_bf16 v[92:95], v[132:135], v[164:167], v[92:95]
	v_mfma_f32_16x16x32_bf16 v[88:91], v[140:143], v[164:167], v[88:91]
	v_mfma_f32_16x16x32_bf16 v[76:79], v[132:135], v[172:175], v[76:79]
	v_mfma_f32_16x16x32_bf16 v[72:75], v[140:143], v[172:175], v[72:75]
	s_setprio 0
	s_barrier
	s_add_i32 s66, s61, s39
	v_lshl_add_u64 v[208:209], s[34:35], 0, v[178:179]
	s_mov_b32 m0, s66
	ds_read_b128 v[192:195], v216
	ds_read_b128 v[196:199], v216 offset:1024
	ds_read_b128 v[200:203], v216 offset:2048
	ds_read_b128 v[204:207], v216 offset:3072
	global_load_lds_dwordx4 v[208:209], off
	v_lshl_add_u64 v[218:219], s[34:35], 0, v[182:183]
	s_add_i32 m0, s66, 0x2000
	s_nop 0
	global_load_lds_dwordx4 v[218:219], off
	s_barrier
	s_waitcnt lgkmcnt(0)
	s_setprio 1
	s_waitcnt lgkmcnt(0)
	v_mfma_f32_16x16x32_bf16 v[116:119], v[192:195], v[144:147], v[116:119]
	v_mfma_f32_16x16x32_bf16 v[112:115], v[200:203], v[144:147], v[112:115]
	v_mfma_f32_16x16x32_bf16 v[100:103], v[192:195], v[152:155], v[100:103]
	v_mfma_f32_16x16x32_bf16 v[96:99], v[200:203], v[152:155], v[96:99]
	v_mfma_f32_16x16x32_bf16 v[84:87], v[192:195], v[160:163], v[84:87]
	v_mfma_f32_16x16x32_bf16 v[80:83], v[200:203], v[160:163], v[80:83]
	v_mfma_f32_16x16x32_bf16 v[68:71], v[192:195], v[168:171], v[68:71]
	v_mfma_f32_16x16x32_bf16 v[64:67], v[200:203], v[168:171], v[64:67]
	v_mfma_f32_16x16x32_bf16 v[116:119], v[196:199], v[148:151], v[116:119]
	v_mfma_f32_16x16x32_bf16 v[112:115], v[204:207], v[148:151], v[112:115]
	v_mfma_f32_16x16x32_bf16 v[100:103], v[196:199], v[156:159], v[100:103]
	v_mfma_f32_16x16x32_bf16 v[96:99], v[204:207], v[156:159], v[96:99]
	v_mfma_f32_16x16x32_bf16 v[84:87], v[196:199], v[164:167], v[84:87]
	v_mfma_f32_16x16x32_bf16 v[80:83], v[204:207], v[164:167], v[80:83]
	v_mfma_f32_16x16x32_bf16 v[68:71], v[196:199], v[172:175], v[68:71]
	v_mfma_f32_16x16x32_bf16 v[64:67], v[204:207], v[172:175], v[64:67]
	s_setprio 0
	s_mov_b32 m0, s29
	v_lshl_add_u64 v[220:221], s[36:37], 0, v[176:177]
	s_barrier
	ds_read_b128 v[144:147], v215 offset:16384
	ds_read_b128 v[148:151], v215 offset:17408
	ds_read_b128 v[152:155], v215 offset:18432
	ds_read_b128 v[156:159], v215 offset:19456
	ds_read_b128 v[160:163], v215 offset:20480
	ds_read_b128 v[164:167], v215 offset:21504
	ds_read_b128 v[168:171], v215 offset:22528
	ds_read_b128 v[172:175], v215 offset:23552
	global_load_lds_dwordx4 v[220:221], off
	v_lshl_add_u64 v[222:223], s[36:37], 0, v[180:181]
	s_mov_b32 m0, s31
	s_nop 0
	global_load_lds_dwordx4 v[222:223], off
	s_barrier
	s_waitcnt lgkmcnt(0)
	s_setprio 1
	s_waitcnt lgkmcnt(0)
	v_mfma_f32_16x16x32_bf16 v[60:63], v[128:131], v[144:147], v[60:63]
	v_mfma_f32_16x16x32_bf16 v[56:59], v[136:139], v[144:147], v[56:59]
	v_mfma_f32_16x16x32_bf16 v[44:47], v[128:131], v[152:155], v[44:47]
	v_mfma_f32_16x16x32_bf16 v[40:43], v[136:139], v[152:155], v[40:43]
	v_mfma_f32_16x16x32_bf16 v[28:31], v[128:131], v[160:163], v[28:31]
	v_mfma_f32_16x16x32_bf16 v[24:27], v[136:139], v[160:163], v[24:27]
	v_mfma_f32_16x16x32_bf16 v[12:15], v[128:131], v[168:171], v[12:15]
	v_mfma_f32_16x16x32_bf16 v[8:11], v[136:139], v[168:171], v[8:11]
	v_mfma_f32_16x16x32_bf16 v[60:63], v[132:135], v[148:151], v[60:63]
	v_mfma_f32_16x16x32_bf16 v[56:59], v[140:143], v[148:151], v[56:59]
	v_mfma_f32_16x16x32_bf16 v[44:47], v[132:135], v[156:159], v[44:47]
	v_mfma_f32_16x16x32_bf16 v[40:43], v[140:143], v[156:159], v[40:43]
	v_mfma_f32_16x16x32_bf16 v[28:31], v[132:135], v[164:167], v[28:31]
	v_mfma_f32_16x16x32_bf16 v[24:27], v[140:143], v[164:167], v[24:27]
	v_mfma_f32_16x16x32_bf16 v[12:15], v[132:135], v[172:175], v[12:15]
	v_mfma_f32_16x16x32_bf16 v[8:11], v[140:143], v[172:175], v[8:11]
	s_setprio 0
	s_barrier
; #define PG8_STAGE(bufoff, gbase, voff) do { _Pragma("unroll") for (int _i = 0; _i < 2; ++_i) \
;         __builtin_amdgcn_global_load_lds((const unsigned*)((const char*)(gbase) + (voff)[_i]), (LAS unsigned*)(lds + (bufoff) + ldsw + _i * 8192), 16, 0, 0); } while (0)
; #define PG8_LDA(dst, b, h) do { _Pragma("unroll") for (int m = 0; m < 4; ++m) _Pragma("unroll") for (int k = 0; k < 2; ++k) dst[m][k] = *(const LAS bf16x8*)(lds + PG8_SA(b, h) + aoff + m * 2048 + k * 1024); } while (0)
; #define PG8_LDB(dst, b, h) do { _Pragma("unroll") for (int n = 0; n < 2; ++n) _Pragma("unroll") for (int k = 0; k < 2; ++k) dst[n][k] = *(const LAS bf16x8*)(lds + PG8_SB(b, h) + boff + n * 2048 + k * 1024); } while (0)
; #define PG8_MMA(ai, bj, At, Bt) do { __builtin_amdgcn_s_setprio(1); _Pragma("unroll") for (int m = 0; m < 4; ++m) _Pragma("unroll") for (int n = 0; n < 2; ++n) _Pragma("unroll") for (int k = 0; k < 2; ++k) \
;         acc[ai][bj][m][n] = __builtin_amdgcn_mfma_f32_16x16x32_bf16(Bt[n][k], At[m][k], acc[ai][bj][m][n], 0, 0, 0); __builtin_amdgcn_s_setprio(0); } while (0)
; #define PG8_WAIT_V(n) asm volatile("s_waitcnt vmcnt(" #n ")" ::: "memory")
; #define PG8_WAIT_L(n) asm volatile("s_waitcnt lgkmcnt(" #n ")" ::: "memory")
; #define PG8_BAR __builtin_amdgcn_s_barrier()
; #define PG8_SCHED __builtin_amdgcn_sched_barrier(0)
; template <class Epi>
; __device__ __forceinline__ void gemm_phase(LAS unsigned char* lds, const Gemm g, const StaticOrder& S, const Epi& E) {
;     ...
;             PG8_STAGE(PG8_SB(0, 1), b2 + hstepB, voffB);
;             PG8_WAIT_V(6); PG8_BAR; PG8_MMA(1, 1, At, B1); PG8_BAR;
;             PG8_LDB(B0, 1, 0); PG8_SCHED; PG8_LDA(At, 1, 0); PG8_STAGE(PG8_SA(0, 1), a2 + hstepA, voffA);
;             PG8_WAIT_L(8); PG8_BAR; PG8_WAIT_L(0); PG8_MMA(0, 0, At, B0); PG8_BAR; PG8_SCHED;
;             PG8_LDB(B1, 1, 1); PG8_STAGE(PG8_SB(1, 0), b3, voffB);
	s_add_u32 s66, s34, 0x40000
	s_addc_u32 s67, s35, 0
	s_add_i32 s78, s62, s39
	s_mov_b32 m0, s78
	s_nop 0
	global_load_lds_dwordx4 v178, s[66:67]
	s_add_i32 m0, s78, 0x2000
	s_nop 0
	global_load_lds_dwordx4 v182, s[66:67]
	s_waitcnt vmcnt(6)
	s_barrier
	s_setprio 1
	v_mfma_f32_16x16x32_bf16 v[52:55], v[192:195], v[144:147], v[52:55]
	v_mfma_f32_16x16x32_bf16 v[48:51], v[200:203], v[144:147], v[48:51]
	v_mfma_f32_16x16x32_bf16 v[36:39], v[192:195], v[152:155], v[36:39]
	v_mfma_f32_16x16x32_bf16 v[32:35], v[200:203], v[152:155], v[32:35]
	v_mfma_f32_16x16x32_bf16 v[20:23], v[192:195], v[160:163], v[20:23]
	v_mfma_f32_16x16x32_bf16 v[16:19], v[200:203], v[160:163], v[16:19]
	v_mfma_f32_16x16x32_bf16 v[4:7], v[192:195], v[168:171], v[4:7]
	v_mfma_f32_16x16x32_bf16 v[0:3], v[200:203], v[168:171], v[0:3]
	v_mfma_f32_16x16x32_bf16 v[52:55], v[196:199], v[148:151], v[52:55]
	v_mfma_f32_16x16x32_bf16 v[48:51], v[204:207], v[148:151], v[48:51]
	v_mfma_f32_16x16x32_bf16 v[36:39], v[196:199], v[156:159], v[36:39]
	v_mfma_f32_16x16x32_bf16 v[32:35], v[204:207], v[156:159], v[32:35]
	v_mfma_f32_16x16x32_bf16 v[20:23], v[196:199], v[164:167], v[20:23]
	v_mfma_f32_16x16x32_bf16 v[16:19], v[204:207], v[164:167], v[16:19]
	v_mfma_f32_16x16x32_bf16 v[4:7], v[196:199], v[172:175], v[4:7]
	v_mfma_f32_16x16x32_bf16 v[0:3], v[204:207], v[172:175], v[0:3]
	s_setprio 0
	s_add_i32 s66, 0, 0x18000
	v_add_u32_e32 v140, s66, v213
	s_barrier
	ds_read_b128 v[128:131], v140
	ds_read_b128 v[132:135], v140 offset:1024
	ds_read_b128 v[136:139], v140 offset:2048
	ds_read_b128 v[140:143], v140 offset:3072
	s_add_u32 s36, s36, 0x40000
	s_addc_u32 s37, s37, 0
	s_mov_b32 m0, s40
	ds_read_b128 v[144:147], v215 offset:32768
	ds_read_b128 v[148:151], v215 offset:33792
	ds_read_b128 v[152:155], v215 offset:34816
	ds_read_b128 v[156:159], v215 offset:35840
	ds_read_b128 v[160:163], v215 offset:36864
	ds_read_b128 v[164:167], v215 offset:37888
	ds_read_b128 v[168:171], v215 offset:38912
	ds_read_b128 v[172:175], v215 offset:39936
	global_load_lds_dwordx4 v176, s[36:37]
	s_mov_b32 m0, s41
	s_nop 0
	global_load_lds_dwordx4 v180, s[36:37]
	s_waitcnt lgkmcnt(8)
	s_barrier
	s_waitcnt lgkmcnt(0)
	s_setprio 1
	s_waitcnt lgkmcnt(0)
	v_mfma_f32_16x16x32_bf16 v[124:127], v[128:131], v[144:147], v[124:127]
	v_mfma_f32_16x16x32_bf16 v[120:123], v[136:139], v[144:147], v[120:123]
	v_mfma_f32_16x16x32_bf16 v[108:111], v[128:131], v[152:155], v[108:111]
	v_mfma_f32_16x16x32_bf16 v[104:107], v[136:139], v[152:155], v[104:107]
	v_mfma_f32_16x16x32_bf16 v[92:95], v[128:131], v[160:163], v[92:95]
	v_mfma_f32_16x16x32_bf16 v[88:91], v[136:139], v[160:163], v[88:91]
	v_mfma_f32_16x16x32_bf16 v[76:79], v[128:131], v[168:171], v[76:79]
	v_mfma_f32_16x16x32_bf16 v[72:75], v[136:139], v[168:171], v[72:75]
	v_mfma_f32_16x16x32_bf16 v[124:127], v[132:135], v[148:151], v[124:127]
	v_mfma_f32_16x16x32_bf16 v[120:123], v[140:143], v[148:151], v[120:123]
	v_mfma_f32_16x16x32_bf16 v[108:111], v[132:135], v[156:159], v[108:111]
	v_mfma_f32_16x16x32_bf16 v[104:107], v[140:143], v[156:159], v[104:107]
	v_mfma_f32_16x16x32_bf16 v[92:95], v[132:135], v[164:167], v[92:95]
	v_mfma_f32_16x16x32_bf16 v[88:91], v[140:143], v[164:167], v[88:91]
	v_mfma_f32_16x16x32_bf16 v[76:79], v[132:135], v[172:175], v[76:79]
	v_mfma_f32_16x16x32_bf16 v[72:75], v[140:143], v[172:175], v[72:75]
	s_setprio 0
	s_barrier
	s_add_i32 s36, 0, 0x1c000
	s_add_i32 s37, s66, s39
	v_add_u32_e32 v204, s36, v213
	v_lshl_add_u64 v[208:209], v[208:209], 0, s[18:19]
	s_mov_b32 m0, s37
	ds_read_b128 v[192:195], v204
	ds_read_b128 v[196:199], v204 offset:1024
	ds_read_b128 v[200:203], v204 offset:2048
	ds_read_b128 v[204:207], v204 offset:3072
	global_load_lds_dwordx4 v[208:209], off
	v_lshl_add_u64 v[208:209], v[218:219], 0, s[18:19]
	s_add_i32 m0, s37, 0x2000
	s_nop 0
	global_load_lds_dwordx4 v[208:209], off
	s_barrier
; #define PG8_STAGE(bufoff, gbase, voff) do { _Pragma("unroll") for (int _i = 0; _i < 2; ++_i) \
;         __builtin_amdgcn_global_load_lds((const unsigned*)((const char*)(gbase) + (voff)[_i]), (LAS unsigned*)(lds + (bufoff) + ldsw + _i * 8192), 16, 0, 0); } while (0)
; #define PG8_LDA(dst, b, h) do { _Pragma("unroll") for (int m = 0; m < 4; ++m) _Pragma("unroll") for (int k = 0; k < 2; ++k) dst[m][k] = *(const LAS bf16x8*)(lds + PG8_SA(b, h) + aoff + m * 2048 + k * 1024); } while (0)
; #define PG8_MMA(ai, bj, At, Bt) do { __builtin_amdgcn_s_setprio(1); _Pragma("unroll") for (int m = 0; m < 4; ++m) _Pragma("unroll") for (int n = 0; n < 2; ++n) _Pragma("unroll") for (int k = 0; k < 2; ++k) \
;         acc[ai][bj][m][n] = __builtin_amdgcn_mfma_f32_16x16x32_bf16(Bt[n][k], At[m][k], acc[ai][bj][m][n], 0, 0, 0); __builtin_amdgcn_s_setprio(0); } while (0)
; #define PG8_WAIT_V(n) asm volatile("s_waitcnt vmcnt(" #n ")" ::: "memory")
; #define PG8_WAIT_L(n) asm volatile("s_waitcnt lgkmcnt(" #n ")" ::: "memory")
; #define PG8_BAR __builtin_amdgcn_s_barrier()
; #define PG8_SCHED __builtin_amdgcn_sched_barrier(0)
; template <class Epi>
; __device__ __forceinline__ void gemm_phase(LAS unsigned char* lds, const Gemm g, const StaticOrder& S, const Epi& E) {
;     ...
;             PG8_BAR; PG8_WAIT_L(0); PG8_MMA(0, 1, At, B1); PG8_BAR;
;             PG8_LDA(At, 1, 1); PG8_STAGE(PG8_SA(1, 0), a3, voffA);
;             PG8_BAR; PG8_WAIT_L(0); PG8_MMA(1, 0, At, B0); PG8_BAR; PG8_SCHED;
;             PG8_STAGE(PG8_SB(1, 1), b3 + hstepB, voffB);
;             PG8_WAIT_V(6); PG8_BAR; PG8_MMA(1, 1, At, B1); PG8_BAR;
;         }
	s_waitcnt lgkmcnt(0)
	s_setprio 1
	s_waitcnt lgkmcnt(0)
	v_mfma_f32_16x16x32_bf16 v[116:119], v[192:195], v[144:147], v[116:119]
	v_mfma_f32_16x16x32_bf16 v[112:115], v[200:203], v[144:147], v[112:115]
	v_mfma_f32_16x16x32_bf16 v[100:103], v[192:195], v[152:155], v[100:103]
	v_mfma_f32_16x16x32_bf16 v[96:99], v[200:203], v[152:155], v[96:99]
	v_mfma_f32_16x16x32_bf16 v[84:87], v[192:195], v[160:163], v[84:87]
	v_mfma_f32_16x16x32_bf16 v[80:83], v[200:203], v[160:163], v[80:83]
	v_mfma_f32_16x16x32_bf16 v[68:71], v[192:195], v[168:171], v[68:71]
	v_mfma_f32_16x16x32_bf16 v[64:67], v[200:203], v[168:171], v[64:67]
	v_mfma_f32_16x16x32_bf16 v[116:119], v[196:199], v[148:151], v[116:119]
	v_mfma_f32_16x16x32_bf16 v[112:115], v[204:207], v[148:151], v[112:115]
	v_mfma_f32_16x16x32_bf16 v[100:103], v[196:199], v[156:159], v[100:103]
	v_mfma_f32_16x16x32_bf16 v[96:99], v[204:207], v[156:159], v[96:99]
	v_mfma_f32_16x16x32_bf16 v[84:87], v[196:199], v[164:167], v[84:87]
	v_mfma_f32_16x16x32_bf16 v[80:83], v[204:207], v[164:167], v[80:83]
	v_mfma_f32_16x16x32_bf16 v[68:71], v[196:199], v[172:175], v[68:71]
	v_mfma_f32_16x16x32_bf16 v[64:67], v[204:207], v[172:175], v[64:67]
	s_setprio 0
	s_mov_b32 m0, s45
	v_lshl_add_u64 v[208:209], v[220:221], 0, s[18:19]
	s_barrier
	ds_read_b128 v[144:147], v215 offset:49152
	ds_read_b128 v[148:151], v215 offset:50176
	ds_read_b128 v[152:155], v215 offset:51200
	ds_read_b128 v[156:159], v215 offset:52224
	ds_read_b128 v[160:163], v215 offset:53248
	ds_read_b128 v[164:167], v215 offset:54272
	ds_read_b128 v[168:171], v215 offset:55296
	ds_read_b128 v[172:175], v215 offset:56320
	global_load_lds_dwordx4 v[208:209], off
	v_lshl_add_u64 v[208:209], v[222:223], 0, s[18:19]
	s_mov_b32 m0, s46
	s_nop 0
	global_load_lds_dwordx4 v[208:209], off
	s_barrier
	s_waitcnt lgkmcnt(0)
	s_setprio 1
	s_waitcnt lgkmcnt(0)
	v_mfma_f32_16x16x32_bf16 v[60:63], v[128:131], v[144:147], v[60:63]
	v_mfma_f32_16x16x32_bf16 v[56:59], v[136:139], v[144:147], v[56:59]
	v_mfma_f32_16x16x32_bf16 v[44:47], v[128:131], v[152:155], v[44:47]
	v_mfma_f32_16x16x32_bf16 v[40:43], v[136:139], v[152:155], v[40:43]
	v_mfma_f32_16x16x32_bf16 v[28:31], v[128:131], v[160:163], v[28:31]
	v_mfma_f32_16x16x32_bf16 v[24:27], v[136:139], v[160:163], v[24:27]
	v_mfma_f32_16x16x32_bf16 v[12:15], v[128:131], v[168:171], v[12:15]
	v_mfma_f32_16x16x32_bf16 v[8:11], v[136:139], v[168:171], v[8:11]
	v_mfma_f32_16x16x32_bf16 v[60:63], v[132:135], v[148:151], v[60:63]
	v_mfma_f32_16x16x32_bf16 v[56:59], v[140:143], v[148:151], v[56:59]
	v_mfma_f32_16x16x32_bf16 v[44:47], v[132:135], v[156:159], v[44:47]
	v_mfma_f32_16x16x32_bf16 v[40:43], v[140:143], v[156:159], v[40:43]
	v_mfma_f32_16x16x32_bf16 v[28:31], v[132:135], v[164:167], v[28:31]
	v_mfma_f32_16x16x32_bf16 v[24:27], v[140:143], v[164:167], v[24:27]
	v_mfma_f32_16x16x32_bf16 v[12:15], v[132:135], v[172:175], v[12:15]
	v_mfma_f32_16x16x32_bf16 v[8:11], v[140:143], v[172:175], v[8:11]
	s_setprio 0
	s_barrier
	s_add_u32 s34, s34, 0x40080
	s_addc_u32 s35, s35, 0
	s_add_i32 s36, s36, s39
	s_mov_b32 m0, s36
	s_nop 0
	global_load_lds_dwordx4 v178, s[34:35]
	s_add_i32 m0, s36, 0x2000
	s_nop 0
	global_load_lds_dwordx4 v182, s[34:35]
	s_waitcnt vmcnt(6)
	s_barrier
	s_setprio 1
	v_mfma_f32_16x16x32_bf16 v[52:55], v[192:195], v[144:147], v[52:55]
	v_mfma_f32_16x16x32_bf16 v[48:51], v[200:203], v[144:147], v[48:51]
	v_mfma_f32_16x16x32_bf16 v[36:39], v[192:195], v[152:155], v[36:39]
	v_mfma_f32_16x16x32_bf16 v[32:35], v[200:203], v[152:155], v[32:35]
	v_mfma_f32_16x16x32_bf16 v[20:23], v[192:195], v[160:163], v[20:23]
	v_mfma_f32_16x16x32_bf16 v[16:19], v[200:203], v[160:163], v[16:19]
	v_mfma_f32_16x16x32_bf16 v[4:7], v[192:195], v[168:171], v[4:7]
	v_mfma_f32_16x16x32_bf16 v[0:3], v[200:203], v[168:171], v[0:3]
	v_mfma_f32_16x16x32_bf16 v[52:55], v[196:199], v[148:151], v[52:55]
	v_mfma_f32_16x16x32_bf16 v[48:51], v[204:207], v[148:151], v[48:51]
	v_mfma_f32_16x16x32_bf16 v[36:39], v[196:199], v[156:159], v[36:39]
	v_mfma_f32_16x16x32_bf16 v[32:35], v[204:207], v[156:159], v[32:35]
	v_mfma_f32_16x16x32_bf16 v[20:23], v[196:199], v[164:167], v[20:23]
	v_mfma_f32_16x16x32_bf16 v[16:19], v[204:207], v[164:167], v[16:19]
	v_mfma_f32_16x16x32_bf16 v[4:7], v[196:199], v[172:175], v[4:7]
	v_mfma_f32_16x16x32_bf16 v[0:3], v[204:207], v[172:175], v[0:3]
	s_setprio 0
	s_add_u32 s12, s12, 0x100
	s_addc_u32 s13, s13, 0
	s_add_u32 s65, s65, 0x100
	s_addc_u32 s76, s76, 0
	s_cmp_ge_i32 s77, s44
	s_mov_b32 s34, s77
	s_barrier
	s_cbranch_scc0 .LBB0_2296

; #define PG8_STAGE(bufoff, gbase, voff) do { _Pragma("unroll") for (int _i = 0; _i < 2; ++_i) \
;         __builtin_amdgcn_global_load_lds((const unsigned*)((const char*)(gbase) + (voff)[_i]), (LAS unsigned*)(lds + (bufoff) + ldsw + _i * 8192), 16, 0, 0); } while (0)
; #define PG8_LDA(dst, b, h) do { _Pragma("unroll") for (int m = 0; m < 4; ++m) _Pragma("unroll") for (int k = 0; k < 2; ++k) dst[m][k] = *(const LAS bf16x8*)(lds + PG8_SA(b, h) + aoff + m * 2048 + k * 1024); } while (0)
; #define PG8_LDB(dst, b, h) do { _Pragma("unroll") for (int n = 0; n < 2; ++n) _Pragma("unroll") for (int k = 0; k < 2; ++k) dst[n][k] = *(const LAS bf16x8*)(lds + PG8_SB(b, h) + boff + n * 2048 + k * 1024); } while (0)
; #define PG8_MMA(ai, bj, At, Bt) do { __builtin_amdgcn_s_setprio(1); _Pragma("unroll") for (int m = 0; m < 4; ++m) _Pragma("unroll") for (int n = 0; n < 2; ++n) _Pragma("unroll") for (int k = 0; k < 2; ++k) \
;         acc[ai][bj][m][n] = __builtin_amdgcn_mfma_f32_16x16x32_bf16(Bt[n][k], At[m][k], acc[ai][bj][m][n], 0, 0, 0); __builtin_amdgcn_s_setprio(0); } while (0)
; #define PG8_WAIT_L(n) asm volatile("s_waitcnt lgkmcnt(" #n ")" ::: "memory")
; #define PG8_BAR __builtin_amdgcn_s_barrier()
; #define PG8_SCHED __builtin_amdgcn_sched_barrier(0)
; template <class Epi>
; __device__ __forceinline__ void gemm_phase(LAS unsigned char* lds, const Gemm g, const StaticOrder& S, const Epi& E) {
;     ...
;             PG8_LDB(B0, 0, 0); PG8_SCHED; PG8_LDA(At, 0, 0); PG8_STAGE(PG8_SA(1, 1), a1 + hstepA, voffA);
;             PG8_WAIT_L(8); PG8_BAR; PG8_WAIT_L(0); PG8_MMA(0, 0, At, B0); PG8_BAR; PG8_SCHED;
;             PG8_LDB(B1, 0, 1); PG8_STAGE(PG8_SB(0, 0), b2, voffB);
;             PG8_BAR; PG8_WAIT_L(0); PG8_MMA(0, 1, At, B1); PG8_BAR;
;             PG8_LDA(At, 0, 1); PG8_STAGE(PG8_SA(0, 0), a2, voffA);
;             PG8_BAR; PG8_WAIT_L(0); PG8_MMA(1, 0, At, B0); PG8_BAR; PG8_SCHED;
;             PG8_STAGE(PG8_SB(0, 1), b2 + hstepB, voffB);
.Lgu38947_skip:
	s_add_i32 m0, s37, 0xc000
	ds_read_b128 v[168:171], v152
	ds_read_b128 v[172:175], v152 offset:1024
	ds_read_b128 v[176:179], v152 offset:2048
	ds_read_b128 v[180:183], v152 offset:3072
	ds_read_b128 v[184:187], v152 offset:4096
	ds_read_b128 v[188:191], v152 offset:5120
	ds_read_b128 v[192:195], v152 offset:6144
	ds_read_b128 v[196:199], v152 offset:7168
	global_load_lds_dwordx4 v136, s[8:9]
	s_add_i32 m0, s37, 0xe000
	s_nop 0
	global_load_lds_dwordx4 v138, s[8:9]
	s_waitcnt lgkmcnt(8)
	s_barrier
	s_waitcnt lgkmcnt(0)
	s_setprio 1
	s_waitcnt lgkmcnt(0)
	v_mfma_f32_16x16x32_bf16 v[116:119], v[144:147], v[168:171], v[116:119]
	v_mfma_f32_16x16x32_bf16 v[112:115], v[160:163], v[168:171], v[112:115]
	v_mfma_f32_16x16x32_bf16 v[104:107], v[144:147], v[176:179], v[104:107]
	v_mfma_f32_16x16x32_bf16 v[96:99], v[160:163], v[176:179], v[96:99]
	v_mfma_f32_16x16x32_bf16 v[88:91], v[144:147], v[184:187], v[88:91]
	v_mfma_f32_16x16x32_bf16 v[80:83], v[160:163], v[184:187], v[80:83]
	v_mfma_f32_16x16x32_bf16 v[72:75], v[144:147], v[192:195], v[72:75]
	v_mfma_f32_16x16x32_bf16 v[64:67], v[160:163], v[192:195], v[64:67]
	v_mfma_f32_16x16x32_bf16 v[116:119], v[156:159], v[172:175], v[116:119]
	v_mfma_f32_16x16x32_bf16 v[112:115], v[164:167], v[172:175], v[112:115]
	v_mfma_f32_16x16x32_bf16 v[104:107], v[156:159], v[180:183], v[104:107]
	v_mfma_f32_16x16x32_bf16 v[96:99], v[164:167], v[180:183], v[96:99]
	v_mfma_f32_16x16x32_bf16 v[88:91], v[156:159], v[188:191], v[88:91]
	v_mfma_f32_16x16x32_bf16 v[80:83], v[164:167], v[188:191], v[80:83]
	v_mfma_f32_16x16x32_bf16 v[72:75], v[156:159], v[196:199], v[72:75]
	v_mfma_f32_16x16x32_bf16 v[64:67], v[164:167], v[196:199], v[64:67]
	s_setprio 0
	s_barrier
	s_add_i32 s66, s49, s36
	v_lshl_add_u64 v[208:209], s[26:27], 0, v[130:131]
	s_mov_b32 m0, s66
	ds_read_b128 v[200:203], v153
	ds_read_b128 v[204:207], v153 offset:1024
	ds_read_b128 v[212:215], v153 offset:2048
	ds_read_b128 v[216:219], v153 offset:3072
	global_load_lds_dwordx4 v[208:209], off
	v_lshl_add_u64 v[220:221], s[26:27], 0, v[134:135]
	s_add_i32 m0, s66, 0x2000
	s_nop 0
	global_load_lds_dwordx4 v[220:221], off
	s_barrier
	s_waitcnt lgkmcnt(0)
	s_setprio 1
	s_waitcnt lgkmcnt(0)
	v_mfma_f32_16x16x32_bf16 v[124:127], v[200:203], v[168:171], v[124:127]
	v_mfma_f32_16x16x32_bf16 v[120:123], v[212:215], v[168:171], v[120:123]
	v_mfma_f32_16x16x32_bf16 v[108:111], v[200:203], v[176:179], v[108:111]
	v_mfma_f32_16x16x32_bf16 v[100:103], v[212:215], v[176:179], v[100:103]
	v_mfma_f32_16x16x32_bf16 v[92:95], v[200:203], v[184:187], v[92:95]
	v_mfma_f32_16x16x32_bf16 v[84:87], v[212:215], v[184:187], v[84:87]
	v_mfma_f32_16x16x32_bf16 v[76:79], v[200:203], v[192:195], v[76:79]
	v_mfma_f32_16x16x32_bf16 v[68:71], v[212:215], v[192:195], v[68:71]
	v_mfma_f32_16x16x32_bf16 v[124:127], v[204:207], v[172:175], v[124:127]
	v_mfma_f32_16x16x32_bf16 v[120:123], v[216:219], v[172:175], v[120:123]
	v_mfma_f32_16x16x32_bf16 v[108:111], v[204:207], v[180:183], v[108:111]
	v_mfma_f32_16x16x32_bf16 v[100:103], v[216:219], v[180:183], v[100:103]
	v_mfma_f32_16x16x32_bf16 v[92:95], v[204:207], v[188:191], v[92:95]
	v_mfma_f32_16x16x32_bf16 v[84:87], v[216:219], v[188:191], v[84:87]
	v_mfma_f32_16x16x32_bf16 v[76:79], v[204:207], v[196:199], v[76:79]
	v_mfma_f32_16x16x32_bf16 v[68:71], v[216:219], v[196:199], v[68:71]
	s_setprio 0
	s_mov_b32 m0, s37
	v_lshl_add_u64 v[222:223], s[28:29], 0, v[128:129]
	s_barrier
	ds_read_b128 v[168:171], v152 offset:16384
	ds_read_b128 v[172:175], v152 offset:17408
	ds_read_b128 v[176:179], v152 offset:18432
	ds_read_b128 v[180:183], v152 offset:19456
	ds_read_b128 v[184:187], v152 offset:20480
	ds_read_b128 v[188:191], v152 offset:21504
	ds_read_b128 v[192:195], v152 offset:22528
	ds_read_b128 v[196:199], v152 offset:23552
	global_load_lds_dwordx4 v[222:223], off
	v_lshl_add_u64 v[224:225], s[28:29], 0, v[132:133]
	s_mov_b32 m0, s38
	s_nop 0
	global_load_lds_dwordx4 v[224:225], off
	s_barrier
	s_waitcnt lgkmcnt(0)
	s_setprio 1
	s_waitcnt lgkmcnt(0)
	v_mfma_f32_16x16x32_bf16 v[56:59], v[144:147], v[168:171], v[56:59]
	v_mfma_f32_16x16x32_bf16 v[48:51], v[160:163], v[168:171], v[48:51]
	v_mfma_f32_16x16x32_bf16 v[40:43], v[144:147], v[176:179], v[40:43]
	v_mfma_f32_16x16x32_bf16 v[32:35], v[160:163], v[176:179], v[32:35]
	v_mfma_f32_16x16x32_bf16 v[24:27], v[144:147], v[184:187], v[24:27]
	v_mfma_f32_16x16x32_bf16 v[16:19], v[160:163], v[184:187], v[16:19]
	v_mfma_f32_16x16x32_bf16 v[8:11], v[144:147], v[192:195], v[8:11]
	v_mfma_f32_16x16x32_bf16 v[4:7], v[160:163], v[192:195], v[4:7]
	v_mfma_f32_16x16x32_bf16 v[56:59], v[156:159], v[172:175], v[56:59]
	v_mfma_f32_16x16x32_bf16 v[48:51], v[164:167], v[172:175], v[48:51]
	v_mfma_f32_16x16x32_bf16 v[40:43], v[156:159], v[180:183], v[40:43]
	v_mfma_f32_16x16x32_bf16 v[32:35], v[164:167], v[180:183], v[32:35]
	v_mfma_f32_16x16x32_bf16 v[24:27], v[156:159], v[188:191], v[24:27]
	v_mfma_f32_16x16x32_bf16 v[16:19], v[164:167], v[188:191], v[16:19]
	v_mfma_f32_16x16x32_bf16 v[8:11], v[156:159], v[196:199], v[8:11]
	v_mfma_f32_16x16x32_bf16 v[4:7], v[164:167], v[196:199], v[4:7]
	s_setprio 0
	s_barrier
	s_add_u32 s66, s26, 0x40000
	s_addc_u32 s67, s27, 0
	s_add_i32 s78, s60, s36
	s_mov_b32 m0, s78
	s_nop 0
	global_load_lds_dwordx4 v130, s[66:67]
	s_add_i32 m0, s78, 0x2000
	s_nop 0
	global_load_lds_dwordx4 v134, s[66:67]
	s_waitcnt vmcnt(6)
	s_barrier
; #define PG8_STAGE(bufoff, gbase, voff) do { _Pragma("unroll") for (int _i = 0; _i < 2; ++_i) \
;         __builtin_amdgcn_global_load_lds((const unsigned*)((const char*)(gbase) + (voff)[_i]), (LAS unsigned*)(lds + (bufoff) + ldsw + _i * 8192), 16, 0, 0); } while (0)
; #define PG8_LDA(dst, b, h) do { _Pragma("unroll") for (int m = 0; m < 4; ++m) _Pragma("unroll") for (int k = 0; k < 2; ++k) dst[m][k] = *(const LAS bf16x8*)(lds + PG8_SA(b, h) + aoff + m * 2048 + k * 1024); } while (0)
; #define PG8_LDB(dst, b, h) do { _Pragma("unroll") for (int n = 0; n < 2; ++n) _Pragma("unroll") for (int k = 0; k < 2; ++k) dst[n][k] = *(const LAS bf16x8*)(lds + PG8_SB(b, h) + boff + n * 2048 + k * 1024); } while (0)
; #define PG8_MMA(ai, bj, At, Bt) do { __builtin_amdgcn_s_setprio(1); _Pragma("unroll") for (int m = 0; m < 4; ++m) _Pragma("unroll") for (int n = 0; n < 2; ++n) _Pragma("unroll") for (int k = 0; k < 2; ++k) \
;         acc[ai][bj][m][n] = __builtin_amdgcn_mfma_f32_16x16x32_bf16(Bt[n][k], At[m][k], acc[ai][bj][m][n], 0, 0, 0); __builtin_amdgcn_s_setprio(0); } while (0)
; #define PG8_WAIT_V(n) asm volatile("s_waitcnt vmcnt(" #n ")" ::: "memory")
; #define PG8_WAIT_L(n) asm volatile("s_waitcnt lgkmcnt(" #n ")" ::: "memory")
; #define PG8_BAR __builtin_amdgcn_s_barrier()
; #define PG8_SCHED __builtin_amdgcn_sched_barrier(0)
; template <class Epi>
; __device__ __forceinline__ void gemm_phase(LAS unsigned char* lds, const Gemm g, const StaticOrder& S, const Epi& E) {
;     ...
;             PG8_WAIT_V(6); PG8_BAR; PG8_MMA(1, 1, At, B1); PG8_BAR;
;             PG8_LDB(B0, 1, 0); PG8_SCHED; PG8_LDA(At, 1, 0); PG8_STAGE(PG8_SA(0, 1), a2 + hstepA, voffA);
;             PG8_WAIT_L(8); PG8_BAR; PG8_WAIT_L(0); PG8_MMA(0, 0, At, B0); PG8_BAR; PG8_SCHED;
;             PG8_LDB(B1, 1, 1); PG8_STAGE(PG8_SB(1, 0), b3, voffB);
	s_setprio 1
	v_mfma_f32_16x16x32_bf16 v[60:63], v[200:203], v[168:171], v[60:63]
	v_mfma_f32_16x16x32_bf16 v[52:55], v[212:215], v[168:171], v[52:55]
	v_mfma_f32_16x16x32_bf16 v[44:47], v[200:203], v[176:179], v[44:47]
	v_mfma_f32_16x16x32_bf16 v[36:39], v[212:215], v[176:179], v[36:39]
	v_mfma_f32_16x16x32_bf16 v[28:31], v[200:203], v[184:187], v[28:31]
	v_mfma_f32_16x16x32_bf16 v[20:23], v[212:215], v[184:187], v[20:23]
	v_mfma_f32_16x16x32_bf16 v[12:15], v[200:203], v[192:195], v[12:15]
	v_mfma_f32_16x16x32_bf16 v[0:3], v[212:215], v[192:195], v[0:3]
	v_mfma_f32_16x16x32_bf16 v[60:63], v[204:207], v[172:175], v[60:63]
	v_mfma_f32_16x16x32_bf16 v[52:55], v[216:219], v[172:175], v[52:55]
	v_mfma_f32_16x16x32_bf16 v[44:47], v[204:207], v[180:183], v[44:47]
	v_mfma_f32_16x16x32_bf16 v[36:39], v[216:219], v[180:183], v[36:39]
	v_mfma_f32_16x16x32_bf16 v[28:31], v[204:207], v[188:191], v[28:31]
	v_mfma_f32_16x16x32_bf16 v[20:23], v[216:219], v[188:191], v[20:23]
	v_mfma_f32_16x16x32_bf16 v[12:15], v[204:207], v[196:199], v[12:15]
	v_mfma_f32_16x16x32_bf16 v[0:3], v[216:219], v[196:199], v[0:3]
	s_setprio 0
	s_add_i32 s66, 0, 0x18000
	v_add_u32_e32 v155, s66, v150
	s_barrier
	ds_read_b128 v[144:147], v155
	ds_read_b128 v[156:159], v155 offset:1024
	ds_read_b128 v[160:163], v155 offset:2048
	ds_read_b128 v[164:167], v155 offset:3072
	s_add_u32 s28, s28, 0x40000
	s_addc_u32 s29, s29, 0
	s_mov_b32 m0, s39
	ds_read_b128 v[168:171], v152 offset:32768
	ds_read_b128 v[172:175], v152 offset:33792
	ds_read_b128 v[176:179], v152 offset:34816
	ds_read_b128 v[180:183], v152 offset:35840
	ds_read_b128 v[184:187], v152 offset:36864
	ds_read_b128 v[188:191], v152 offset:37888
	ds_read_b128 v[192:195], v152 offset:38912
	ds_read_b128 v[196:199], v152 offset:39936
	global_load_lds_dwordx4 v128, s[28:29]
	s_mov_b32 m0, s40
	s_nop 0
	global_load_lds_dwordx4 v132, s[28:29]
	s_waitcnt lgkmcnt(8)
	s_barrier
	s_waitcnt lgkmcnt(0)
	s_setprio 1
	s_waitcnt lgkmcnt(0)
	v_mfma_f32_16x16x32_bf16 v[116:119], v[144:147], v[168:171], v[116:119]
	v_mfma_f32_16x16x32_bf16 v[112:115], v[160:163], v[168:171], v[112:115]
	v_mfma_f32_16x16x32_bf16 v[104:107], v[144:147], v[176:179], v[104:107]
	v_mfma_f32_16x16x32_bf16 v[96:99], v[160:163], v[176:179], v[96:99]
	v_mfma_f32_16x16x32_bf16 v[88:91], v[144:147], v[184:187], v[88:91]
	v_mfma_f32_16x16x32_bf16 v[80:83], v[160:163], v[184:187], v[80:83]
	v_mfma_f32_16x16x32_bf16 v[72:75], v[144:147], v[192:195], v[72:75]
	v_mfma_f32_16x16x32_bf16 v[64:67], v[160:163], v[192:195], v[64:67]
	v_mfma_f32_16x16x32_bf16 v[116:119], v[156:159], v[172:175], v[116:119]
	v_mfma_f32_16x16x32_bf16 v[112:115], v[164:167], v[172:175], v[112:115]
	v_mfma_f32_16x16x32_bf16 v[104:107], v[156:159], v[180:183], v[104:107]
	v_mfma_f32_16x16x32_bf16 v[96:99], v[164:167], v[180:183], v[96:99]
	v_mfma_f32_16x16x32_bf16 v[88:91], v[156:159], v[188:191], v[88:91]
	v_mfma_f32_16x16x32_bf16 v[80:83], v[164:167], v[188:191], v[80:83]
	v_mfma_f32_16x16x32_bf16 v[72:75], v[156:159], v[196:199], v[72:75]
	v_mfma_f32_16x16x32_bf16 v[64:67], v[164:167], v[196:199], v[64:67]
	s_setprio 0
	s_barrier
	s_add_i32 s28, 0, 0x1c000
	s_add_i32 s29, s66, s36
	v_add_u32_e32 v155, s28, v150
	v_lshl_add_u64 v[208:209], v[208:209], 0, s[12:13]
	s_mov_b32 m0, s29
	ds_read_b128 v[200:203], v155
	ds_read_b128 v[204:207], v155 offset:1024
	ds_read_b128 v[212:215], v155 offset:2048
	ds_read_b128 v[216:219], v155 offset:3072
	global_load_lds_dwordx4 v[208:209], off
	v_lshl_add_u64 v[208:209], v[220:221], 0, s[12:13]
	s_add_i32 m0, s29, 0x2000
	s_nop 0
	global_load_lds_dwordx4 v[208:209], off
	s_barrier
; #define PG8_STAGE(bufoff, gbase, voff) do { _Pragma("unroll") for (int _i = 0; _i < 2; ++_i) \
;         __builtin_amdgcn_global_load_lds((const unsigned*)((const char*)(gbase) + (voff)[_i]), (LAS unsigned*)(lds + (bufoff) + ldsw + _i * 8192), 16, 0, 0); } while (0)
; #define PG8_LDA(dst, b, h) do { _Pragma("unroll") for (int m = 0; m < 4; ++m) _Pragma("unroll") for (int k = 0; k < 2; ++k) dst[m][k] = *(const LAS bf16x8*)(lds + PG8_SA(b, h) + aoff + m * 2048 + k * 1024); } while (0)
; #define PG8_MMA(ai, bj, At, Bt) do { __builtin_amdgcn_s_setprio(1); _Pragma("unroll") for (int m = 0; m < 4; ++m) _Pragma("unroll") for (int n = 0; n < 2; ++n) _Pragma("unroll") for (int k = 0; k < 2; ++k) \
;         acc[ai][bj][m][n] = __builtin_amdgcn_mfma_f32_16x16x32_bf16(Bt[n][k], At[m][k], acc[ai][bj][m][n], 0, 0, 0); __builtin_amdgcn_s_setprio(0); } while (0)
; #define PG8_WAIT_V(n) asm volatile("s_waitcnt vmcnt(" #n ")" ::: "memory")
; #define PG8_WAIT_L(n) asm volatile("s_waitcnt lgkmcnt(" #n ")" ::: "memory")
; #define PG8_BAR __builtin_amdgcn_s_barrier()
; #define PG8_SCHED __builtin_amdgcn_sched_barrier(0)
; template <class Epi>
; __device__ __forceinline__ void gemm_phase(LAS unsigned char* lds, const Gemm g, const StaticOrder& S, const Epi& E) {
;     ...
;             PG8_BAR; PG8_WAIT_L(0); PG8_MMA(0, 1, At, B1); PG8_BAR;
;             PG8_LDA(At, 1, 1); PG8_STAGE(PG8_SA(1, 0), a3, voffA);
;             PG8_BAR; PG8_WAIT_L(0); PG8_MMA(1, 0, At, B0); PG8_BAR; PG8_SCHED;
;             PG8_STAGE(PG8_SB(1, 1), b3 + hstepB, voffB);
;             PG8_WAIT_V(6); PG8_BAR; PG8_MMA(1, 1, At, B1); PG8_BAR;
	s_waitcnt lgkmcnt(0)
	s_setprio 1
	s_waitcnt lgkmcnt(0)
	v_mfma_f32_16x16x32_bf16 v[124:127], v[200:203], v[168:171], v[124:127]
	v_mfma_f32_16x16x32_bf16 v[120:123], v[212:215], v[168:171], v[120:123]
	v_mfma_f32_16x16x32_bf16 v[108:111], v[200:203], v[176:179], v[108:111]
	v_mfma_f32_16x16x32_bf16 v[100:103], v[212:215], v[176:179], v[100:103]
	v_mfma_f32_16x16x32_bf16 v[92:95], v[200:203], v[184:187], v[92:95]
	v_mfma_f32_16x16x32_bf16 v[84:87], v[212:215], v[184:187], v[84:87]
	v_mfma_f32_16x16x32_bf16 v[76:79], v[200:203], v[192:195], v[76:79]
	v_mfma_f32_16x16x32_bf16 v[68:71], v[212:215], v[192:195], v[68:71]
	v_mfma_f32_16x16x32_bf16 v[124:127], v[204:207], v[172:175], v[124:127]
	v_mfma_f32_16x16x32_bf16 v[120:123], v[216:219], v[172:175], v[120:123]
	v_mfma_f32_16x16x32_bf16 v[108:111], v[204:207], v[180:183], v[108:111]
	v_mfma_f32_16x16x32_bf16 v[100:103], v[216:219], v[180:183], v[100:103]
	v_mfma_f32_16x16x32_bf16 v[92:95], v[204:207], v[188:191], v[92:95]
	v_mfma_f32_16x16x32_bf16 v[84:87], v[216:219], v[188:191], v[84:87]
	v_mfma_f32_16x16x32_bf16 v[76:79], v[204:207], v[196:199], v[76:79]
	v_mfma_f32_16x16x32_bf16 v[68:71], v[216:219], v[196:199], v[68:71]
	s_setprio 0
	s_mov_b32 m0, s44
	v_lshl_add_u64 v[208:209], v[222:223], 0, s[12:13]
	s_barrier
	ds_read_b128 v[168:171], v152 offset:49152
	ds_read_b128 v[172:175], v152 offset:50176
	ds_read_b128 v[176:179], v152 offset:51200
	ds_read_b128 v[180:183], v152 offset:52224
	ds_read_b128 v[184:187], v152 offset:53248
	ds_read_b128 v[188:191], v152 offset:54272
	ds_read_b128 v[192:195], v152 offset:55296
	ds_read_b128 v[196:199], v152 offset:56320
	global_load_lds_dwordx4 v[208:209], off
	v_lshl_add_u64 v[208:209], v[224:225], 0, s[12:13]
	s_mov_b32 m0, s45
	s_nop 0
	global_load_lds_dwordx4 v[208:209], off
	s_barrier
	s_waitcnt lgkmcnt(0)
	s_setprio 1
	s_waitcnt lgkmcnt(0)
	v_mfma_f32_16x16x32_bf16 v[56:59], v[144:147], v[168:171], v[56:59]
	v_mfma_f32_16x16x32_bf16 v[48:51], v[160:163], v[168:171], v[48:51]
	v_mfma_f32_16x16x32_bf16 v[40:43], v[144:147], v[176:179], v[40:43]
	v_mfma_f32_16x16x32_bf16 v[32:35], v[160:163], v[176:179], v[32:35]
	v_mfma_f32_16x16x32_bf16 v[24:27], v[144:147], v[184:187], v[24:27]
	v_mfma_f32_16x16x32_bf16 v[16:19], v[160:163], v[184:187], v[16:19]
	v_mfma_f32_16x16x32_bf16 v[8:11], v[144:147], v[192:195], v[8:11]
	v_mfma_f32_16x16x32_bf16 v[4:7], v[160:163], v[192:195], v[4:7]
	v_mfma_f32_16x16x32_bf16 v[56:59], v[156:159], v[172:175], v[56:59]
	v_mfma_f32_16x16x32_bf16 v[48:51], v[164:167], v[172:175], v[48:51]
	v_mfma_f32_16x16x32_bf16 v[40:43], v[156:159], v[180:183], v[40:43]
	v_mfma_f32_16x16x32_bf16 v[32:35], v[164:167], v[180:183], v[32:35]
	v_mfma_f32_16x16x32_bf16 v[24:27], v[156:159], v[188:191], v[24:27]
	v_mfma_f32_16x16x32_bf16 v[16:19], v[164:167], v[188:191], v[16:19]
	v_mfma_f32_16x16x32_bf16 v[8:11], v[156:159], v[196:199], v[8:11]
	v_mfma_f32_16x16x32_bf16 v[4:7], v[164:167], v[196:199], v[4:7]
	s_setprio 0
	s_barrier
	s_add_u32 s26, s26, 0x40080
	s_addc_u32 s27, s27, 0
	s_add_i32 s28, s28, s36
	s_mov_b32 m0, s28
	s_nop 0
	global_load_lds_dwordx4 v130, s[26:27]
	s_add_i32 m0, s28, 0x2000
	s_nop 0
	global_load_lds_dwordx4 v134, s[26:27]
	s_waitcnt vmcnt(6)
	s_barrier
	s_setprio 1
	v_mfma_f32_16x16x32_bf16 v[60:63], v[200:203], v[168:171], v[60:63]
	v_mfma_f32_16x16x32_bf16 v[52:55], v[212:215], v[168:171], v[52:55]
	v_mfma_f32_16x16x32_bf16 v[44:47], v[200:203], v[176:179], v[44:47]
	v_mfma_f32_16x16x32_bf16 v[36:39], v[212:215], v[176:179], v[36:39]
	v_mfma_f32_16x16x32_bf16 v[28:31], v[200:203], v[184:187], v[28:31]
	v_mfma_f32_16x16x32_bf16 v[20:23], v[212:215], v[184:187], v[20:23]
	v_mfma_f32_16x16x32_bf16 v[12:15], v[200:203], v[192:195], v[12:15]
	v_mfma_f32_16x16x32_bf16 v[0:3], v[212:215], v[192:195], v[0:3]
	v_mfma_f32_16x16x32_bf16 v[60:63], v[204:207], v[172:175], v[60:63]
	v_mfma_f32_16x16x32_bf16 v[52:55], v[216:219], v[172:175], v[52:55]
	v_mfma_f32_16x16x32_bf16 v[44:47], v[204:207], v[180:183], v[44:47]
	v_mfma_f32_16x16x32_bf16 v[36:39], v[216:219], v[180:183], v[36:39]
	v_mfma_f32_16x16x32_bf16 v[28:31], v[204:207], v[188:191], v[28:31]
	v_mfma_f32_16x16x32_bf16 v[20:23], v[216:219], v[188:191], v[20:23]
	v_mfma_f32_16x16x32_bf16 v[12:15], v[204:207], v[196:199], v[12:15]
	v_mfma_f32_16x16x32_bf16 v[0:3], v[216:219], v[196:199], v[0:3]
	s_setprio 0
	s_add_u32 s8, s8, 0x100
	s_addc_u32 s9, s9, 0
	s_add_u32 s65, s65, 0x100
	s_addc_u32 s76, s76, 0
	s_cmp_ge_i32 s77, s43
	s_mov_b32 s26, s77
	s_barrier
	s_cbranch_scc0 .LBB0_2411
	s_branch .LBB0_2402

; #define PG8_STAGE(bufoff, gbase, voff) do { _Pragma("unroll") for (int _i = 0; _i < 2; ++_i) \
;         __builtin_amdgcn_global_load_lds((const unsigned*)((const char*)(gbase) + (voff)[_i]), (LAS unsigned*)(lds + (bufoff) + ldsw + _i * 8192), 16, 0, 0); } while (0)
; #define PG8_LDA(dst, b, h) do { _Pragma("unroll") for (int m = 0; m < 4; ++m) _Pragma("unroll") for (int k = 0; k < 2; ++k) dst[m][k] = *(const LAS bf16x8*)(lds + PG8_SA(b, h) + aoff + m * 2048 + k * 1024); } while (0)
; #define PG8_LDB(dst, b, h) do { _Pragma("unroll") for (int n = 0; n < 2; ++n) _Pragma("unroll") for (int k = 0; k < 2; ++k) dst[n][k] = *(const LAS bf16x8*)(lds + PG8_SB(b, h) + boff + n * 2048 + k * 1024); } while (0)
; #define PG8_MMA(ai, bj, At, Bt) do { __builtin_amdgcn_s_setprio(1); _Pragma("unroll") for (int m = 0; m < 4; ++m) _Pragma("unroll") for (int n = 0; n < 2; ++n) _Pragma("unroll") for (int k = 0; k < 2; ++k) \
;         acc[ai][bj][m][n] = __builtin_amdgcn_mfma_f32_16x16x32_bf16(Bt[n][k], At[m][k], acc[ai][bj][m][n], 0, 0, 0); __builtin_amdgcn_s_setprio(0); } while (0)
; #define PG8_WAIT_L(n) asm volatile("s_waitcnt lgkmcnt(" #n ")" ::: "memory")
; #define PG8_BAR __builtin_amdgcn_s_barrier()
; #define PG8_SCHED __builtin_amdgcn_sched_barrier(0)
; template <class Epi>
; __device__ __forceinline__ void gemm_phase(LAS unsigned char* lds, const Gemm g, const StaticOrder& S, const Epi& E) {
;     ...
;         for (int t = 0; t < nt; t += 2) {
;             const bool last = (t == nt - 2);
;             const char* a1 = cA + (size_t)(t + 1) * kstep;
;             const char* a2 = last ? nA : cA + (size_t)(t + 2) * kstep; const char* b2 = last ? nB : cB + (size_t)(t + 2) * kstep;
;             const char* a3 = a2 + kstep; const char* b3 = b2 + kstep;
;             PG8_LDB(B0, 0, 0); PG8_SCHED; PG8_LDA(At, 0, 0); PG8_STAGE(PG8_SA(1, 1), a1 + hstepA, voffA);
;             PG8_WAIT_L(8); PG8_BAR; PG8_WAIT_L(0); PG8_MMA(0, 0, At, B0); PG8_BAR; PG8_SCHED;
;             PG8_LDB(B1, 0, 1); PG8_STAGE(PG8_SB(0, 0), b2, voffB);
;             PG8_BAR; PG8_WAIT_L(0); PG8_MMA(0, 1, At, B1); PG8_BAR;
;             PG8_LDA(At, 0, 1); PG8_STAGE(PG8_SA(0, 0), a2, voffA);
;             PG8_BAR; PG8_WAIT_L(0); PG8_MMA(1, 0, At, B0); PG8_BAR; PG8_SCHED;
.LBB0_2433:
	ds_read_b128 v[150:153], v147
	ds_read_b128 v[154:157], v147 offset:1024
	ds_read_b128 v[158:161], v147 offset:2048
	ds_read_b128 v[162:165], v147 offset:3072
	s_add_i32 s68, s28, 2
	s_add_u32 s29, s10, 0xffff0080
	s_addc_u32 s30, s11, -1
	s_cmp_eq_u32 s47, s28
	s_cselect_b32 s28, s63, s64
	s_cselect_b32 s31, s21, s30
	s_cselect_b32 s30, s23, s29
	s_cselect_b32 s29, s62, s65
	s_add_i32 m0, s19, 0xc000
	ds_read_b128 v[166:169], v148
	ds_read_b128 v[170:173], v148 offset:1024
	ds_read_b128 v[174:177], v148 offset:2048
	ds_read_b128 v[178:181], v148 offset:3072
	ds_read_b128 v[182:185], v148 offset:4096
	ds_read_b128 v[186:189], v148 offset:5120
	ds_read_b128 v[190:193], v148 offset:6144
	ds_read_b128 v[194:197], v148 offset:7168
	global_load_lds_dwordx4 v136, s[10:11]
	s_add_i32 m0, s19, 0xe000
	s_nop 0
	global_load_lds_dwordx4 v138, s[10:11]
	s_waitcnt lgkmcnt(8)
	s_barrier
	s_waitcnt lgkmcnt(0)
	s_setprio 1
	s_waitcnt lgkmcnt(0)
	v_mfma_f32_16x16x32_bf16 v[124:127], v[150:153], v[166:169], v[124:127]
	v_mfma_f32_16x16x32_bf16 v[120:123], v[158:161], v[166:169], v[120:123]
	v_mfma_f32_16x16x32_bf16 v[108:111], v[150:153], v[174:177], v[108:111]
	v_mfma_f32_16x16x32_bf16 v[104:107], v[158:161], v[174:177], v[104:107]
	v_mfma_f32_16x16x32_bf16 v[92:95], v[150:153], v[182:185], v[92:95]
	v_mfma_f32_16x16x32_bf16 v[88:91], v[158:161], v[182:185], v[88:91]
	v_mfma_f32_16x16x32_bf16 v[76:79], v[150:153], v[190:193], v[76:79]
	v_mfma_f32_16x16x32_bf16 v[72:75], v[158:161], v[190:193], v[72:75]
	v_mfma_f32_16x16x32_bf16 v[124:127], v[154:157], v[170:173], v[124:127]
	v_mfma_f32_16x16x32_bf16 v[120:123], v[162:165], v[170:173], v[120:123]
	v_mfma_f32_16x16x32_bf16 v[108:111], v[154:157], v[178:181], v[108:111]
	v_mfma_f32_16x16x32_bf16 v[104:107], v[162:165], v[178:181], v[104:107]
	v_mfma_f32_16x16x32_bf16 v[92:95], v[154:157], v[186:189], v[92:95]
	v_mfma_f32_16x16x32_bf16 v[88:91], v[162:165], v[186:189], v[88:91]
	v_mfma_f32_16x16x32_bf16 v[76:79], v[154:157], v[194:197], v[76:79]
	v_mfma_f32_16x16x32_bf16 v[72:75], v[162:165], v[194:197], v[72:75]
	s_setprio 0
	s_barrier
	s_add_i32 s66, s49, s38
	v_lshl_add_u64 v[216:217], s[28:29], 0, v[130:131]
	s_mov_b32 m0, s66
	ds_read_b128 v[198:201], v149
	ds_read_b128 v[202:205], v149 offset:1024
	ds_read_b128 v[206:209], v149 offset:2048
	ds_read_b128 v[212:215], v149 offset:3072
	global_load_lds_dwordx4 v[216:217], off
	v_lshl_add_u64 v[218:219], s[28:29], 0, v[134:135]
	s_add_i32 m0, s66, 0x2000
	s_nop 0
	global_load_lds_dwordx4 v[218:219], off
	s_barrier
	s_waitcnt lgkmcnt(0)
	s_setprio 1
	s_waitcnt lgkmcnt(0)
	v_mfma_f32_16x16x32_bf16 v[116:119], v[198:201], v[166:169], v[116:119]
	v_mfma_f32_16x16x32_bf16 v[112:115], v[206:209], v[166:169], v[112:115]
	v_mfma_f32_16x16x32_bf16 v[100:103], v[198:201], v[174:177], v[100:103]
	v_mfma_f32_16x16x32_bf16 v[96:99], v[206:209], v[174:177], v[96:99]
	v_mfma_f32_16x16x32_bf16 v[84:87], v[198:201], v[182:185], v[84:87]
	v_mfma_f32_16x16x32_bf16 v[80:83], v[206:209], v[182:185], v[80:83]
	v_mfma_f32_16x16x32_bf16 v[68:71], v[198:201], v[190:193], v[68:71]
	v_mfma_f32_16x16x32_bf16 v[64:67], v[206:209], v[190:193], v[64:67]
	v_mfma_f32_16x16x32_bf16 v[116:119], v[202:205], v[170:173], v[116:119]
	v_mfma_f32_16x16x32_bf16 v[112:115], v[212:215], v[170:173], v[112:115]
	v_mfma_f32_16x16x32_bf16 v[100:103], v[202:205], v[178:181], v[100:103]
	v_mfma_f32_16x16x32_bf16 v[96:99], v[212:215], v[178:181], v[96:99]
	v_mfma_f32_16x16x32_bf16 v[84:87], v[202:205], v[186:189], v[84:87]
	v_mfma_f32_16x16x32_bf16 v[80:83], v[212:215], v[186:189], v[80:83]
	v_mfma_f32_16x16x32_bf16 v[68:71], v[202:205], v[194:197], v[68:71]
	v_mfma_f32_16x16x32_bf16 v[64:67], v[212:215], v[194:197], v[64:67]
	s_setprio 0
	s_mov_b32 m0, s19
	v_lshl_add_u64 v[220:221], s[30:31], 0, v[128:129]
	s_barrier
	ds_read_b128 v[166:169], v148 offset:16384
	ds_read_b128 v[170:173], v148 offset:17408
	ds_read_b128 v[174:177], v148 offset:18432
	ds_read_b128 v[178:181], v148 offset:19456
	ds_read_b128 v[182:185], v148 offset:20480
	ds_read_b128 v[186:189], v148 offset:21504
	ds_read_b128 v[190:193], v148 offset:22528
	ds_read_b128 v[194:197], v148 offset:23552
	global_load_lds_dwordx4 v[220:221], off
	v_lshl_add_u64 v[222:223], s[30:31], 0, v[132:133]
	s_mov_b32 m0, s39
	s_nop 0
	global_load_lds_dwordx4 v[222:223], off
	s_barrier
	s_waitcnt lgkmcnt(0)
	s_setprio 1
	s_waitcnt lgkmcnt(0)
	v_mfma_f32_16x16x32_bf16 v[60:63], v[150:153], v[166:169], v[60:63]
	v_mfma_f32_16x16x32_bf16 v[56:59], v[158:161], v[166:169], v[56:59]
	v_mfma_f32_16x16x32_bf16 v[44:47], v[150:153], v[174:177], v[44:47]
	v_mfma_f32_16x16x32_bf16 v[40:43], v[158:161], v[174:177], v[40:43]
	v_mfma_f32_16x16x32_bf16 v[28:31], v[150:153], v[182:185], v[28:31]
	v_mfma_f32_16x16x32_bf16 v[24:27], v[158:161], v[182:185], v[24:27]
	v_mfma_f32_16x16x32_bf16 v[12:15], v[150:153], v[190:193], v[12:15]
	v_mfma_f32_16x16x32_bf16 v[8:11], v[158:161], v[190:193], v[8:11]
	v_mfma_f32_16x16x32_bf16 v[60:63], v[154:157], v[170:173], v[60:63]
	v_mfma_f32_16x16x32_bf16 v[56:59], v[162:165], v[170:173], v[56:59]
	v_mfma_f32_16x16x32_bf16 v[44:47], v[154:157], v[178:181], v[44:47]
	v_mfma_f32_16x16x32_bf16 v[40:43], v[162:165], v[178:181], v[40:43]
	v_mfma_f32_16x16x32_bf16 v[28:31], v[154:157], v[186:189], v[28:31]
	v_mfma_f32_16x16x32_bf16 v[24:27], v[162:165], v[186:189], v[24:27]
	v_mfma_f32_16x16x32_bf16 v[12:15], v[154:157], v[194:197], v[12:15]
	v_mfma_f32_16x16x32_bf16 v[8:11], v[162:165], v[194:197], v[8:11]
	s_setprio 0
	s_barrier
; #define PG8_STAGE(bufoff, gbase, voff) do { _Pragma("unroll") for (int _i = 0; _i < 2; ++_i) \
;         __builtin_amdgcn_global_load_lds((const unsigned*)((const char*)(gbase) + (voff)[_i]), (LAS unsigned*)(lds + (bufoff) + ldsw + _i * 8192), 16, 0, 0); } while (0)
; #define PG8_LDA(dst, b, h) do { _Pragma("unroll") for (int m = 0; m < 4; ++m) _Pragma("unroll") for (int k = 0; k < 2; ++k) dst[m][k] = *(const LAS bf16x8*)(lds + PG8_SA(b, h) + aoff + m * 2048 + k * 1024); } while (0)
; #define PG8_LDB(dst, b, h) do { _Pragma("unroll") for (int n = 0; n < 2; ++n) _Pragma("unroll") for (int k = 0; k < 2; ++k) dst[n][k] = *(const LAS bf16x8*)(lds + PG8_SB(b, h) + boff + n * 2048 + k * 1024); } while (0)
; #define PG8_MMA(ai, bj, At, Bt) do { __builtin_amdgcn_s_setprio(1); _Pragma("unroll") for (int m = 0; m < 4; ++m) _Pragma("unroll") for (int n = 0; n < 2; ++n) _Pragma("unroll") for (int k = 0; k < 2; ++k) \
;         acc[ai][bj][m][n] = __builtin_amdgcn_mfma_f32_16x16x32_bf16(Bt[n][k], At[m][k], acc[ai][bj][m][n], 0, 0, 0); __builtin_amdgcn_s_setprio(0); } while (0)
; #define PG8_WAIT_V(n) asm volatile("s_waitcnt vmcnt(" #n ")" ::: "memory")
; #define PG8_WAIT_L(n) asm volatile("s_waitcnt lgkmcnt(" #n ")" ::: "memory")
; #define PG8_BAR __builtin_amdgcn_s_barrier()
; #define PG8_SCHED __builtin_amdgcn_sched_barrier(0)
; template <class Epi>
; __device__ __forceinline__ void gemm_phase(LAS unsigned char* lds, const Gemm g, const StaticOrder& S, const Epi& E) {
;     ...
;             PG8_STAGE(PG8_SB(0, 1), b2 + hstepB, voffB);
;             PG8_WAIT_V(6); PG8_BAR; PG8_MMA(1, 1, At, B1); PG8_BAR;
;             PG8_LDB(B0, 1, 0); PG8_SCHED; PG8_LDA(At, 1, 0); PG8_STAGE(PG8_SA(0, 1), a2 + hstepA, voffA);
;             PG8_WAIT_L(8); PG8_BAR; PG8_WAIT_L(0); PG8_MMA(0, 0, At, B0); PG8_BAR; PG8_SCHED;
;             PG8_LDB(B1, 1, 1); PG8_STAGE(PG8_SB(1, 0), b3, voffB);
	s_add_u32 s66, s28, 0x10000
	s_addc_u32 s67, s29, 0
	s_add_i32 s69, s60, s38
	s_mov_b32 m0, s69
	s_nop 0
	global_load_lds_dwordx4 v130, s[66:67]
	s_add_i32 m0, s69, 0x2000
	s_nop 0
	global_load_lds_dwordx4 v134, s[66:67]
	s_waitcnt vmcnt(6)
	s_barrier
	s_setprio 1
	v_mfma_f32_16x16x32_bf16 v[52:55], v[198:201], v[166:169], v[52:55]
	v_mfma_f32_16x16x32_bf16 v[48:51], v[206:209], v[166:169], v[48:51]
	v_mfma_f32_16x16x32_bf16 v[36:39], v[198:201], v[174:177], v[36:39]
	v_mfma_f32_16x16x32_bf16 v[32:35], v[206:209], v[174:177], v[32:35]
	v_mfma_f32_16x16x32_bf16 v[20:23], v[198:201], v[182:185], v[20:23]
	v_mfma_f32_16x16x32_bf16 v[16:19], v[206:209], v[182:185], v[16:19]
	v_mfma_f32_16x16x32_bf16 v[4:7], v[198:201], v[190:193], v[4:7]
	v_mfma_f32_16x16x32_bf16 v[0:3], v[206:209], v[190:193], v[0:3]
	v_mfma_f32_16x16x32_bf16 v[52:55], v[202:205], v[170:173], v[52:55]
	v_mfma_f32_16x16x32_bf16 v[48:51], v[212:215], v[170:173], v[48:51]
	v_mfma_f32_16x16x32_bf16 v[36:39], v[202:205], v[178:181], v[36:39]
	v_mfma_f32_16x16x32_bf16 v[32:35], v[212:215], v[178:181], v[32:35]
	v_mfma_f32_16x16x32_bf16 v[20:23], v[202:205], v[186:189], v[20:23]
	v_mfma_f32_16x16x32_bf16 v[16:19], v[212:215], v[186:189], v[16:19]
	v_mfma_f32_16x16x32_bf16 v[4:7], v[202:205], v[194:197], v[4:7]
	v_mfma_f32_16x16x32_bf16 v[0:3], v[212:215], v[194:197], v[0:3]
	s_setprio 0
	s_add_i32 s66, 0, 0x18000
	v_add_u32_e32 v162, s66, v146
	s_barrier
	ds_read_b128 v[150:153], v162
	ds_read_b128 v[154:157], v162 offset:1024
	ds_read_b128 v[158:161], v162 offset:2048
	ds_read_b128 v[162:165], v162 offset:3072
	s_add_u32 s30, s30, 0x10000
	s_addc_u32 s31, s31, 0
	s_mov_b32 m0, s40
	ds_read_b128 v[166:169], v148 offset:32768
	ds_read_b128 v[170:173], v148 offset:33792
	ds_read_b128 v[174:177], v148 offset:34816
	ds_read_b128 v[178:181], v148 offset:35840
	ds_read_b128 v[182:185], v148 offset:36864
	ds_read_b128 v[186:189], v148 offset:37888
	ds_read_b128 v[190:193], v148 offset:38912
	ds_read_b128 v[194:197], v148 offset:39936
	global_load_lds_dwordx4 v128, s[30:31]
	s_mov_b32 m0, s41
	s_nop 0
	global_load_lds_dwordx4 v132, s[30:31]
	s_waitcnt lgkmcnt(8)
	s_barrier
	s_waitcnt lgkmcnt(0)
	s_setprio 1
	s_waitcnt lgkmcnt(0)
	v_mfma_f32_16x16x32_bf16 v[124:127], v[150:153], v[166:169], v[124:127]
	v_mfma_f32_16x16x32_bf16 v[120:123], v[158:161], v[166:169], v[120:123]
	v_mfma_f32_16x16x32_bf16 v[108:111], v[150:153], v[174:177], v[108:111]
	v_mfma_f32_16x16x32_bf16 v[104:107], v[158:161], v[174:177], v[104:107]
	v_mfma_f32_16x16x32_bf16 v[92:95], v[150:153], v[182:185], v[92:95]
	v_mfma_f32_16x16x32_bf16 v[88:91], v[158:161], v[182:185], v[88:91]
	v_mfma_f32_16x16x32_bf16 v[76:79], v[150:153], v[190:193], v[76:79]
	v_mfma_f32_16x16x32_bf16 v[72:75], v[158:161], v[190:193], v[72:75]
	v_mfma_f32_16x16x32_bf16 v[124:127], v[154:157], v[170:173], v[124:127]
	v_mfma_f32_16x16x32_bf16 v[120:123], v[162:165], v[170:173], v[120:123]
	v_mfma_f32_16x16x32_bf16 v[108:111], v[154:157], v[178:181], v[108:111]
	v_mfma_f32_16x16x32_bf16 v[104:107], v[162:165], v[178:181], v[104:107]
	v_mfma_f32_16x16x32_bf16 v[92:95], v[154:157], v[186:189], v[92:95]
	v_mfma_f32_16x16x32_bf16 v[88:91], v[162:165], v[186:189], v[88:91]
	v_mfma_f32_16x16x32_bf16 v[76:79], v[154:157], v[194:197], v[76:79]
	v_mfma_f32_16x16x32_bf16 v[72:75], v[162:165], v[194:197], v[72:75]
	s_setprio 0
	s_barrier
	s_add_i32 s30, 0, 0x1c000
	s_add_i32 s31, s66, s38
	v_add_u32_e32 v211, s30, v146
	v_lshl_add_u64 v[216:217], v[216:217], 0, s[16:17]
	s_mov_b32 m0, s31
	ds_read_b128 v[198:201], v211
	ds_read_b128 v[202:205], v211 offset:1024
	ds_read_b128 v[206:209], v211 offset:2048
	ds_read_b128 v[212:215], v211 offset:3072
	global_load_lds_dwordx4 v[216:217], off
	v_lshl_add_u64 v[216:217], v[218:219], 0, s[16:17]
	s_add_i32 m0, s31, 0x2000
	s_nop 0
	global_load_lds_dwordx4 v[216:217], off
	s_barrier
; #define PG8_STAGE(bufoff, gbase, voff) do { _Pragma("unroll") for (int _i = 0; _i < 2; ++_i) \
;         __builtin_amdgcn_global_load_lds((const unsigned*)((const char*)(gbase) + (voff)[_i]), (LAS unsigned*)(lds + (bufoff) + ldsw + _i * 8192), 16, 0, 0); } while (0)
; #define PG8_LDA(dst, b, h) do { _Pragma("unroll") for (int m = 0; m < 4; ++m) _Pragma("unroll") for (int k = 0; k < 2; ++k) dst[m][k] = *(const LAS bf16x8*)(lds + PG8_SA(b, h) + aoff + m * 2048 + k * 1024); } while (0)
; #define PG8_MMA(ai, bj, At, Bt) do { __builtin_amdgcn_s_setprio(1); _Pragma("unroll") for (int m = 0; m < 4; ++m) _Pragma("unroll") for (int n = 0; n < 2; ++n) _Pragma("unroll") for (int k = 0; k < 2; ++k) \
;         acc[ai][bj][m][n] = __builtin_amdgcn_mfma_f32_16x16x32_bf16(Bt[n][k], At[m][k], acc[ai][bj][m][n], 0, 0, 0); __builtin_amdgcn_s_setprio(0); } while (0)
; #define PG8_WAIT_V(n) asm volatile("s_waitcnt vmcnt(" #n ")" ::: "memory")
; #define PG8_WAIT_L(n) asm volatile("s_waitcnt lgkmcnt(" #n ")" ::: "memory")
; #define PG8_BAR __builtin_amdgcn_s_barrier()
; #define PG8_SCHED __builtin_amdgcn_sched_barrier(0)
; template <class Epi>
; __device__ __forceinline__ void gemm_phase(LAS unsigned char* lds, const Gemm g, const StaticOrder& S, const Epi& E) {
;     ...
;             PG8_BAR; PG8_WAIT_L(0); PG8_MMA(0, 1, At, B1); PG8_BAR;
;             PG8_LDA(At, 1, 1); PG8_STAGE(PG8_SA(1, 0), a3, voffA);
;             PG8_BAR; PG8_WAIT_L(0); PG8_MMA(1, 0, At, B0); PG8_BAR; PG8_SCHED;
;             PG8_STAGE(PG8_SB(1, 1), b3 + hstepB, voffB);
;             PG8_WAIT_V(6); PG8_BAR; PG8_MMA(1, 1, At, B1); PG8_BAR;
;         }
	s_waitcnt lgkmcnt(0)
	s_setprio 1
	s_waitcnt lgkmcnt(0)
	v_mfma_f32_16x16x32_bf16 v[116:119], v[198:201], v[166:169], v[116:119]
	v_mfma_f32_16x16x32_bf16 v[112:115], v[206:209], v[166:169], v[112:115]
	v_mfma_f32_16x16x32_bf16 v[100:103], v[198:201], v[174:177], v[100:103]
	v_mfma_f32_16x16x32_bf16 v[96:99], v[206:209], v[174:177], v[96:99]
	v_mfma_f32_16x16x32_bf16 v[84:87], v[198:201], v[182:185], v[84:87]
	v_mfma_f32_16x16x32_bf16 v[80:83], v[206:209], v[182:185], v[80:83]
	v_mfma_f32_16x16x32_bf16 v[68:71], v[198:201], v[190:193], v[68:71]
	v_mfma_f32_16x16x32_bf16 v[64:67], v[206:209], v[190:193], v[64:67]
	v_mfma_f32_16x16x32_bf16 v[116:119], v[202:205], v[170:173], v[116:119]
	v_mfma_f32_16x16x32_bf16 v[112:115], v[212:215], v[170:173], v[112:115]
	v_mfma_f32_16x16x32_bf16 v[100:103], v[202:205], v[178:181], v[100:103]
	v_mfma_f32_16x16x32_bf16 v[96:99], v[212:215], v[178:181], v[96:99]
	v_mfma_f32_16x16x32_bf16 v[84:87], v[202:205], v[186:189], v[84:87]
	v_mfma_f32_16x16x32_bf16 v[80:83], v[212:215], v[186:189], v[80:83]
	v_mfma_f32_16x16x32_bf16 v[68:71], v[202:205], v[194:197], v[68:71]
	v_mfma_f32_16x16x32_bf16 v[64:67], v[212:215], v[194:197], v[64:67]
	s_setprio 0
	s_mov_b32 m0, s45
	v_lshl_add_u64 v[216:217], v[220:221], 0, s[16:17]
	s_barrier
	ds_read_b128 v[166:169], v148 offset:49152
	ds_read_b128 v[170:173], v148 offset:50176
	ds_read_b128 v[174:177], v148 offset:51200
	ds_read_b128 v[178:181], v148 offset:52224
	ds_read_b128 v[182:185], v148 offset:53248
	ds_read_b128 v[186:189], v148 offset:54272
	ds_read_b128 v[190:193], v148 offset:55296
	ds_read_b128 v[194:197], v148 offset:56320
	global_load_lds_dwordx4 v[216:217], off
	v_lshl_add_u64 v[216:217], v[222:223], 0, s[16:17]
	s_mov_b32 m0, s46
	s_nop 0
	global_load_lds_dwordx4 v[216:217], off
	s_barrier
	s_waitcnt lgkmcnt(0)
	s_setprio 1
	s_waitcnt lgkmcnt(0)
	v_mfma_f32_16x16x32_bf16 v[60:63], v[150:153], v[166:169], v[60:63]
	v_mfma_f32_16x16x32_bf16 v[56:59], v[158:161], v[166:169], v[56:59]
	v_mfma_f32_16x16x32_bf16 v[44:47], v[150:153], v[174:177], v[44:47]
	v_mfma_f32_16x16x32_bf16 v[40:43], v[158:161], v[174:177], v[40:43]
	v_mfma_f32_16x16x32_bf16 v[28:31], v[150:153], v[182:185], v[28:31]
	v_mfma_f32_16x16x32_bf16 v[24:27], v[158:161], v[182:185], v[24:27]
	v_mfma_f32_16x16x32_bf16 v[12:15], v[150:153], v[190:193], v[12:15]
	v_mfma_f32_16x16x32_bf16 v[8:11], v[158:161], v[190:193], v[8:11]
	v_mfma_f32_16x16x32_bf16 v[60:63], v[154:157], v[170:173], v[60:63]
	v_mfma_f32_16x16x32_bf16 v[56:59], v[162:165], v[170:173], v[56:59]
	v_mfma_f32_16x16x32_bf16 v[44:47], v[154:157], v[178:181], v[44:47]
	v_mfma_f32_16x16x32_bf16 v[40:43], v[162:165], v[178:181], v[40:43]
	v_mfma_f32_16x16x32_bf16 v[28:31], v[154:157], v[186:189], v[28:31]
	v_mfma_f32_16x16x32_bf16 v[24:27], v[162:165], v[186:189], v[24:27]
	v_mfma_f32_16x16x32_bf16 v[12:15], v[154:157], v[194:197], v[12:15]
	v_mfma_f32_16x16x32_bf16 v[8:11], v[162:165], v[194:197], v[8:11]
	s_setprio 0
	s_barrier
	s_add_u32 s28, s28, 0x10080
	s_addc_u32 s29, s29, 0
	s_add_i32 s30, s30, s38
	s_mov_b32 m0, s30
	s_nop 0
	global_load_lds_dwordx4 v130, s[28:29]
	s_add_i32 m0, s30, 0x2000
	s_nop 0
	global_load_lds_dwordx4 v134, s[28:29]
	s_waitcnt vmcnt(6)
	s_barrier
	s_setprio 1
	v_mfma_f32_16x16x32_bf16 v[52:55], v[198:201], v[166:169], v[52:55]
	v_mfma_f32_16x16x32_bf16 v[48:51], v[206:209], v[166:169], v[48:51]
	v_mfma_f32_16x16x32_bf16 v[36:39], v[198:201], v[174:177], v[36:39]
	v_mfma_f32_16x16x32_bf16 v[32:35], v[206:209], v[174:177], v[32:35]
	v_mfma_f32_16x16x32_bf16 v[20:23], v[198:201], v[182:185], v[20:23]
	v_mfma_f32_16x16x32_bf16 v[16:19], v[206:209], v[182:185], v[16:19]
	v_mfma_f32_16x16x32_bf16 v[4:7], v[198:201], v[190:193], v[4:7]
	v_mfma_f32_16x16x32_bf16 v[0:3], v[206:209], v[190:193], v[0:3]
	v_mfma_f32_16x16x32_bf16 v[52:55], v[202:205], v[170:173], v[52:55]
	v_mfma_f32_16x16x32_bf16 v[48:51], v[212:215], v[170:173], v[48:51]
	v_mfma_f32_16x16x32_bf16 v[36:39], v[202:205], v[178:181], v[36:39]
	v_mfma_f32_16x16x32_bf16 v[32:35], v[212:215], v[178:181], v[32:35]
	v_mfma_f32_16x16x32_bf16 v[20:23], v[202:205], v[186:189], v[20:23]
	v_mfma_f32_16x16x32_bf16 v[16:19], v[212:215], v[186:189], v[16:19]
	v_mfma_f32_16x16x32_bf16 v[4:7], v[202:205], v[194:197], v[4:7]
	v_mfma_f32_16x16x32_bf16 v[0:3], v[212:215], v[194:197], v[0:3]
	s_setprio 0
	s_add_u32 s10, s10, 0x100
	s_addc_u32 s11, s11, 0
	s_add_u32 s64, s64, 0x100
	s_addc_u32 s65, s65, 0
	s_cmp_ge_i32 s68, s44
	s_mov_b32 s28, s68
	s_barrier
	s_cbranch_scc0 .LBB0_2433
	s_branch .LBB0_2424

; #define PG8_STAGE(bufoff, gbase, voff) do { _Pragma("unroll") for (int _i = 0; _i < 2; ++_i) \
;         __builtin_amdgcn_global_load_lds((const unsigned*)((const char*)(gbase) + (voff)[_i]), (LAS unsigned*)(lds + (bufoff) + ldsw + _i * 8192), 16, 0, 0); } while (0)
; #define PG8_LDA(dst, b, h) do { _Pragma("unroll") for (int m = 0; m < 4; ++m) _Pragma("unroll") for (int k = 0; k < 2; ++k) dst[m][k] = *(const LAS bf16x8*)(lds + PG8_SA(b, h) + aoff + m * 2048 + k * 1024); } while (0)
; #define PG8_LDB(dst, b, h) do { _Pragma("unroll") for (int n = 0; n < 2; ++n) _Pragma("unroll") for (int k = 0; k < 2; ++k) dst[n][k] = *(const LAS bf16x8*)(lds + PG8_SB(b, h) + boff + n * 2048 + k * 1024); } while (0)
; #define PG8_MMA(ai, bj, At, Bt) do { __builtin_amdgcn_s_setprio(1); _Pragma("unroll") for (int m = 0; m < 4; ++m) _Pragma("unroll") for (int n = 0; n < 2; ++n) _Pragma("unroll") for (int k = 0; k < 2; ++k) \
;         acc[ai][bj][m][n] = __builtin_amdgcn_mfma_f32_16x16x32_bf16(Bt[n][k], At[m][k], acc[ai][bj][m][n], 0, 0, 0); __builtin_amdgcn_s_setprio(0); } while (0)
; #define PG8_WAIT_L(n) asm volatile("s_waitcnt lgkmcnt(" #n ")" ::: "memory")
; #define PG8_BAR __builtin_amdgcn_s_barrier()
; #define PG8_SCHED __builtin_amdgcn_sched_barrier(0)
; template <class Epi>
; __device__ __forceinline__ void gemm_phase(LAS unsigned char* lds, const Gemm g, const StaticOrder& S, const Epi& E) {
;     ...
;         for (int t = 0; t < nt; t += 2) {
;             const bool last = (t == nt - 2);
;             const char* a1 = cA + (size_t)(t + 1) * kstep;
;             const char* a2 = last ? nA : cA + (size_t)(t + 2) * kstep; const char* b2 = last ? nB : cB + (size_t)(t + 2) * kstep;
;             const char* a3 = a2 + kstep; const char* b3 = b2 + kstep;
;             PG8_LDB(B0, 0, 0); PG8_SCHED; PG8_LDA(At, 0, 0); PG8_STAGE(PG8_SA(1, 1), a1 + hstepA, voffA);
;             PG8_WAIT_L(8); PG8_BAR; PG8_WAIT_L(0); PG8_MMA(0, 0, At, B0); PG8_BAR; PG8_SCHED;
;             PG8_LDB(B1, 0, 1); PG8_STAGE(PG8_SB(0, 0), b2, voffB);
;             PG8_BAR; PG8_WAIT_L(0); PG8_MMA(0, 1, At, B1); PG8_BAR;
;             PG8_LDA(At, 0, 1); PG8_STAGE(PG8_SA(0, 0), a2, voffA);
;             PG8_BAR; PG8_WAIT_L(0); PG8_MMA(1, 0, At, B0); PG8_BAR; PG8_SCHED;
.LBB0_2620:
	ds_read_b128 v[128:131], v183
	ds_read_b128 v[132:135], v183 offset:1024
	ds_read_b128 v[136:139], v183 offset:2048
	ds_read_b128 v[140:143], v183 offset:3072
	s_add_i32 s78, s38, 2
	s_add_u32 s39, s12, 0xfffc0080
	s_addc_u32 s40, s13, -1
	s_cmp_eq_u32 s61, s38
	s_cselect_b32 s38, s65, s76
	s_cselect_b32 s41, s25, s40
	s_cselect_b32 s40, s27, s39
	s_cselect_b32 s39, s64, s77
	s_add_i32 m0, s35, 0xc000
	ds_read_b128 v[144:147], v184
	ds_read_b128 v[148:151], v184 offset:1024
	ds_read_b128 v[168:171], v184 offset:2048
	ds_read_b128 v[172:175], v184 offset:3072
	ds_read_b128 v[176:179], v184 offset:4096
	ds_read_b128 v[188:191], v184 offset:5120
	ds_read_b128 v[192:195], v184 offset:6144
	ds_read_b128 v[196:199], v184 offset:7168
	global_load_lds_dwordx4 v160, s[12:13]
	s_add_i32 m0, s35, 0xe000
	s_nop 0
	global_load_lds_dwordx4 v162, s[12:13]
	s_waitcnt lgkmcnt(8)
	s_barrier
	s_waitcnt lgkmcnt(0)
	s_setprio 1
	s_waitcnt lgkmcnt(0)
	v_mfma_f32_16x16x32_bf16 v[124:127], v[128:131], v[144:147], v[124:127]
	v_mfma_f32_16x16x32_bf16 v[120:123], v[136:139], v[144:147], v[120:123]
	v_mfma_f32_16x16x32_bf16 v[108:111], v[128:131], v[168:171], v[108:111]
	v_mfma_f32_16x16x32_bf16 v[104:107], v[136:139], v[168:171], v[104:107]
	v_mfma_f32_16x16x32_bf16 v[92:95], v[128:131], v[176:179], v[92:95]
	v_mfma_f32_16x16x32_bf16 v[88:91], v[136:139], v[176:179], v[88:91]
	v_mfma_f32_16x16x32_bf16 v[76:79], v[128:131], v[192:195], v[76:79]
	v_mfma_f32_16x16x32_bf16 v[72:75], v[136:139], v[192:195], v[72:75]
	v_mfma_f32_16x16x32_bf16 v[124:127], v[132:135], v[148:151], v[124:127]
	v_mfma_f32_16x16x32_bf16 v[120:123], v[140:143], v[148:151], v[120:123]
	v_mfma_f32_16x16x32_bf16 v[108:111], v[132:135], v[172:175], v[108:111]
	v_mfma_f32_16x16x32_bf16 v[104:107], v[140:143], v[172:175], v[104:107]
	v_mfma_f32_16x16x32_bf16 v[92:95], v[132:135], v[188:191], v[92:95]
	v_mfma_f32_16x16x32_bf16 v[88:91], v[140:143], v[188:191], v[88:91]
	v_mfma_f32_16x16x32_bf16 v[76:79], v[132:135], v[196:199], v[76:79]
	v_mfma_f32_16x16x32_bf16 v[72:75], v[140:143], v[196:199], v[72:75]
	s_setprio 0
	s_barrier
	s_add_i32 s66, s69, s43
	v_lshl_add_u64 v[208:209], s[38:39], 0, v[154:155]
	s_mov_b32 m0, s66
	ds_read_b128 v[200:203], v185
	ds_read_b128 v[204:207], v185 offset:1024
	ds_read_b128 v[212:215], v185 offset:2048
	ds_read_b128 v[216:219], v185 offset:3072
	global_load_lds_dwordx4 v[208:209], off
	v_lshl_add_u64 v[220:221], s[38:39], 0, v[158:159]
	s_add_i32 m0, s66, 0x2000
	s_nop 0
	global_load_lds_dwordx4 v[220:221], off
	s_barrier
	s_waitcnt lgkmcnt(0)
	s_setprio 1
	s_waitcnt lgkmcnt(0)
	v_mfma_f32_16x16x32_bf16 v[116:119], v[200:203], v[144:147], v[116:119]
	v_mfma_f32_16x16x32_bf16 v[112:115], v[212:215], v[144:147], v[112:115]
	v_mfma_f32_16x16x32_bf16 v[100:103], v[200:203], v[168:171], v[100:103]
	v_mfma_f32_16x16x32_bf16 v[96:99], v[212:215], v[168:171], v[96:99]
	v_mfma_f32_16x16x32_bf16 v[84:87], v[200:203], v[176:179], v[84:87]
	v_mfma_f32_16x16x32_bf16 v[80:83], v[212:215], v[176:179], v[80:83]
	v_mfma_f32_16x16x32_bf16 v[68:71], v[200:203], v[192:195], v[68:71]
	v_mfma_f32_16x16x32_bf16 v[64:67], v[212:215], v[192:195], v[64:67]
	v_mfma_f32_16x16x32_bf16 v[116:119], v[204:207], v[148:151], v[116:119]
	v_mfma_f32_16x16x32_bf16 v[112:115], v[216:219], v[148:151], v[112:115]
	v_mfma_f32_16x16x32_bf16 v[100:103], v[204:207], v[172:175], v[100:103]
	v_mfma_f32_16x16x32_bf16 v[96:99], v[216:219], v[172:175], v[96:99]
	v_mfma_f32_16x16x32_bf16 v[84:87], v[204:207], v[188:191], v[84:87]
	v_mfma_f32_16x16x32_bf16 v[80:83], v[216:219], v[188:191], v[80:83]
	v_mfma_f32_16x16x32_bf16 v[68:71], v[204:207], v[196:199], v[68:71]
	v_mfma_f32_16x16x32_bf16 v[64:67], v[216:219], v[196:199], v[64:67]
	s_setprio 0
	s_mov_b32 m0, s35
	v_lshl_add_u64 v[222:223], s[40:41], 0, v[152:153]
	s_barrier
	ds_read_b128 v[144:147], v184 offset:16384
	ds_read_b128 v[148:151], v184 offset:17408
	ds_read_b128 v[168:171], v184 offset:18432
	ds_read_b128 v[172:175], v184 offset:19456
	ds_read_b128 v[176:179], v184 offset:20480
	ds_read_b128 v[188:191], v184 offset:21504
	ds_read_b128 v[192:195], v184 offset:22528
	ds_read_b128 v[196:199], v184 offset:23552
	global_load_lds_dwordx4 v[222:223], off
	v_lshl_add_u64 v[224:225], s[40:41], 0, v[156:157]
	s_mov_b32 m0, s37
	s_nop 0
	global_load_lds_dwordx4 v[224:225], off
	s_barrier
	s_waitcnt lgkmcnt(0)
	s_setprio 1
	s_waitcnt lgkmcnt(0)
	v_mfma_f32_16x16x32_bf16 v[60:63], v[128:131], v[144:147], v[60:63]
	v_mfma_f32_16x16x32_bf16 v[56:59], v[136:139], v[144:147], v[56:59]
	v_mfma_f32_16x16x32_bf16 v[44:47], v[128:131], v[168:171], v[44:47]
	v_mfma_f32_16x16x32_bf16 v[40:43], v[136:139], v[168:171], v[40:43]
	v_mfma_f32_16x16x32_bf16 v[28:31], v[128:131], v[176:179], v[28:31]
	v_mfma_f32_16x16x32_bf16 v[24:27], v[136:139], v[176:179], v[24:27]
	v_mfma_f32_16x16x32_bf16 v[12:15], v[128:131], v[192:195], v[12:15]
	v_mfma_f32_16x16x32_bf16 v[8:11], v[136:139], v[192:195], v[8:11]
	v_mfma_f32_16x16x32_bf16 v[60:63], v[132:135], v[148:151], v[60:63]
	v_mfma_f32_16x16x32_bf16 v[56:59], v[140:143], v[148:151], v[56:59]
	v_mfma_f32_16x16x32_bf16 v[44:47], v[132:135], v[172:175], v[44:47]
	v_mfma_f32_16x16x32_bf16 v[40:43], v[140:143], v[172:175], v[40:43]
	v_mfma_f32_16x16x32_bf16 v[28:31], v[132:135], v[188:191], v[28:31]
	v_mfma_f32_16x16x32_bf16 v[24:27], v[140:143], v[188:191], v[24:27]
	v_mfma_f32_16x16x32_bf16 v[12:15], v[132:135], v[196:199], v[12:15]
	v_mfma_f32_16x16x32_bf16 v[8:11], v[140:143], v[196:199], v[8:11]
	s_setprio 0
	s_barrier
; #define PG8_STAGE(bufoff, gbase, voff) do { _Pragma("unroll") for (int _i = 0; _i < 2; ++_i) \
;         __builtin_amdgcn_global_load_lds((const unsigned*)((const char*)(gbase) + (voff)[_i]), (LAS unsigned*)(lds + (bufoff) + ldsw + _i * 8192), 16, 0, 0); } while (0)
; #define PG8_LDA(dst, b, h) do { _Pragma("unroll") for (int m = 0; m < 4; ++m) _Pragma("unroll") for (int k = 0; k < 2; ++k) dst[m][k] = *(const LAS bf16x8*)(lds + PG8_SA(b, h) + aoff + m * 2048 + k * 1024); } while (0)
; #define PG8_LDB(dst, b, h) do { _Pragma("unroll") for (int n = 0; n < 2; ++n) _Pragma("unroll") for (int k = 0; k < 2; ++k) dst[n][k] = *(const LAS bf16x8*)(lds + PG8_SB(b, h) + boff + n * 2048 + k * 1024); } while (0)
; #define PG8_MMA(ai, bj, At, Bt) do { __builtin_amdgcn_s_setprio(1); _Pragma("unroll") for (int m = 0; m < 4; ++m) _Pragma("unroll") for (int n = 0; n < 2; ++n) _Pragma("unroll") for (int k = 0; k < 2; ++k) \
;         acc[ai][bj][m][n] = __builtin_amdgcn_mfma_f32_16x16x32_bf16(Bt[n][k], At[m][k], acc[ai][bj][m][n], 0, 0, 0); __builtin_amdgcn_s_setprio(0); } while (0)
; #define PG8_WAIT_V(n) asm volatile("s_waitcnt vmcnt(" #n ")" ::: "memory")
; #define PG8_WAIT_L(n) asm volatile("s_waitcnt lgkmcnt(" #n ")" ::: "memory")
; #define PG8_BAR __builtin_amdgcn_s_barrier()
; #define PG8_SCHED __builtin_amdgcn_sched_barrier(0)
; template <class Epi>
; __device__ __forceinline__ void gemm_phase(LAS unsigned char* lds, const Gemm g, const StaticOrder& S, const Epi& E) {
;     ...
;             PG8_STAGE(PG8_SB(0, 1), b2 + hstepB, voffB);
;             PG8_WAIT_V(6); PG8_BAR; PG8_MMA(1, 1, At, B1); PG8_BAR;
;             PG8_LDB(B0, 1, 0); PG8_SCHED; PG8_LDA(At, 1, 0); PG8_STAGE(PG8_SA(0, 1), a2 + hstepA, voffA);
;             PG8_WAIT_L(8); PG8_BAR; PG8_WAIT_L(0); PG8_MMA(0, 0, At, B0); PG8_BAR; PG8_SCHED;
;             PG8_LDB(B1, 1, 1); PG8_STAGE(PG8_SB(1, 0), b3, voffB);
;             PG8_BAR; PG8_WAIT_L(0); PG8_MMA(0, 1, At, B1); PG8_BAR;
	s_add_u32 s66, s38, 0x40000
	s_addc_u32 s67, s39, 0
	s_add_i32 s79, s74, s43
	s_mov_b32 m0, s79
	s_nop 0
	global_load_lds_dwordx4 v154, s[66:67]
	s_add_i32 m0, s79, 0x2000
	s_nop 0
	global_load_lds_dwordx4 v158, s[66:67]
	s_waitcnt vmcnt(6)
	s_barrier
	s_setprio 1
	v_mfma_f32_16x16x32_bf16 v[52:55], v[200:203], v[144:147], v[52:55]
	v_mfma_f32_16x16x32_bf16 v[48:51], v[212:215], v[144:147], v[48:51]
	v_mfma_f32_16x16x32_bf16 v[36:39], v[200:203], v[168:171], v[36:39]
	v_mfma_f32_16x16x32_bf16 v[32:35], v[212:215], v[168:171], v[32:35]
	v_mfma_f32_16x16x32_bf16 v[20:23], v[200:203], v[176:179], v[20:23]
	v_mfma_f32_16x16x32_bf16 v[16:19], v[212:215], v[176:179], v[16:19]
	v_mfma_f32_16x16x32_bf16 v[4:7], v[200:203], v[192:195], v[4:7]
	v_mfma_f32_16x16x32_bf16 v[0:3], v[212:215], v[192:195], v[0:3]
	v_mfma_f32_16x16x32_bf16 v[52:55], v[204:207], v[148:151], v[52:55]
	v_mfma_f32_16x16x32_bf16 v[48:51], v[216:219], v[148:151], v[48:51]
	v_mfma_f32_16x16x32_bf16 v[36:39], v[204:207], v[172:175], v[36:39]
	v_mfma_f32_16x16x32_bf16 v[32:35], v[216:219], v[172:175], v[32:35]
	v_mfma_f32_16x16x32_bf16 v[20:23], v[204:207], v[188:191], v[20:23]
	v_mfma_f32_16x16x32_bf16 v[16:19], v[216:219], v[188:191], v[16:19]
	v_mfma_f32_16x16x32_bf16 v[4:7], v[204:207], v[196:199], v[4:7]
	v_mfma_f32_16x16x32_bf16 v[0:3], v[216:219], v[196:199], v[0:3]
	s_setprio 0
	s_add_i32 s66, 0, 0x18000
	v_add_u32_e32 v140, s66, v182
	s_barrier
	ds_read_b128 v[128:131], v140
	ds_read_b128 v[132:135], v140 offset:1024
	ds_read_b128 v[136:139], v140 offset:2048
	ds_read_b128 v[140:143], v140 offset:3072
	s_add_u32 s40, s40, 0x40000
	s_addc_u32 s41, s41, 0
	s_mov_b32 m0, s44
	ds_read_b128 v[144:147], v184 offset:32768
	ds_read_b128 v[148:151], v184 offset:33792
	ds_read_b128 v[168:171], v184 offset:34816
	ds_read_b128 v[172:175], v184 offset:35840
	ds_read_b128 v[176:179], v184 offset:36864
	ds_read_b128 v[188:191], v184 offset:37888
	ds_read_b128 v[192:195], v184 offset:38912
	ds_read_b128 v[196:199], v184 offset:39936
	global_load_lds_dwordx4 v152, s[40:41]
	s_mov_b32 m0, s45
	s_nop 0
	global_load_lds_dwordx4 v156, s[40:41]
	s_waitcnt lgkmcnt(8)
	s_barrier
	s_waitcnt lgkmcnt(0)
	s_setprio 1
	s_waitcnt lgkmcnt(0)
	v_mfma_f32_16x16x32_bf16 v[124:127], v[128:131], v[144:147], v[124:127]
	v_mfma_f32_16x16x32_bf16 v[120:123], v[136:139], v[144:147], v[120:123]
	v_mfma_f32_16x16x32_bf16 v[108:111], v[128:131], v[168:171], v[108:111]
	v_mfma_f32_16x16x32_bf16 v[104:107], v[136:139], v[168:171], v[104:107]
	v_mfma_f32_16x16x32_bf16 v[92:95], v[128:131], v[176:179], v[92:95]
	v_mfma_f32_16x16x32_bf16 v[88:91], v[136:139], v[176:179], v[88:91]
	v_mfma_f32_16x16x32_bf16 v[76:79], v[128:131], v[192:195], v[76:79]
	v_mfma_f32_16x16x32_bf16 v[72:75], v[136:139], v[192:195], v[72:75]
	v_mfma_f32_16x16x32_bf16 v[124:127], v[132:135], v[148:151], v[124:127]
	v_mfma_f32_16x16x32_bf16 v[120:123], v[140:143], v[148:151], v[120:123]
	v_mfma_f32_16x16x32_bf16 v[108:111], v[132:135], v[172:175], v[108:111]
	v_mfma_f32_16x16x32_bf16 v[104:107], v[140:143], v[172:175], v[104:107]
	v_mfma_f32_16x16x32_bf16 v[92:95], v[132:135], v[188:191], v[92:95]
	v_mfma_f32_16x16x32_bf16 v[88:91], v[140:143], v[188:191], v[88:91]
	v_mfma_f32_16x16x32_bf16 v[76:79], v[132:135], v[196:199], v[76:79]
	v_mfma_f32_16x16x32_bf16 v[72:75], v[140:143], v[196:199], v[72:75]
	s_setprio 0
	s_barrier
	s_add_i32 s40, 0, 0x1c000
	s_add_i32 s41, s66, s43
	v_add_u32_e32 v211, s40, v182
	v_lshl_add_u64 v[208:209], v[208:209], 0, s[22:23]
	s_mov_b32 m0, s41
	ds_read_b128 v[200:203], v211
	ds_read_b128 v[204:207], v211 offset:1024
	ds_read_b128 v[212:215], v211 offset:2048
	ds_read_b128 v[216:219], v211 offset:3072
	global_load_lds_dwordx4 v[208:209], off
	v_lshl_add_u64 v[208:209], v[220:221], 0, s[22:23]
	s_add_i32 m0, s41, 0x2000
	s_nop 0
	global_load_lds_dwordx4 v[208:209], off
	s_barrier
; #define PG8_STAGE(bufoff, gbase, voff) do { _Pragma("unroll") for (int _i = 0; _i < 2; ++_i) \
;         __builtin_amdgcn_global_load_lds((const unsigned*)((const char*)(gbase) + (voff)[_i]), (LAS unsigned*)(lds + (bufoff) + ldsw + _i * 8192), 16, 0, 0); } while (0)
; #define PG8_LDA(dst, b, h) do { _Pragma("unroll") for (int m = 0; m < 4; ++m) _Pragma("unroll") for (int k = 0; k < 2; ++k) dst[m][k] = *(const LAS bf16x8*)(lds + PG8_SA(b, h) + aoff + m * 2048 + k * 1024); } while (0)
; #define PG8_MMA(ai, bj, At, Bt) do { __builtin_amdgcn_s_setprio(1); _Pragma("unroll") for (int m = 0; m < 4; ++m) _Pragma("unroll") for (int n = 0; n < 2; ++n) _Pragma("unroll") for (int k = 0; k < 2; ++k) \
;         acc[ai][bj][m][n] = __builtin_amdgcn_mfma_f32_16x16x32_bf16(Bt[n][k], At[m][k], acc[ai][bj][m][n], 0, 0, 0); __builtin_amdgcn_s_setprio(0); } while (0)
; #define PG8_WAIT_V(n) asm volatile("s_waitcnt vmcnt(" #n ")" ::: "memory")
; #define PG8_WAIT_L(n) asm volatile("s_waitcnt lgkmcnt(" #n ")" ::: "memory")
; #define PG8_BAR __builtin_amdgcn_s_barrier()
; #define PG8_SCHED __builtin_amdgcn_sched_barrier(0)
; template <class Epi>
; __device__ __forceinline__ void gemm_phase(LAS unsigned char* lds, const Gemm g, const StaticOrder& S, const Epi& E) {
;     ...
;             PG8_BAR; PG8_WAIT_L(0); PG8_MMA(0, 1, At, B1); PG8_BAR;
;             PG8_LDA(At, 1, 1); PG8_STAGE(PG8_SA(1, 0), a3, voffA);
;             PG8_BAR; PG8_WAIT_L(0); PG8_MMA(1, 0, At, B0); PG8_BAR; PG8_SCHED;
;             PG8_STAGE(PG8_SB(1, 1), b3 + hstepB, voffB);
;             PG8_WAIT_V(6); PG8_BAR; PG8_MMA(1, 1, At, B1); PG8_BAR;
;         }
	s_waitcnt lgkmcnt(0)
	s_setprio 1
	s_waitcnt lgkmcnt(0)
	v_mfma_f32_16x16x32_bf16 v[116:119], v[200:203], v[144:147], v[116:119]
	v_mfma_f32_16x16x32_bf16 v[112:115], v[212:215], v[144:147], v[112:115]
	v_mfma_f32_16x16x32_bf16 v[100:103], v[200:203], v[168:171], v[100:103]
	v_mfma_f32_16x16x32_bf16 v[96:99], v[212:215], v[168:171], v[96:99]
	v_mfma_f32_16x16x32_bf16 v[84:87], v[200:203], v[176:179], v[84:87]
	v_mfma_f32_16x16x32_bf16 v[80:83], v[212:215], v[176:179], v[80:83]
	v_mfma_f32_16x16x32_bf16 v[68:71], v[200:203], v[192:195], v[68:71]
	v_mfma_f32_16x16x32_bf16 v[64:67], v[212:215], v[192:195], v[64:67]
	v_mfma_f32_16x16x32_bf16 v[116:119], v[204:207], v[148:151], v[116:119]
	v_mfma_f32_16x16x32_bf16 v[112:115], v[216:219], v[148:151], v[112:115]
	v_mfma_f32_16x16x32_bf16 v[100:103], v[204:207], v[172:175], v[100:103]
	v_mfma_f32_16x16x32_bf16 v[96:99], v[216:219], v[172:175], v[96:99]
	v_mfma_f32_16x16x32_bf16 v[84:87], v[204:207], v[188:191], v[84:87]
	v_mfma_f32_16x16x32_bf16 v[80:83], v[216:219], v[188:191], v[80:83]
	v_mfma_f32_16x16x32_bf16 v[68:71], v[204:207], v[196:199], v[68:71]
	v_mfma_f32_16x16x32_bf16 v[64:67], v[216:219], v[196:199], v[64:67]
	s_setprio 0
	s_mov_b32 m0, s49
	v_lshl_add_u64 v[208:209], v[222:223], 0, s[22:23]
	s_barrier
	ds_read_b128 v[144:147], v184 offset:49152
	ds_read_b128 v[148:151], v184 offset:50176
	ds_read_b128 v[168:171], v184 offset:51200
	ds_read_b128 v[172:175], v184 offset:52224
	ds_read_b128 v[176:179], v184 offset:53248
	ds_read_b128 v[188:191], v184 offset:54272
	ds_read_b128 v[192:195], v184 offset:55296
	ds_read_b128 v[196:199], v184 offset:56320
	global_load_lds_dwordx4 v[208:209], off
	v_lshl_add_u64 v[208:209], v[224:225], 0, s[22:23]
	s_mov_b32 m0, s60
	s_nop 0
	global_load_lds_dwordx4 v[208:209], off
	s_barrier
	s_waitcnt lgkmcnt(0)
	s_setprio 1
	s_waitcnt lgkmcnt(0)
	v_mfma_f32_16x16x32_bf16 v[60:63], v[128:131], v[144:147], v[60:63]
	v_mfma_f32_16x16x32_bf16 v[56:59], v[136:139], v[144:147], v[56:59]
	v_mfma_f32_16x16x32_bf16 v[44:47], v[128:131], v[168:171], v[44:47]
	v_mfma_f32_16x16x32_bf16 v[40:43], v[136:139], v[168:171], v[40:43]
	v_mfma_f32_16x16x32_bf16 v[28:31], v[128:131], v[176:179], v[28:31]
	v_mfma_f32_16x16x32_bf16 v[24:27], v[136:139], v[176:179], v[24:27]
	v_mfma_f32_16x16x32_bf16 v[12:15], v[128:131], v[192:195], v[12:15]
	v_mfma_f32_16x16x32_bf16 v[8:11], v[136:139], v[192:195], v[8:11]
	v_mfma_f32_16x16x32_bf16 v[60:63], v[132:135], v[148:151], v[60:63]
	v_mfma_f32_16x16x32_bf16 v[56:59], v[140:143], v[148:151], v[56:59]
	v_mfma_f32_16x16x32_bf16 v[44:47], v[132:135], v[172:175], v[44:47]
	v_mfma_f32_16x16x32_bf16 v[40:43], v[140:143], v[172:175], v[40:43]
	v_mfma_f32_16x16x32_bf16 v[28:31], v[132:135], v[188:191], v[28:31]
	v_mfma_f32_16x16x32_bf16 v[24:27], v[140:143], v[188:191], v[24:27]
	v_mfma_f32_16x16x32_bf16 v[12:15], v[132:135], v[196:199], v[12:15]
	v_mfma_f32_16x16x32_bf16 v[8:11], v[140:143], v[196:199], v[8:11]
	s_setprio 0
	s_barrier
	s_add_u32 s38, s38, 0x40080
	s_addc_u32 s39, s39, 0
	s_add_i32 s40, s40, s43
	s_mov_b32 m0, s40
	s_nop 0
	global_load_lds_dwordx4 v154, s[38:39]
	s_add_i32 m0, s40, 0x2000
	s_nop 0
	global_load_lds_dwordx4 v158, s[38:39]
	s_waitcnt vmcnt(6)
	s_barrier
	s_setprio 1
	v_mfma_f32_16x16x32_bf16 v[52:55], v[200:203], v[144:147], v[52:55]
	v_mfma_f32_16x16x32_bf16 v[48:51], v[212:215], v[144:147], v[48:51]
	v_mfma_f32_16x16x32_bf16 v[36:39], v[200:203], v[168:171], v[36:39]
	v_mfma_f32_16x16x32_bf16 v[32:35], v[212:215], v[168:171], v[32:35]
	v_mfma_f32_16x16x32_bf16 v[20:23], v[200:203], v[176:179], v[20:23]
	v_mfma_f32_16x16x32_bf16 v[16:19], v[212:215], v[176:179], v[16:19]
	v_mfma_f32_16x16x32_bf16 v[4:7], v[200:203], v[192:195], v[4:7]
	v_mfma_f32_16x16x32_bf16 v[0:3], v[212:215], v[192:195], v[0:3]
	v_mfma_f32_16x16x32_bf16 v[52:55], v[204:207], v[148:151], v[52:55]
	v_mfma_f32_16x16x32_bf16 v[48:51], v[216:219], v[148:151], v[48:51]
	v_mfma_f32_16x16x32_bf16 v[36:39], v[204:207], v[172:175], v[36:39]
	v_mfma_f32_16x16x32_bf16 v[32:35], v[216:219], v[172:175], v[32:35]
	v_mfma_f32_16x16x32_bf16 v[20:23], v[204:207], v[188:191], v[20:23]
	v_mfma_f32_16x16x32_bf16 v[16:19], v[216:219], v[188:191], v[16:19]
	v_mfma_f32_16x16x32_bf16 v[4:7], v[204:207], v[196:199], v[4:7]
	v_mfma_f32_16x16x32_bf16 v[0:3], v[216:219], v[196:199], v[0:3]
	s_setprio 0
	s_add_u32 s12, s12, 0x100
	s_addc_u32 s13, s13, 0
	s_add_u32 s76, s76, 0x100
	s_addc_u32 s77, s77, 0
	s_cmp_ge_i32 s78, s48
	s_mov_b32 s38, s78
	s_barrier
	s_cbranch_scc0 .LBB0_2620
